# E46: GEMM K-loops: per-segment s_setprio toggles removed; one static s_setprio 1 for the trailing wave half at loop entry, lowered at the phase end (guide 7.4); on E41
# speedup vs baseline: 1.0038x; 1.0038x over previous
.LBB0_189:
	s_andn2_b64 vcc, exec, s[0:1]
	s_cbranch_vccnz .LBB0_256
	v_ashrrev_i32_e32 v4, 31, v2
	v_lshrrev_b32_e32 v4, 26, v4
	v_lshlrev_b32_e32 v3, 4, v2
	v_add_u32_e32 v4, v2, v4
	v_bfe_i32 v2, v2, 27, 1
	v_lshrrev_b32_e32 v2, 22, v2
	v_add_u32_e32 v2, v3, v2
	v_and_b32_e32 v2, 0xfffffc00, v2
	v_sub_u32_e32 v2, v3, v2
	v_ashrrev_i32_e32 v10, 6, v4
	v_lshrrev_b32_e32 v4, 4, v2
	v_bitop3_b32 v2, v4, v2, 32 bitop3:0x6c
	v_ashrrev_i32_e32 v5, 31, v2
	v_lshrrev_b32_e32 v5, 26, v5
	v_add_u32_e32 v5, v2, v5
	v_lshlrev_b32_e32 v4, 3, v10
	v_ashrrev_i32_e32 v11, 6, v5
	v_and_b32_e32 v5, 0xc0, v5
	v_and_b32_e32 v4, -16, v4
	v_sub_u32_e32 v2, v2, v5
	v_mov_b32_e32 v5, 1
	v_add_u32_e32 v4, v11, v4
	v_ashrrev_i16_sdwa v2, v5, sext(v2) dst_sel:DWORD dst_unused:UNUSED_PAD src0_sel:DWORD src1_sel:BYTE_0
	v_lshlrev_b32_e32 v6, 5, v10
	v_bfe_i32 v12, v2, 0, 16
	v_lshlrev_b32_e32 v2, 1, v4
	v_lshrrev_b32_e32 v7, 2, v4
	v_and_b32_e32 v8, 3, v11
	s_mov_b32 s1, 0x1fffe0
	v_and_b32_e32 v6, 32, v6
	v_and_b32_e32 v2, 24, v2
	v_and_b32_e32 v7, 4, v7
	v_and_or_b32 v8, v4, s1, v8
	v_or3_b32 v2, v8, v7, v2
	v_add_lshl_u32 v6, v6, v12, 1
	v_lshl_add_u32 v132, v2, 11, v6
	v_add_u32_e32 v2, 0x2000, v3
	v_ashrrev_i32_e32 v3, 31, v2
	v_lshrrev_b32_e32 v3, 22, v3
	v_add_u32_e32 v3, v2, v3
	v_ashrrev_i32_e32 v13, 10, v3
	v_mul_i32_i24_e32 v3, 0x400, v13
	v_sub_u32_e32 v2, v2, v3
	v_lshrrev_b32_e32 v3, 4, v2
	v_bitop3_b32 v2, v3, v2, 32 bitop3:0x6c
	v_lshl_add_u32 v130, v4, 11, v6
	v_ashrrev_i32_e32 v4, 31, v2
	v_lshrrev_b32_e32 v4, 26, v4
	v_add_u32_e32 v4, v2, v4
	v_lshlrev_b32_e32 v3, 3, v13
	v_ashrrev_i32_e32 v14, 6, v4
	v_and_b32_e32 v4, 0xc0, v4
	v_and_b32_e32 v3, -16, v3
	v_sub_u32_e32 v2, v2, v4
	s_add_u32 s3, s82, 0x400000
	v_add_u32_e32 v3, v14, v3
	v_ashrrev_i16_sdwa v2, v5, sext(v2) dst_sel:DWORD dst_unused:UNUSED_PAD src0_sel:DWORD src1_sel:BYTE_0
	v_and_b32_e32 v5, 3, v14
	s_addc_u32 s33, s83, 0
	v_and_or_b32 v5, v3, s1, v5
	s_ashr_i32 s1, s38, 6
	s_ashr_i32 s5, s4, 31
	s_ashr_i32 s49, s48, 31
	s_ashr_i32 s0, s38, 8
	s_lshl_b32 s92, s1, 10
	s_lshl_b64 s[24:25], s[4:5], 19
	s_lshl_b64 s[26:27], s[48:49], 19
	s_add_u32 s78, s3, s26
	v_lshlrev_b32_e32 v6, 5, v13
	v_bfe_i32 v15, v2, 0, 16
	v_lshlrev_b32_e32 v2, 1, v3
	v_lshrrev_b32_e32 v4, 2, v3
	s_addc_u32 s79, s33, s27
	s_add_i32 s93, s92, 0
	v_and_b32_e32 v6, 32, v6
	v_and_b32_e32 v2, 24, v2
	v_and_b32_e32 v4, 4, v4
	s_add_i32 m0, s93, 0x10000
	v_or3_b32 v2, v5, v4, v2
	v_add_lshl_u32 v4, v6, v15, 1
	global_load_lds_dwordx4 v132, s[78:79]
	s_add_i32 m0, s93, 0x12000
	v_lshl_add_u32 v136, v2, 11, v4
	s_add_u32 s26, s78, 0x40000
	global_load_lds_dwordx4 v136, s[78:79]
	s_addc_u32 s27, s79, 0
	s_add_i32 m0, s93, 0x14000
	v_lshl_add_u32 v134, v3, 11, v4
	global_load_lds_dwordx4 v132, s[26:27]
	s_add_i32 m0, s93, 0x16000
	s_add_u32 s76, s62, s24
	s_addc_u32 s77, s63, s25
	s_add_i32 s94, s93, 0x2000
	global_load_lds_dwordx4 v136, s[26:27]
	s_mov_b32 m0, s93
	s_add_u32 s24, s76, 0x40000
	global_load_lds_dwordx4 v130, s[76:77]
	s_mov_b32 m0, s94
	s_addc_u32 s25, s77, 0
	s_add_i32 s95, s93, 0x4000
	global_load_lds_dwordx4 v134, s[76:77]
	s_mov_b32 m0, s95
	s_add_i32 s96, s93, 0x6000
	global_load_lds_dwordx4 v130, s[24:25]
	s_mov_b32 m0, s96
	v_mov_b32_e32 v133, 0
	global_load_lds_dwordx4 v134, s[24:25]
	v_mov_b32_e32 v137, v133
	v_mov_b32_e32 v131, v133
	v_mov_b32_e32 v135, v133
	s_cmp_eq_u32 s0, 1
	s_mov_b32 s97, 0
	v_lshl_add_u64 v[8:9], s[78:79], 0, v[132:133]
	v_lshl_add_u64 v[6:7], s[78:79], 0, v[136:137]
	v_lshl_add_u64 v[2:3], s[76:77], 0, v[130:131]
	s_cselect_b64 s[24:25], -1, 0
	s_cmp_lg_u32 s0, 1
	v_lshl_add_u64 v[4:5], s[76:77], 0, v[134:135]
	s_cbranch_scc1 .LBB0_192
	s_barrier
	s_setprio 1

.LBB0_202:
	ds_read_b128 v[146:149], v157
	ds_read_b128 v[150:153], v157 offset:1024
	ds_read_b128 v[164:167], v157 offset:2048
	ds_read_b128 v[168:171], v157 offset:3072
	ds_read_b128 v[172:175], v158
	ds_read_b128 v[176:179], v158 offset:1024
	ds_read_b128 v[180:183], v158 offset:2048
	ds_read_b128 v[184:187], v158 offset:3072
	s_add_u32 s72, s76, 0xfffc0080
	s_addc_u32 s73, s77, -1
	s_cmp_eq_u32 s71, 12
	s_cselect_b32 s85, s5, s73
	s_cselect_b32 s84, s43, s72
	s_cselect_b32 s79, s41, s70
	s_cselect_b32 s78, s49, s69
	v_lshl_add_u64 v[188:189], s[76:77], 0, v[138:139]
	s_add_i32 m0, s93, 0xc000
	ds_read_b128 v[192:195], v159
	ds_read_b128 v[196:199], v159 offset:1024
	ds_read_b128 v[200:203], v159 offset:2048
	ds_read_b128 v[204:207], v159 offset:3072
	ds_read_b128 v[208:211], v159 offset:4096
	ds_read_b128 v[218:221], v159 offset:5120
	ds_read_b128 v[224:227], v159 offset:6144
	ds_read_b128 v[228:231], v159 offset:7168
	global_load_lds_dwordx4 v[188:189], off
	v_lshl_add_u64 v[188:189], s[76:77], 0, v[140:141]
	s_add_i32 m0, s93, 0xe000
	s_nop 0
	global_load_lds_dwordx4 v[188:189], off
	s_waitcnt vmcnt(8)
	s_waitcnt lgkmcnt(0)
	s_barrier
	s_waitcnt lgkmcnt(0)
	v_mfma_f32_16x16x32_bf16 v[126:129], v[146:149], v[192:195], v[126:129]
	v_mfma_f32_16x16x32_bf16 v[122:125], v[164:167], v[192:195], v[122:125]
	v_mfma_f32_16x16x32_bf16 v[110:113], v[146:149], v[200:203], v[110:113]
	v_mfma_f32_16x16x32_bf16 v[106:109], v[164:167], v[200:203], v[106:109]
	v_mfma_f32_16x16x32_bf16 v[94:97], v[146:149], v[208:211], v[94:97]
	v_mfma_f32_16x16x32_bf16 v[90:93], v[164:167], v[208:211], v[90:93]
	v_mfma_f32_16x16x32_bf16 v[78:81], v[146:149], v[224:227], v[78:81]
	v_mfma_f32_16x16x32_bf16 v[74:77], v[164:167], v[224:227], v[74:77]
	v_mfma_f32_16x16x32_bf16 v[126:129], v[150:153], v[196:199], v[126:129]
	v_mfma_f32_16x16x32_bf16 v[122:125], v[168:171], v[196:199], v[122:125]
	v_mfma_f32_16x16x32_bf16 v[110:113], v[150:153], v[204:207], v[110:113]
	v_mfma_f32_16x16x32_bf16 v[106:109], v[168:171], v[204:207], v[106:109]
	v_mfma_f32_16x16x32_bf16 v[94:97], v[150:153], v[218:221], v[94:97]
	v_mfma_f32_16x16x32_bf16 v[90:93], v[168:171], v[218:221], v[90:93]
	v_mfma_f32_16x16x32_bf16 v[78:81], v[150:153], v[228:231], v[78:81]
	v_mfma_f32_16x16x32_bf16 v[74:77], v[168:171], v[228:231], v[74:77]
	v_mfma_f32_16x16x32_bf16 v[118:121], v[172:175], v[192:195], v[118:121]
	v_mfma_f32_16x16x32_bf16 v[114:117], v[180:183], v[192:195], v[114:117]
	v_mfma_f32_16x16x32_bf16 v[102:105], v[172:175], v[200:203], v[102:105]
	v_mfma_f32_16x16x32_bf16 v[98:101], v[180:183], v[200:203], v[98:101]
	v_mfma_f32_16x16x32_bf16 v[86:89], v[172:175], v[208:211], v[86:89]
	v_mfma_f32_16x16x32_bf16 v[82:85], v[180:183], v[208:211], v[82:85]
	v_mfma_f32_16x16x32_bf16 v[70:73], v[172:175], v[224:227], v[70:73]
	v_mfma_f32_16x16x32_bf16 v[66:69], v[180:183], v[224:227], v[66:69]
	v_mfma_f32_16x16x32_bf16 v[118:121], v[176:179], v[196:199], v[118:121]
	v_mfma_f32_16x16x32_bf16 v[114:117], v[184:187], v[196:199], v[114:117]
	v_mfma_f32_16x16x32_bf16 v[102:105], v[176:179], v[204:207], v[102:105]
	v_mfma_f32_16x16x32_bf16 v[98:101], v[184:187], v[204:207], v[98:101]
	v_mfma_f32_16x16x32_bf16 v[86:89], v[176:179], v[218:221], v[86:89]
	v_mfma_f32_16x16x32_bf16 v[82:85], v[184:187], v[218:221], v[82:85]
	v_mfma_f32_16x16x32_bf16 v[70:73], v[176:179], v[228:231], v[70:73]
	v_mfma_f32_16x16x32_bf16 v[66:69], v[184:187], v[228:231], v[66:69]
	s_barrier
	s_add_i32 s72, s67, s92
	v_lshl_add_u64 v[188:189], s[78:79], 0, v[132:133]
	s_mov_b32 m0, s72
	ds_read_b128 v[192:195], v159 offset:16384
	ds_read_b128 v[196:199], v159 offset:17408
	ds_read_b128 v[200:203], v159 offset:18432
	ds_read_b128 v[204:207], v159 offset:19456
	ds_read_b128 v[208:211], v159 offset:20480
	ds_read_b128 v[218:221], v159 offset:21504
	ds_read_b128 v[224:227], v159 offset:22528
	ds_read_b128 v[228:231], v159 offset:23552
	global_load_lds_dwordx4 v[188:189], off
	s_add_i32 m0, s72, 0x2000
	s_add_u32 s72, s78, 0x40000
	v_lshl_add_u64 v[214:215], s[78:79], 0, v[136:137]
	s_addc_u32 s73, s79, 0
	s_add_i32 s74, s68, s92
	global_load_lds_dwordx4 v[214:215], off
	v_lshl_add_u64 v[232:233], s[72:73], 0, v[132:133]
	s_mov_b32 m0, s74
	v_lshl_add_u64 v[234:235], s[84:85], 0, v[134:135]
	global_load_lds_dwordx4 v[232:233], off
	v_lshl_add_u64 v[232:233], s[72:73], 0, v[136:137]
	s_add_i32 m0, s74, 0x2000
	s_nop 0
	global_load_lds_dwordx4 v[232:233], off
	v_lshl_add_u64 v[232:233], s[84:85], 0, v[130:131]
	s_mov_b32 m0, s93
	s_nop 0
	global_load_lds_dwordx4 v[232:233], off
	s_mov_b32 m0, s94
	s_nop 0
	global_load_lds_dwordx4 v[234:235], off
	s_waitcnt vmcnt(8)
	s_waitcnt lgkmcnt(0)
	s_barrier
	s_waitcnt lgkmcnt(0)
	v_mfma_f32_16x16x32_bf16 v[62:65], v[146:149], v[192:195], v[62:65]
	v_mfma_f32_16x16x32_bf16 v[58:61], v[164:167], v[192:195], v[58:61]
	v_mfma_f32_16x16x32_bf16 v[46:49], v[146:149], v[200:203], v[46:49]
	v_mfma_f32_16x16x32_bf16 v[42:45], v[164:167], v[200:203], v[42:45]
	v_mfma_f32_16x16x32_bf16 v[30:33], v[146:149], v[208:211], v[30:33]
	v_mfma_f32_16x16x32_bf16 v[26:29], v[164:167], v[208:211], v[26:29]
	v_mfma_f32_16x16x32_bf16 v[14:17], v[146:149], v[224:227], v[14:17]
	v_mfma_f32_16x16x32_bf16 v[10:13], v[164:167], v[224:227], v[10:13]
	v_mfma_f32_16x16x32_bf16 v[62:65], v[150:153], v[196:199], v[62:65]
	v_mfma_f32_16x16x32_bf16 v[58:61], v[168:171], v[196:199], v[58:61]
	v_mfma_f32_16x16x32_bf16 v[46:49], v[150:153], v[204:207], v[46:49]
	v_mfma_f32_16x16x32_bf16 v[42:45], v[168:171], v[204:207], v[42:45]
	v_mfma_f32_16x16x32_bf16 v[30:33], v[150:153], v[218:221], v[30:33]
	v_mfma_f32_16x16x32_bf16 v[26:29], v[168:171], v[218:221], v[26:29]
	v_mfma_f32_16x16x32_bf16 v[14:17], v[150:153], v[228:231], v[14:17]
	v_mfma_f32_16x16x32_bf16 v[10:13], v[168:171], v[228:231], v[10:13]
	v_mfma_f32_16x16x32_bf16 v[54:57], v[172:175], v[192:195], v[54:57]
	v_mfma_f32_16x16x32_bf16 v[50:53], v[180:183], v[192:195], v[50:53]
	v_mfma_f32_16x16x32_bf16 v[38:41], v[172:175], v[200:203], v[38:41]
	v_mfma_f32_16x16x32_bf16 v[34:37], v[180:183], v[200:203], v[34:37]
	v_mfma_f32_16x16x32_bf16 v[22:25], v[172:175], v[208:211], v[22:25]
	v_mfma_f32_16x16x32_bf16 v[18:21], v[180:183], v[208:211], v[18:21]
	v_mfma_f32_16x16x32_bf16 v[6:9], v[172:175], v[224:227], v[6:9]
	v_mfma_f32_16x16x32_bf16 v[2:5], v[180:183], v[224:227], v[2:5]
	v_mfma_f32_16x16x32_bf16 v[54:57], v[176:179], v[196:199], v[54:57]
	v_mfma_f32_16x16x32_bf16 v[50:53], v[184:187], v[196:199], v[50:53]
	v_mfma_f32_16x16x32_bf16 v[38:41], v[176:179], v[204:207], v[38:41]
	v_mfma_f32_16x16x32_bf16 v[34:37], v[184:187], v[204:207], v[34:37]
	v_mfma_f32_16x16x32_bf16 v[22:25], v[176:179], v[218:221], v[22:25]
	v_mfma_f32_16x16x32_bf16 v[18:21], v[184:187], v[218:221], v[18:21]
	v_mfma_f32_16x16x32_bf16 v[6:9], v[176:179], v[228:231], v[6:9]
	v_mfma_f32_16x16x32_bf16 v[2:5], v[184:187], v[228:231], v[2:5]
	s_barrier
	s_add_i32 s74, 0, 0x18000
	v_add_u32_e32 v161, s74, v155
	s_add_i32 s75, 0, 0x1c000
	ds_read_b128 v[146:149], v161
	ds_read_b128 v[150:153], v161 offset:1024
	ds_read_b128 v[164:167], v161 offset:2048
	ds_read_b128 v[168:171], v161 offset:3072
	v_add_u32_e32 v161, s75, v155
	ds_read_b128 v[172:175], v161
	ds_read_b128 v[176:179], v161 offset:1024
	ds_read_b128 v[180:183], v161 offset:2048
	ds_read_b128 v[184:187], v161 offset:3072
	s_add_u32 s72, s84, 0x40000
	s_addc_u32 s73, s85, 0
	s_mov_b32 m0, s95
	v_lshl_add_u64 v[236:237], s[72:73], 0, v[130:131]
	ds_read_b128 v[192:195], v159 offset:32768
	ds_read_b128 v[196:199], v159 offset:33792
	ds_read_b128 v[200:203], v159 offset:34816
	ds_read_b128 v[204:207], v159 offset:35840
	ds_read_b128 v[208:211], v159 offset:36864
	ds_read_b128 v[218:221], v159 offset:37888
	ds_read_b128 v[224:227], v159 offset:38912
	ds_read_b128 v[228:231], v159 offset:39936
	global_load_lds_dwordx4 v[236:237], off
	v_lshl_add_u64 v[236:237], s[72:73], 0, v[134:135]
	s_mov_b32 m0, s96
	s_nop 0
	global_load_lds_dwordx4 v[236:237], off
	s_waitcnt vmcnt(8)
	s_waitcnt lgkmcnt(0)
	s_barrier
	s_waitcnt lgkmcnt(0)
	v_mfma_f32_16x16x32_bf16 v[126:129], v[146:149], v[192:195], v[126:129]
	v_mfma_f32_16x16x32_bf16 v[122:125], v[164:167], v[192:195], v[122:125]
	v_mfma_f32_16x16x32_bf16 v[110:113], v[146:149], v[200:203], v[110:113]
	v_mfma_f32_16x16x32_bf16 v[106:109], v[164:167], v[200:203], v[106:109]
	v_mfma_f32_16x16x32_bf16 v[94:97], v[146:149], v[208:211], v[94:97]
	v_mfma_f32_16x16x32_bf16 v[90:93], v[164:167], v[208:211], v[90:93]
	v_mfma_f32_16x16x32_bf16 v[78:81], v[146:149], v[224:227], v[78:81]
	v_mfma_f32_16x16x32_bf16 v[74:77], v[164:167], v[224:227], v[74:77]
	v_mfma_f32_16x16x32_bf16 v[126:129], v[150:153], v[196:199], v[126:129]
	v_mfma_f32_16x16x32_bf16 v[122:125], v[168:171], v[196:199], v[122:125]
	v_mfma_f32_16x16x32_bf16 v[110:113], v[150:153], v[204:207], v[110:113]
	v_mfma_f32_16x16x32_bf16 v[106:109], v[168:171], v[204:207], v[106:109]
	v_mfma_f32_16x16x32_bf16 v[94:97], v[150:153], v[218:221], v[94:97]
	v_mfma_f32_16x16x32_bf16 v[90:93], v[168:171], v[218:221], v[90:93]
	v_mfma_f32_16x16x32_bf16 v[78:81], v[150:153], v[228:231], v[78:81]
	v_mfma_f32_16x16x32_bf16 v[74:77], v[168:171], v[228:231], v[74:77]
	v_mfma_f32_16x16x32_bf16 v[118:121], v[172:175], v[192:195], v[118:121]
	v_mfma_f32_16x16x32_bf16 v[114:117], v[180:183], v[192:195], v[114:117]
	v_mfma_f32_16x16x32_bf16 v[102:105], v[172:175], v[200:203], v[102:105]
	v_mfma_f32_16x16x32_bf16 v[98:101], v[180:183], v[200:203], v[98:101]
	v_mfma_f32_16x16x32_bf16 v[86:89], v[172:175], v[208:211], v[86:89]
	v_mfma_f32_16x16x32_bf16 v[82:85], v[180:183], v[208:211], v[82:85]
	v_mfma_f32_16x16x32_bf16 v[70:73], v[172:175], v[224:227], v[70:73]
	v_mfma_f32_16x16x32_bf16 v[66:69], v[180:183], v[224:227], v[66:69]
	v_mfma_f32_16x16x32_bf16 v[118:121], v[176:179], v[196:199], v[118:121]
	v_mfma_f32_16x16x32_bf16 v[114:117], v[184:187], v[196:199], v[114:117]
	v_mfma_f32_16x16x32_bf16 v[102:105], v[176:179], v[204:207], v[102:105]
	v_mfma_f32_16x16x32_bf16 v[98:101], v[184:187], v[204:207], v[98:101]
	v_mfma_f32_16x16x32_bf16 v[86:89], v[176:179], v[218:221], v[86:89]
	v_mfma_f32_16x16x32_bf16 v[82:85], v[184:187], v[218:221], v[82:85]
	v_mfma_f32_16x16x32_bf16 v[70:73], v[176:179], v[228:231], v[70:73]
	v_mfma_f32_16x16x32_bf16 v[66:69], v[184:187], v[228:231], v[66:69]
	s_barrier
	s_add_i32 s72, s74, s92
	v_lshl_add_u64 v[188:189], v[188:189], 0, s[36:37]
	s_mov_b32 m0, s72
	ds_read_b128 v[192:195], v159 offset:49152
	ds_read_b128 v[196:199], v159 offset:50176
	ds_read_b128 v[200:203], v159 offset:51200
	ds_read_b128 v[204:207], v159 offset:52224
	ds_read_b128 v[208:211], v159 offset:53248
	ds_read_b128 v[218:221], v159 offset:54272
	ds_read_b128 v[224:227], v159 offset:55296
	ds_read_b128 v[228:231], v159 offset:56320
	global_load_lds_dwordx4 v[188:189], off
	s_add_i32 m0, s72, 0x2000
	s_add_u32 s72, s78, 0x40080
	v_lshl_add_u64 v[188:189], v[214:215], 0, s[36:37]
	s_addc_u32 s73, s79, 0
	s_add_i32 s74, s75, s92
	global_load_lds_dwordx4 v[188:189], off
	v_lshl_add_u64 v[188:189], s[72:73], 0, v[132:133]
	s_mov_b32 m0, s74
	s_nop 0
	global_load_lds_dwordx4 v[188:189], off
	v_lshl_add_u64 v[188:189], s[72:73], 0, v[136:137]
	s_add_i32 m0, s74, 0x2000
	s_nop 0
	global_load_lds_dwordx4 v[188:189], off
	v_lshl_add_u64 v[188:189], v[232:233], 0, s[36:37]
	s_mov_b32 m0, s86
	s_nop 0
	global_load_lds_dwordx4 v[188:189], off
	v_lshl_add_u64 v[188:189], v[234:235], 0, s[36:37]
	s_mov_b32 m0, s87
	s_nop 0
	global_load_lds_dwordx4 v[188:189], off
	s_waitcnt vmcnt(8)
	s_waitcnt lgkmcnt(0)
	s_barrier
	s_waitcnt lgkmcnt(0)
	v_mfma_f32_16x16x32_bf16 v[62:65], v[146:149], v[192:195], v[62:65]
	v_mfma_f32_16x16x32_bf16 v[58:61], v[164:167], v[192:195], v[58:61]
	v_mfma_f32_16x16x32_bf16 v[46:49], v[146:149], v[200:203], v[46:49]
	v_mfma_f32_16x16x32_bf16 v[42:45], v[164:167], v[200:203], v[42:45]
	v_mfma_f32_16x16x32_bf16 v[30:33], v[146:149], v[208:211], v[30:33]
	v_mfma_f32_16x16x32_bf16 v[26:29], v[164:167], v[208:211], v[26:29]
	v_mfma_f32_16x16x32_bf16 v[14:17], v[146:149], v[224:227], v[14:17]
	v_mfma_f32_16x16x32_bf16 v[10:13], v[164:167], v[224:227], v[10:13]
	v_mfma_f32_16x16x32_bf16 v[62:65], v[150:153], v[196:199], v[62:65]
	v_mfma_f32_16x16x32_bf16 v[58:61], v[168:171], v[196:199], v[58:61]
	v_mfma_f32_16x16x32_bf16 v[46:49], v[150:153], v[204:207], v[46:49]
	v_mfma_f32_16x16x32_bf16 v[42:45], v[168:171], v[204:207], v[42:45]
	v_mfma_f32_16x16x32_bf16 v[30:33], v[150:153], v[218:221], v[30:33]
	v_mfma_f32_16x16x32_bf16 v[26:29], v[168:171], v[218:221], v[26:29]
	v_mfma_f32_16x16x32_bf16 v[14:17], v[150:153], v[228:231], v[14:17]
	v_mfma_f32_16x16x32_bf16 v[10:13], v[168:171], v[228:231], v[10:13]
	v_mfma_f32_16x16x32_bf16 v[54:57], v[172:175], v[192:195], v[54:57]
	v_mfma_f32_16x16x32_bf16 v[50:53], v[180:183], v[192:195], v[50:53]
	v_mfma_f32_16x16x32_bf16 v[38:41], v[172:175], v[200:203], v[38:41]
	v_mfma_f32_16x16x32_bf16 v[34:37], v[180:183], v[200:203], v[34:37]
	v_mfma_f32_16x16x32_bf16 v[22:25], v[172:175], v[208:211], v[22:25]
	v_mfma_f32_16x16x32_bf16 v[18:21], v[180:183], v[208:211], v[18:21]
	v_mfma_f32_16x16x32_bf16 v[6:9], v[172:175], v[224:227], v[6:9]
	v_mfma_f32_16x16x32_bf16 v[2:5], v[180:183], v[224:227], v[2:5]
	v_mfma_f32_16x16x32_bf16 v[54:57], v[176:179], v[196:199], v[54:57]
	v_mfma_f32_16x16x32_bf16 v[50:53], v[184:187], v[196:199], v[50:53]
	v_mfma_f32_16x16x32_bf16 v[38:41], v[176:179], v[204:207], v[38:41]
	v_mfma_f32_16x16x32_bf16 v[34:37], v[184:187], v[204:207], v[34:37]
	v_mfma_f32_16x16x32_bf16 v[22:25], v[176:179], v[218:221], v[22:25]
	v_mfma_f32_16x16x32_bf16 v[18:21], v[184:187], v[218:221], v[18:21]
	v_mfma_f32_16x16x32_bf16 v[6:9], v[176:179], v[228:231], v[6:9]
	v_mfma_f32_16x16x32_bf16 v[2:5], v[184:187], v[228:231], v[2:5]
	s_barrier
	s_add_i32 s71, s71, 2
	s_add_u32 s76, s76, 0x100
	s_addc_u32 s77, s77, 0
	s_add_u32 s69, s69, 0x100
	s_addc_u32 s70, s70, 0
	s_cmp_gt_u32 s71, 13
	s_cbranch_scc0 .LBB0_202
	s_and_b64 vcc, exec, s[38:39]
	s_cbranch_vccz .LBB0_205
	s_barrier

.LBB0_256:
	v_readlane_b32 s0, v244, 3
	v_readlane_b32 s1, v244, 4
	s_cmp_gt_i32 s1, 2
	s_cselect_b64 s[0:1], -1, 0
	s_and_b64 s[4:5], s[6:7], s[0:1]
	s_andn2_b64 vcc, exec, s[4:5]
	s_cbranch_vccnz .LBB0_310
	s_setprio 0
	s_waitcnt vmcnt(0)
	s_waitcnt vmcnt(0)
	s_barrier
	s_getreg_b32 s3, hwreg(HW_REG_HW_ID, 0, 6)
	s_and_b32 s3, s3, 63
	s_lshl_b32 s3, s3, 2
	s_add_i32 s3, s3, 0
	s_mov_b64 s[4:5], src_shared_base
	s_add_i32 s3, s3, 0x23e00
	v_mov_b32_e32 v2, s3
	v_mov_b32_e32 v3, s5
	flat_load_dword v2, v[2:3] sc0 sc1
	s_waitcnt vmcnt(0) lgkmcnt(0)
	v_readfirstlane_b32 s3, v2
	s_cmp_lg_u32 s3, 1
	s_cbranch_scc1 .Learlyinv_skip1
	buffer_inv sc1
	s_waitcnt vmcnt(0)

.LBB0_667:
	v_ashrrev_i32_e32 v6, 31, v4
	v_lshrrev_b32_e32 v6, 26, v6
	v_lshlrev_b32_e32 v5, 4, v4
	v_add_u32_e32 v6, v4, v6
	v_bfe_i32 v4, v4, 27, 1
	v_lshrrev_b32_e32 v4, 22, v4
	v_add_u32_e32 v4, v5, v4
	v_and_b32_e32 v4, 0xfffffc00, v4
	v_sub_u32_e32 v4, v5, v4
	v_ashrrev_i32_e32 v12, 6, v6
	v_lshrrev_b32_e32 v6, 4, v4
	v_bitop3_b32 v4, v6, v4, 32 bitop3:0x6c
	v_ashrrev_i32_e32 v7, 31, v4
	v_lshrrev_b32_e32 v7, 26, v7
	v_add_u32_e32 v7, v4, v7
	v_lshlrev_b32_e32 v6, 3, v12
	v_ashrrev_i32_e32 v13, 6, v7
	v_and_b32_e32 v7, 0xc0, v7
	v_and_b32_e32 v6, -16, v6
	v_sub_u32_e32 v4, v4, v7
	v_mov_b32_e32 v7, 1
	v_add_u32_e32 v6, v13, v6
	v_ashrrev_i16_sdwa v4, v7, sext(v4) dst_sel:DWORD dst_unused:UNUSED_PAD src0_sel:DWORD src1_sel:BYTE_0
	v_lshlrev_b32_e32 v8, 5, v12
	v_bfe_i32 v14, v4, 0, 16
	v_lshlrev_b32_e32 v4, 1, v6
	v_lshrrev_b32_e32 v9, 2, v6
	v_and_b32_e32 v10, 3, v13
	s_mov_b32 s1, 0x1fffe0
	v_and_b32_e32 v8, 32, v8
	v_and_b32_e32 v4, 24, v4
	v_and_b32_e32 v9, 4, v9
	v_and_or_b32 v10, v6, s1, v10
	v_or3_b32 v4, v10, v9, v4
	v_add_lshl_u32 v8, v8, v14, 1
	v_lshl_add_u32 v134, v4, 11, v8
	v_add_u32_e32 v4, 0x2000, v5
	v_ashrrev_i32_e32 v5, 31, v4
	v_lshrrev_b32_e32 v5, 22, v5
	v_add_u32_e32 v5, v4, v5
	v_ashrrev_i32_e32 v15, 10, v5
	v_mul_i32_i24_e32 v5, 0x400, v15
	v_sub_u32_e32 v4, v4, v5
	v_lshrrev_b32_e32 v5, 4, v4
	v_bitop3_b32 v4, v5, v4, 32 bitop3:0x6c
	v_lshl_add_u32 v132, v6, 11, v8
	v_ashrrev_i32_e32 v6, 31, v4
	v_lshrrev_b32_e32 v6, 26, v6
	v_add_u32_e32 v6, v4, v6
	s_ashr_i32 s0, s5, 3
	v_lshlrev_b32_e32 v5, 3, v15
	v_ashrrev_i32_e32 v16, 6, v6
	v_and_b32_e32 v6, 0xc0, v6
	s_add_u32 s38, s82, 0x8600000
	v_and_b32_e32 v5, -16, v5
	v_sub_u32_e32 v4, v4, v6
	s_addc_u32 s39, s83, 0
	v_add_u32_e32 v5, v16, v5
	v_ashrrev_i16_sdwa v4, v7, sext(v4) dst_sel:DWORD dst_unused:UNUSED_PAD src0_sel:DWORD src1_sel:BYTE_0
	v_and_b32_e32 v7, 3, v16
	s_add_i32 s0, s4, s0
	v_and_or_b32 v7, v5, s1, v7
	s_ashr_i32 s1, s0, 31
	s_lshr_b32 s1, s1, 27
	s_add_i32 s1, s0, s1
	s_ashr_i32 s4, s1, 5
	s_andn2_b32 s1, s1, 31
	s_sub_i32 s1, s0, s1
	s_bfe_i32 s0, s1, 0x80000
	s_bfe_u32 s0, s0, 0x3000c
	s_add_i32 s5, s1, s0
	s_bfe_i32 s0, s5, 0x80000
	s_and_b32 s5, s5, 0xf8
	s_sub_i32 s1, s1, s5
	s_lshl_b32 s4, s4, 3
	s_sext_i32_i16 s0, s0
	s_sext_i32_i8 s1, s1
	s_lshr_b32 s0, s0, 3
	s_add_i32 s12, s4, s1
	s_ashr_i32 s7, s3, 6
	s_ashr_i32 s13, s12, 31
	s_bfe_i64 s[16:17], s[0:1], 0x100000
	s_ashr_i32 s36, s3, 8
	s_lshl_b32 s40, s7, 10
	s_lshl_b64 s[4:5], s[12:13], 19
	s_lshl_b64 s[16:17], s[16:17], 19
	s_add_u32 s28, s10, s16
	v_lshlrev_b32_e32 v8, 5, v15
	v_bfe_i32 v17, v4, 0, 16
	v_lshlrev_b32_e32 v4, 1, v5
	v_lshrrev_b32_e32 v6, 2, v5
	s_addc_u32 s29, s11, s17
	s_add_i32 s13, s40, 0
	v_and_b32_e32 v8, 32, v8
	v_and_b32_e32 v4, 24, v4
	v_and_b32_e32 v6, 4, v6
	s_add_i32 m0, s13, 0x10000
	v_or3_b32 v4, v7, v6, v4
	v_add_lshl_u32 v6, v8, v17, 1
	global_load_lds_dwordx4 v134, s[28:29]
	s_add_i32 m0, s13, 0x12000
	v_lshl_add_u32 v138, v4, 11, v6
	s_add_u32 s16, s28, 0x40000
	global_load_lds_dwordx4 v138, s[28:29]
	s_addc_u32 s17, s29, 0
	s_add_i32 m0, s13, 0x14000
	v_lshl_add_u32 v136, v5, 11, v6
	global_load_lds_dwordx4 v134, s[16:17]
	s_add_i32 m0, s13, 0x16000
	v_mov_b32_e32 v135, 0
	global_load_lds_dwordx4 v138, s[16:17]
	s_add_u32 s16, s38, s4
	s_addc_u32 s17, s39, s5
	s_add_i32 s41, s13, 0x2000
	s_mov_b32 m0, s13
	s_add_u32 s4, s16, 0x40000
	global_load_lds_dwordx4 v132, s[16:17]
	s_mov_b32 m0, s41
	s_addc_u32 s5, s17, 0
	s_add_i32 s42, s13, 0x4000
	global_load_lds_dwordx4 v136, s[16:17]
	s_mov_b32 m0, s42
	s_add_i32 s43, s13, 0x6000
	global_load_lds_dwordx4 v132, s[4:5]
	s_mov_b32 m0, s43
	v_mov_b32_e32 v139, v135
	global_load_lds_dwordx4 v136, s[4:5]
	v_mov_b32_e32 v133, v135
	v_mov_b32_e32 v137, v135
	v_lshl_add_u64 v[10:11], s[28:29], 0, v[134:135]
	v_lshl_add_u64 v[8:9], s[28:29], 0, v[138:139]
	v_lshl_add_u64 v[6:7], s[16:17], 0, v[132:133]
	s_cmp_lg_u32 s36, 1
	v_lshl_add_u64 v[4:5], s[16:17], 0, v[136:137]
	s_cbranch_scc1 .LBB0_669
	s_barrier
	s_setprio 1

.LBB0_679:
	v_add_u32_e32 v168, s47, v153
	v_add_u32_e32 v184, s48, v153
	s_add_u32 s30, s16, s28
	ds_read_b128 v[156:159], v168
	ds_read_b128 v[160:163], v168 offset:1024
	ds_read_b128 v[164:167], v168 offset:2048
	ds_read_b128 v[168:171], v168 offset:3072
	ds_read_b128 v[172:175], v184
	ds_read_b128 v[176:179], v184 offset:1024
	ds_read_b128 v[180:183], v184 offset:2048
	ds_read_b128 v[184:187], v184 offset:3072
	s_addc_u32 s31, s17, s29
	s_add_u32 s30, s30, 0x100
	s_addc_u32 s31, s31, 0
	s_add_u32 s61, s50, s28
	s_addc_u32 s64, s51, s29
	s_cmpk_eq_i32 s28, 0x700
	s_cselect_b32 s35, s23, s31
	s_cselect_b32 s34, s58, s30
	s_cselect_b32 s31, s21, s64
	s_cselect_b32 s30, s59, s61
	v_lshl_add_u64 v[188:189], v[148:149], 0, s[28:29]
	s_add_i32 m0, s13, 0xc000
	ds_read_b128 v[192:195], v154
	ds_read_b128 v[196:199], v154 offset:1024
	ds_read_b128 v[200:203], v154 offset:2048
	ds_read_b128 v[204:207], v154 offset:3072
	ds_read_b128 v[208:211], v154 offset:4096
	ds_read_b128 v[218:221], v154 offset:5120
	ds_read_b128 v[226:229], v154 offset:6144
	ds_read_b128 v[230:233], v154 offset:7168
	global_load_lds_dwordx4 v[188:189], off
	v_lshl_add_u64 v[188:189], v[150:151], 0, s[28:29]
	s_add_i32 m0, s13, 0xe000
	s_nop 0
	global_load_lds_dwordx4 v[188:189], off
	s_waitcnt vmcnt(8)
	s_waitcnt lgkmcnt(0)
	s_barrier
	s_waitcnt lgkmcnt(0)
	v_mfma_f32_16x16x32_bf16 v[128:131], v[156:159], v[192:195], v[128:131]
	v_mfma_f32_16x16x32_bf16 v[124:127], v[164:167], v[192:195], v[124:127]
	v_mfma_f32_16x16x32_bf16 v[112:115], v[156:159], v[200:203], v[112:115]
	v_mfma_f32_16x16x32_bf16 v[108:111], v[164:167], v[200:203], v[108:111]
	v_mfma_f32_16x16x32_bf16 v[96:99], v[156:159], v[208:211], v[96:99]
	v_mfma_f32_16x16x32_bf16 v[92:95], v[164:167], v[208:211], v[92:95]
	v_mfma_f32_16x16x32_bf16 v[80:83], v[156:159], v[226:229], v[80:83]
	v_mfma_f32_16x16x32_bf16 v[76:79], v[164:167], v[226:229], v[76:79]
	v_mfma_f32_16x16x32_bf16 v[128:131], v[160:163], v[196:199], v[128:131]
	v_mfma_f32_16x16x32_bf16 v[124:127], v[168:171], v[196:199], v[124:127]
	v_mfma_f32_16x16x32_bf16 v[112:115], v[160:163], v[204:207], v[112:115]
	v_mfma_f32_16x16x32_bf16 v[108:111], v[168:171], v[204:207], v[108:111]
	v_mfma_f32_16x16x32_bf16 v[96:99], v[160:163], v[218:221], v[96:99]
	v_mfma_f32_16x16x32_bf16 v[92:95], v[168:171], v[218:221], v[92:95]
	v_mfma_f32_16x16x32_bf16 v[80:83], v[160:163], v[230:233], v[80:83]
	v_mfma_f32_16x16x32_bf16 v[76:79], v[168:171], v[230:233], v[76:79]
	v_mfma_f32_16x16x32_bf16 v[120:123], v[172:175], v[192:195], v[120:123]
	v_mfma_f32_16x16x32_bf16 v[116:119], v[180:183], v[192:195], v[116:119]
	v_mfma_f32_16x16x32_bf16 v[104:107], v[172:175], v[200:203], v[104:107]
	v_mfma_f32_16x16x32_bf16 v[100:103], v[180:183], v[200:203], v[100:103]
	v_mfma_f32_16x16x32_bf16 v[88:91], v[172:175], v[208:211], v[88:91]
	v_mfma_f32_16x16x32_bf16 v[84:87], v[180:183], v[208:211], v[84:87]
	v_mfma_f32_16x16x32_bf16 v[72:75], v[172:175], v[226:229], v[72:75]
	v_mfma_f32_16x16x32_bf16 v[68:71], v[180:183], v[226:229], v[68:71]
	v_mfma_f32_16x16x32_bf16 v[120:123], v[176:179], v[196:199], v[120:123]
	v_mfma_f32_16x16x32_bf16 v[116:119], v[184:187], v[196:199], v[116:119]
	v_mfma_f32_16x16x32_bf16 v[104:107], v[176:179], v[204:207], v[104:107]
	v_mfma_f32_16x16x32_bf16 v[100:103], v[184:187], v[204:207], v[100:103]
	v_mfma_f32_16x16x32_bf16 v[88:91], v[176:179], v[218:221], v[88:91]
	v_mfma_f32_16x16x32_bf16 v[84:87], v[184:187], v[218:221], v[84:87]
	v_mfma_f32_16x16x32_bf16 v[72:75], v[176:179], v[230:233], v[72:75]
	v_mfma_f32_16x16x32_bf16 v[68:71], v[184:187], v[230:233], v[68:71]
	s_barrier
	s_add_i32 s61, s47, s40
	v_lshl_add_u64 v[188:189], s[30:31], 0, v[134:135]
	s_mov_b32 m0, s61
	ds_read_b128 v[192:195], v154 offset:16384
	ds_read_b128 v[196:199], v154 offset:17408
	ds_read_b128 v[200:203], v154 offset:18432
	ds_read_b128 v[204:207], v154 offset:19456
	ds_read_b128 v[208:211], v154 offset:20480
	ds_read_b128 v[218:221], v154 offset:21504
	ds_read_b128 v[226:229], v154 offset:22528
	ds_read_b128 v[230:233], v154 offset:23552
	global_load_lds_dwordx4 v[188:189], off
	s_add_i32 m0, s61, 0x2000
	s_add_u32 s64, s30, 0x40000
	v_lshl_add_u64 v[234:235], s[30:31], 0, v[138:139]
	s_addc_u32 s65, s31, 0
	s_add_i32 s61, s48, s40
	global_load_lds_dwordx4 v[234:235], off
	v_lshl_add_u64 v[236:237], s[64:65], 0, v[134:135]
	s_mov_b32 m0, s61
	v_lshl_add_u64 v[238:239], s[34:35], 0, v[136:137]
	global_load_lds_dwordx4 v[236:237], off
	v_lshl_add_u64 v[236:237], s[64:65], 0, v[138:139]
	s_add_i32 m0, s61, 0x2000
	s_nop 0
	global_load_lds_dwordx4 v[236:237], off
	v_lshl_add_u64 v[236:237], s[34:35], 0, v[132:133]
	s_mov_b32 m0, s13
	s_nop 0
	global_load_lds_dwordx4 v[236:237], off
	s_mov_b32 m0, s41
	s_nop 0
	global_load_lds_dwordx4 v[238:239], off
	s_waitcnt vmcnt(8)
	s_waitcnt lgkmcnt(0)
	s_barrier
	s_waitcnt lgkmcnt(0)
	v_mfma_f32_16x16x32_bf16 v[64:67], v[156:159], v[192:195], v[64:67]
	v_mfma_f32_16x16x32_bf16 v[60:63], v[164:167], v[192:195], v[60:63]
	v_mfma_f32_16x16x32_bf16 v[48:51], v[156:159], v[200:203], v[48:51]
	v_mfma_f32_16x16x32_bf16 v[44:47], v[164:167], v[200:203], v[44:47]
	v_mfma_f32_16x16x32_bf16 v[32:35], v[156:159], v[208:211], v[32:35]
	v_mfma_f32_16x16x32_bf16 v[28:31], v[164:167], v[208:211], v[28:31]
	v_mfma_f32_16x16x32_bf16 v[16:19], v[156:159], v[226:229], v[16:19]
	v_mfma_f32_16x16x32_bf16 v[12:15], v[164:167], v[226:229], v[12:15]
	v_mfma_f32_16x16x32_bf16 v[64:67], v[160:163], v[196:199], v[64:67]
	v_mfma_f32_16x16x32_bf16 v[60:63], v[168:171], v[196:199], v[60:63]
	v_mfma_f32_16x16x32_bf16 v[48:51], v[160:163], v[204:207], v[48:51]
	v_mfma_f32_16x16x32_bf16 v[44:47], v[168:171], v[204:207], v[44:47]
	v_mfma_f32_16x16x32_bf16 v[32:35], v[160:163], v[218:221], v[32:35]
	v_mfma_f32_16x16x32_bf16 v[28:31], v[168:171], v[218:221], v[28:31]
	v_mfma_f32_16x16x32_bf16 v[16:19], v[160:163], v[230:233], v[16:19]
	v_mfma_f32_16x16x32_bf16 v[12:15], v[168:171], v[230:233], v[12:15]
	v_mfma_f32_16x16x32_bf16 v[56:59], v[172:175], v[192:195], v[56:59]
	v_mfma_f32_16x16x32_bf16 v[52:55], v[180:183], v[192:195], v[52:55]
	v_mfma_f32_16x16x32_bf16 v[40:43], v[172:175], v[200:203], v[40:43]
	v_mfma_f32_16x16x32_bf16 v[36:39], v[180:183], v[200:203], v[36:39]
	v_mfma_f32_16x16x32_bf16 v[24:27], v[172:175], v[208:211], v[24:27]
	v_mfma_f32_16x16x32_bf16 v[20:23], v[180:183], v[208:211], v[20:23]
	v_mfma_f32_16x16x32_bf16 v[8:11], v[172:175], v[226:229], v[8:11]
	v_mfma_f32_16x16x32_bf16 v[4:7], v[180:183], v[226:229], v[4:7]
	v_mfma_f32_16x16x32_bf16 v[56:59], v[176:179], v[196:199], v[56:59]
	v_mfma_f32_16x16x32_bf16 v[52:55], v[184:187], v[196:199], v[52:55]
	v_mfma_f32_16x16x32_bf16 v[40:43], v[176:179], v[204:207], v[40:43]
	v_mfma_f32_16x16x32_bf16 v[36:39], v[184:187], v[204:207], v[36:39]
	v_mfma_f32_16x16x32_bf16 v[24:27], v[176:179], v[218:221], v[24:27]
	v_mfma_f32_16x16x32_bf16 v[20:23], v[184:187], v[218:221], v[20:23]
	v_mfma_f32_16x16x32_bf16 v[8:11], v[176:179], v[230:233], v[8:11]
	v_mfma_f32_16x16x32_bf16 v[4:7], v[184:187], v[230:233], v[4:7]
	s_barrier
	s_add_i32 s61, 0, 0x18000
	s_add_i32 s64, 0, 0x1c000
	v_add_u32_e32 v168, s61, v153
	v_add_u32_e32 v184, s64, v153
	ds_read_b128 v[156:159], v168
	ds_read_b128 v[160:163], v168 offset:1024
	ds_read_b128 v[164:167], v168 offset:2048
	ds_read_b128 v[168:171], v168 offset:3072
	ds_read_b128 v[172:175], v184
	ds_read_b128 v[176:179], v184 offset:1024
	ds_read_b128 v[180:183], v184 offset:2048
	ds_read_b128 v[184:187], v184 offset:3072
	s_add_u32 s34, s34, 0x40000
	s_addc_u32 s35, s35, 0
	s_mov_b32 m0, s42
	v_lshl_add_u64 v[240:241], s[34:35], 0, v[132:133]
	ds_read_b128 v[192:195], v154 offset:32768
	ds_read_b128 v[196:199], v154 offset:33792
	ds_read_b128 v[200:203], v154 offset:34816
	ds_read_b128 v[204:207], v154 offset:35840
	ds_read_b128 v[208:211], v154 offset:36864
	ds_read_b128 v[218:221], v154 offset:37888
	ds_read_b128 v[226:229], v154 offset:38912
	ds_read_b128 v[230:233], v154 offset:39936
	global_load_lds_dwordx4 v[240:241], off
	v_lshl_add_u64 v[240:241], s[34:35], 0, v[136:137]
	s_mov_b32 m0, s43
	s_nop 0
	global_load_lds_dwordx4 v[240:241], off
	s_waitcnt vmcnt(8)
	s_waitcnt lgkmcnt(0)
	s_barrier
	s_waitcnt lgkmcnt(0)
	v_mfma_f32_16x16x32_bf16 v[128:131], v[156:159], v[192:195], v[128:131]
	v_mfma_f32_16x16x32_bf16 v[124:127], v[164:167], v[192:195], v[124:127]
	v_mfma_f32_16x16x32_bf16 v[112:115], v[156:159], v[200:203], v[112:115]
	v_mfma_f32_16x16x32_bf16 v[108:111], v[164:167], v[200:203], v[108:111]
	v_mfma_f32_16x16x32_bf16 v[96:99], v[156:159], v[208:211], v[96:99]
	v_mfma_f32_16x16x32_bf16 v[92:95], v[164:167], v[208:211], v[92:95]
	v_mfma_f32_16x16x32_bf16 v[80:83], v[156:159], v[226:229], v[80:83]
	v_mfma_f32_16x16x32_bf16 v[76:79], v[164:167], v[226:229], v[76:79]
	v_mfma_f32_16x16x32_bf16 v[128:131], v[160:163], v[196:199], v[128:131]
	v_mfma_f32_16x16x32_bf16 v[124:127], v[168:171], v[196:199], v[124:127]
	v_mfma_f32_16x16x32_bf16 v[112:115], v[160:163], v[204:207], v[112:115]
	v_mfma_f32_16x16x32_bf16 v[108:111], v[168:171], v[204:207], v[108:111]
	v_mfma_f32_16x16x32_bf16 v[96:99], v[160:163], v[218:221], v[96:99]
	v_mfma_f32_16x16x32_bf16 v[92:95], v[168:171], v[218:221], v[92:95]
	v_mfma_f32_16x16x32_bf16 v[80:83], v[160:163], v[230:233], v[80:83]
	v_mfma_f32_16x16x32_bf16 v[76:79], v[168:171], v[230:233], v[76:79]
	v_mfma_f32_16x16x32_bf16 v[120:123], v[172:175], v[192:195], v[120:123]
	v_mfma_f32_16x16x32_bf16 v[116:119], v[180:183], v[192:195], v[116:119]
	v_mfma_f32_16x16x32_bf16 v[104:107], v[172:175], v[200:203], v[104:107]
	v_mfma_f32_16x16x32_bf16 v[100:103], v[180:183], v[200:203], v[100:103]
	v_mfma_f32_16x16x32_bf16 v[88:91], v[172:175], v[208:211], v[88:91]
	v_mfma_f32_16x16x32_bf16 v[84:87], v[180:183], v[208:211], v[84:87]
	v_mfma_f32_16x16x32_bf16 v[72:75], v[172:175], v[226:229], v[72:75]
	v_mfma_f32_16x16x32_bf16 v[68:71], v[180:183], v[226:229], v[68:71]
	v_mfma_f32_16x16x32_bf16 v[120:123], v[176:179], v[196:199], v[120:123]
	v_mfma_f32_16x16x32_bf16 v[116:119], v[184:187], v[196:199], v[116:119]
	v_mfma_f32_16x16x32_bf16 v[104:107], v[176:179], v[204:207], v[104:107]
	v_mfma_f32_16x16x32_bf16 v[100:103], v[184:187], v[204:207], v[100:103]
	v_mfma_f32_16x16x32_bf16 v[88:91], v[176:179], v[218:221], v[88:91]
	v_mfma_f32_16x16x32_bf16 v[84:87], v[184:187], v[218:221], v[84:87]
	v_mfma_f32_16x16x32_bf16 v[72:75], v[176:179], v[230:233], v[72:75]
	v_mfma_f32_16x16x32_bf16 v[68:71], v[184:187], v[230:233], v[68:71]
	s_barrier
	s_add_i32 s34, s61, s40
	v_lshl_add_u64 v[188:189], v[188:189], 0, s[18:19]
	s_mov_b32 m0, s34
	ds_read_b128 v[192:195], v154 offset:49152
	ds_read_b128 v[196:199], v154 offset:50176
	ds_read_b128 v[200:203], v154 offset:51200
	ds_read_b128 v[204:207], v154 offset:52224
	ds_read_b128 v[208:211], v154 offset:53248
	ds_read_b128 v[218:221], v154 offset:54272
	ds_read_b128 v[226:229], v154 offset:55296
	ds_read_b128 v[230:233], v154 offset:56320
	global_load_lds_dwordx4 v[188:189], off
	s_add_i32 m0, s34, 0x2000
	s_add_u32 s30, s30, 0x40080
	v_lshl_add_u64 v[188:189], v[234:235], 0, s[18:19]
	s_addc_u32 s31, s31, 0
	s_add_i32 s34, s64, s40
	global_load_lds_dwordx4 v[188:189], off
	v_lshl_add_u64 v[188:189], s[30:31], 0, v[134:135]
	s_mov_b32 m0, s34
	s_nop 0
	global_load_lds_dwordx4 v[188:189], off
	v_lshl_add_u64 v[188:189], s[30:31], 0, v[138:139]
	s_add_i32 m0, s34, 0x2000
	s_nop 0
	global_load_lds_dwordx4 v[188:189], off
	v_lshl_add_u64 v[188:189], v[236:237], 0, s[18:19]
	s_mov_b32 m0, s44
	s_nop 0
	global_load_lds_dwordx4 v[188:189], off
	v_lshl_add_u64 v[188:189], v[238:239], 0, s[18:19]
	s_mov_b32 m0, s45
	s_nop 0
	global_load_lds_dwordx4 v[188:189], off
	s_waitcnt vmcnt(8)
	s_waitcnt lgkmcnt(0)
	s_barrier
	s_waitcnt lgkmcnt(0)
	v_mfma_f32_16x16x32_bf16 v[64:67], v[156:159], v[192:195], v[64:67]
	v_mfma_f32_16x16x32_bf16 v[60:63], v[164:167], v[192:195], v[60:63]
	v_mfma_f32_16x16x32_bf16 v[48:51], v[156:159], v[200:203], v[48:51]
	v_mfma_f32_16x16x32_bf16 v[44:47], v[164:167], v[200:203], v[44:47]
	v_mfma_f32_16x16x32_bf16 v[32:35], v[156:159], v[208:211], v[32:35]
	v_mfma_f32_16x16x32_bf16 v[28:31], v[164:167], v[208:211], v[28:31]
	v_mfma_f32_16x16x32_bf16 v[16:19], v[156:159], v[226:229], v[16:19]
	v_mfma_f32_16x16x32_bf16 v[12:15], v[164:167], v[226:229], v[12:15]
	v_mfma_f32_16x16x32_bf16 v[64:67], v[160:163], v[196:199], v[64:67]
	v_mfma_f32_16x16x32_bf16 v[60:63], v[168:171], v[196:199], v[60:63]
	v_mfma_f32_16x16x32_bf16 v[48:51], v[160:163], v[204:207], v[48:51]
	v_mfma_f32_16x16x32_bf16 v[44:47], v[168:171], v[204:207], v[44:47]
	v_mfma_f32_16x16x32_bf16 v[32:35], v[160:163], v[218:221], v[32:35]
	v_mfma_f32_16x16x32_bf16 v[28:31], v[168:171], v[218:221], v[28:31]
	v_mfma_f32_16x16x32_bf16 v[16:19], v[160:163], v[230:233], v[16:19]
	v_mfma_f32_16x16x32_bf16 v[12:15], v[168:171], v[230:233], v[12:15]
	v_mfma_f32_16x16x32_bf16 v[56:59], v[172:175], v[192:195], v[56:59]
	v_mfma_f32_16x16x32_bf16 v[52:55], v[180:183], v[192:195], v[52:55]
	v_mfma_f32_16x16x32_bf16 v[40:43], v[172:175], v[200:203], v[40:43]
	v_mfma_f32_16x16x32_bf16 v[36:39], v[180:183], v[200:203], v[36:39]
	v_mfma_f32_16x16x32_bf16 v[24:27], v[172:175], v[208:211], v[24:27]
	v_mfma_f32_16x16x32_bf16 v[20:23], v[180:183], v[208:211], v[20:23]
	v_mfma_f32_16x16x32_bf16 v[8:11], v[172:175], v[226:229], v[8:11]
	v_mfma_f32_16x16x32_bf16 v[4:7], v[180:183], v[226:229], v[4:7]
	v_mfma_f32_16x16x32_bf16 v[56:59], v[176:179], v[196:199], v[56:59]
	v_mfma_f32_16x16x32_bf16 v[52:55], v[184:187], v[196:199], v[52:55]
	v_mfma_f32_16x16x32_bf16 v[40:43], v[176:179], v[204:207], v[40:43]
	v_mfma_f32_16x16x32_bf16 v[36:39], v[184:187], v[204:207], v[36:39]
	v_mfma_f32_16x16x32_bf16 v[24:27], v[176:179], v[218:221], v[24:27]
	v_mfma_f32_16x16x32_bf16 v[20:23], v[184:187], v[218:221], v[20:23]
	v_mfma_f32_16x16x32_bf16 v[8:11], v[176:179], v[230:233], v[8:11]
	v_mfma_f32_16x16x32_bf16 v[4:7], v[184:187], v[230:233], v[4:7]
	s_barrier
	s_add_i32 s60, s60, 2
	s_add_u32 s28, s28, 0x100
	s_addc_u32 s29, s29, 0
	s_cmp_gt_u32 s60, 13
	s_cbranch_scc0 .LBB0_679
	s_add_u32 s28, s50, 0xffffff00
	s_addc_u32 s29, s51, -1
	s_andn2_b64 vcc, exec, s[4:5]
	s_cbranch_vccnz .LBB0_670
	v_mov_b32_e32 v4, 0
	s_mov_b32 s6, s20
	s_mov_b32 s12, s22
	s_mov_b64 s[16:17], s[26:27]
	s_mov_b32 s46, s49
	v_mov_b32_e32 v5, v4
	v_mov_b32_e32 v6, v4
	v_mov_b32_e32 v7, v4
	v_mov_b32_e32 v8, v4
	v_mov_b32_e32 v9, v4
	v_mov_b32_e32 v10, v4
	v_mov_b32_e32 v11, v4
	v_mov_b32_e32 v20, v4
	v_mov_b32_e32 v21, v4
	v_mov_b32_e32 v22, v4
	v_mov_b32_e32 v23, v4
	v_mov_b32_e32 v24, v4
	v_mov_b32_e32 v25, v4
	v_mov_b32_e32 v26, v4
	v_mov_b32_e32 v27, v4
	v_mov_b32_e32 v36, v4
	v_mov_b32_e32 v37, v4
	v_mov_b32_e32 v38, v4
	v_mov_b32_e32 v39, v4
	v_mov_b32_e32 v40, v4
	v_mov_b32_e32 v41, v4
	v_mov_b32_e32 v42, v4
	v_mov_b32_e32 v43, v4
	v_mov_b32_e32 v52, v4
	v_mov_b32_e32 v53, v4
	v_mov_b32_e32 v54, v4
	v_mov_b32_e32 v55, v4
	v_mov_b32_e32 v56, v4
	v_mov_b32_e32 v57, v4
	v_mov_b32_e32 v58, v4
	v_mov_b32_e32 v59, v4
	v_mov_b32_e32 v12, v4
	v_mov_b32_e32 v13, v4
	v_mov_b32_e32 v14, v4
	v_mov_b32_e32 v15, v4
	v_mov_b32_e32 v16, v4
	v_mov_b32_e32 v17, v4
	v_mov_b32_e32 v18, v4
	v_mov_b32_e32 v19, v4
	v_mov_b32_e32 v28, v4
	v_mov_b32_e32 v29, v4
	v_mov_b32_e32 v30, v4
	v_mov_b32_e32 v31, v4
	v_mov_b32_e32 v32, v4
	v_mov_b32_e32 v33, v4
	v_mov_b32_e32 v34, v4
	v_mov_b32_e32 v35, v4
	v_mov_b32_e32 v44, v4
	v_mov_b32_e32 v45, v4
	v_mov_b32_e32 v46, v4
	v_mov_b32_e32 v47, v4
	v_mov_b32_e32 v48, v4
	v_mov_b32_e32 v49, v4
	v_mov_b32_e32 v50, v4
	v_mov_b32_e32 v51, v4
	v_mov_b32_e32 v60, v4
	v_mov_b32_e32 v61, v4
	v_mov_b32_e32 v62, v4
	v_mov_b32_e32 v63, v4
	v_mov_b32_e32 v64, v4
	v_mov_b32_e32 v65, v4
	v_mov_b32_e32 v66, v4
	v_mov_b32_e32 v67, v4
	v_mov_b32_e32 v68, v4
	v_mov_b32_e32 v69, v4
	v_mov_b32_e32 v70, v4
	v_mov_b32_e32 v71, v4
	v_mov_b32_e32 v72, v4
	v_mov_b32_e32 v73, v4
	v_mov_b32_e32 v74, v4
	v_mov_b32_e32 v75, v4
	v_mov_b32_e32 v84, v4
	v_mov_b32_e32 v85, v4
	v_mov_b32_e32 v86, v4
	v_mov_b32_e32 v87, v4
	v_mov_b32_e32 v88, v4
	v_mov_b32_e32 v89, v4
	v_mov_b32_e32 v90, v4
	v_mov_b32_e32 v91, v4
	v_mov_b32_e32 v100, v4
	v_mov_b32_e32 v101, v4
	v_mov_b32_e32 v102, v4
	v_mov_b32_e32 v103, v4
	v_mov_b32_e32 v104, v4
	v_mov_b32_e32 v105, v4
	v_mov_b32_e32 v106, v4
	v_mov_b32_e32 v107, v4
	v_mov_b32_e32 v116, v4
	v_mov_b32_e32 v117, v4
	v_mov_b32_e32 v118, v4
	v_mov_b32_e32 v119, v4
	v_mov_b32_e32 v120, v4
	v_mov_b32_e32 v121, v4
	v_mov_b32_e32 v122, v4
	v_mov_b32_e32 v123, v4
	v_mov_b32_e32 v76, v4
	v_mov_b32_e32 v77, v4
	v_mov_b32_e32 v78, v4
	v_mov_b32_e32 v79, v4
	v_mov_b32_e32 v80, v4
	v_mov_b32_e32 v81, v4
	v_mov_b32_e32 v82, v4
	v_mov_b32_e32 v83, v4
	v_mov_b32_e32 v92, v4
	v_mov_b32_e32 v93, v4
	v_mov_b32_e32 v94, v4
	v_mov_b32_e32 v95, v4
	v_mov_b32_e32 v96, v4
	v_mov_b32_e32 v97, v4
	v_mov_b32_e32 v98, v4
	v_mov_b32_e32 v99, v4
	v_mov_b32_e32 v108, v4
	v_mov_b32_e32 v109, v4
	v_mov_b32_e32 v110, v4
	v_mov_b32_e32 v111, v4
	v_mov_b32_e32 v112, v4
	v_mov_b32_e32 v113, v4
	v_mov_b32_e32 v114, v4
	v_mov_b32_e32 v115, v4
	v_mov_b32_e32 v124, v4
	v_mov_b32_e32 v125, v4
	v_mov_b32_e32 v126, v4
	v_mov_b32_e32 v127, v4
	v_mov_b32_e32 v128, v4
	v_mov_b32_e32 v129, v4
	v_mov_b32_e32 v130, v4
	v_mov_b32_e32 v131, v4
	s_andn2_b64 vcc, exec, s[0:1]
	s_cbranch_vccnz .LBB0_671

.LBB0_730:
	v_readlane_b32 s0, v244, 3
	v_readlane_b32 s1, v244, 4
	s_cmp_gt_i32 s1, 4
	s_cselect_b64 s[0:1], -1, 0
	s_and_b64 s[4:5], s[8:9], s[0:1]
	s_andn2_b64 vcc, exec, s[4:5]
	s_cbranch_vccnz .LBB0_784
	s_setprio 0
	s_waitcnt vmcnt(0)
	s_waitcnt vmcnt(0) lgkmcnt(0)
	s_barrier
	s_getreg_b32 s3, hwreg(HW_REG_HW_ID, 0, 6)
	s_and_b32 s3, s3, 63
	s_lshl_b32 s3, s3, 2
	s_add_i32 s3, s3, 0
	s_mov_b64 s[4:5], src_shared_base
	s_add_i32 s3, s3, 0x23e00
	v_mov_b32_e32 v4, s3
	v_mov_b32_e32 v5, s5
	flat_load_dword v3, v[4:5] sc0 sc1
	s_waitcnt vmcnt(0) lgkmcnt(0)
	v_readfirstlane_b32 s3, v3
	s_cmp_lg_u32 s3, 1
	s_cbranch_scc1 .Learlyinv_skip3
	buffer_inv sc1
	s_waitcnt vmcnt(0)

.LBB0_808:
	v_ashrrev_i32_e32 v5, 31, v3
	v_lshrrev_b32_e32 v5, 26, v5
	v_lshlrev_b32_e32 v4, 4, v3
	v_add_u32_e32 v5, v3, v5
	v_bfe_i32 v3, v3, 27, 1
	v_lshrrev_b32_e32 v3, 22, v3
	v_add_u32_e32 v3, v4, v3
	v_and_b32_e32 v3, 0xfffffc00, v3
	v_sub_u32_e32 v3, v4, v3
	v_ashrrev_i32_e32 v12, 6, v5
	v_lshrrev_b32_e32 v5, 4, v3
	v_bitop3_b32 v3, v5, v3, 32 bitop3:0x6c
	v_ashrrev_i32_e32 v6, 31, v3
	v_lshrrev_b32_e32 v6, 26, v6
	v_add_u32_e32 v6, v3, v6
	v_lshlrev_b32_e32 v5, 3, v12
	v_ashrrev_i32_e32 v13, 6, v6
	v_and_b32_e32 v6, 0xc0, v6
	v_and_b32_e32 v5, -16, v5
	v_sub_u32_e32 v3, v3, v6
	v_mov_b32_e32 v6, 1
	v_add_u32_e32 v5, v13, v5
	v_ashrrev_i16_sdwa v3, v6, sext(v3) dst_sel:DWORD dst_unused:UNUSED_PAD src0_sel:DWORD src1_sel:BYTE_0
	s_ashr_i32 s0, s9, 3
	v_lshlrev_b32_e32 v7, 5, v12
	v_bfe_i32 v14, v3, 0, 16
	v_lshlrev_b32_e32 v3, 1, v5
	v_lshrrev_b32_e32 v8, 2, v5
	v_and_b32_e32 v9, 3, v13
	s_mov_b32 s9, 0x1fffe0
	v_and_b32_e32 v7, 32, v7
	v_and_b32_e32 v3, 24, v3
	v_and_b32_e32 v8, 4, v8
	v_and_or_b32 v9, v5, s9, v9
	v_or3_b32 v3, v9, v8, v3
	v_add_lshl_u32 v7, v7, v14, 1
	v_lshl_add_u32 v134, v3, 11, v7
	v_add_u32_e32 v3, 0x2000, v4
	v_ashrrev_i32_e32 v4, 31, v3
	v_lshrrev_b32_e32 v4, 22, v4
	v_add_u32_e32 v4, v3, v4
	v_ashrrev_i32_e32 v15, 10, v4
	v_mul_i32_i24_e32 v4, 0x400, v15
	v_sub_u32_e32 v3, v3, v4
	v_lshrrev_b32_e32 v4, 4, v3
	v_bitop3_b32 v3, v4, v3, 32 bitop3:0x6c
	v_lshl_add_u32 v132, v5, 11, v7
	v_ashrrev_i32_e32 v5, 31, v3
	v_lshrrev_b32_e32 v5, 26, v5
	v_add_u32_e32 v5, v3, v5
	s_add_i32 s0, s8, s0
	v_lshlrev_b32_e32 v4, 3, v15
	v_ashrrev_i32_e32 v16, 6, v5
	v_and_b32_e32 v5, 0xc0, v5
	s_ashr_i32 s8, s0, 31
	v_and_b32_e32 v4, -16, v4
	v_sub_u32_e32 v3, v3, v5
	s_lshr_b32 s8, s8, 25
	v_add_u32_e32 v4, v16, v4
	v_ashrrev_i16_sdwa v3, v6, sext(v3) dst_sel:DWORD dst_unused:UNUSED_PAD src0_sel:DWORD src1_sel:BYTE_0
	v_and_b32_e32 v6, 3, v16
	s_add_i32 s8, s0, s8
	v_and_or_b32 v6, v4, s9, v6
	s_ashr_i32 s9, s8, 7
	s_and_b32 s8, s8, 0xffffff80
	s_sub_i32 s8, s0, s8
	s_bfe_i32 s0, s8, 0x80000
	s_bfe_u32 s0, s0, 0x3000c
	s_add_i32 s11, s8, s0
	s_bfe_i32 s0, s11, 0x80000
	s_and_b32 s11, s11, 0xf8
	s_sub_i32 s8, s8, s11
	s_lshl_b32 s9, s9, 3
	s_sext_i32_i16 s0, s0
	s_sext_i32_i8 s8, s8
	s_ashr_i32 s1, s16, 8
	s_lshr_b32 s0, s0, 3
	s_add_i32 s36, s9, s8
	s_ashr_i32 s10, s16, 6
	s_ashr_i32 s37, s36, 31
	s_bfe_i64 s[12:13], s[0:1], 0x100000
	s_lshl_b32 s33, s10, 10
	s_lshl_b64 s[8:9], s[36:37], 19
	s_lshl_b64 s[12:13], s[12:13], 19
	s_add_u32 s40, s6, s12
	v_lshlrev_b32_e32 v7, 5, v15
	v_bfe_i32 v17, v3, 0, 16
	v_lshlrev_b32_e32 v3, 1, v4
	v_lshrrev_b32_e32 v5, 2, v4
	s_addc_u32 s41, s7, s13
	s_add_i32 s37, s33, 0
	v_and_b32_e32 v7, 32, v7
	v_and_b32_e32 v3, 24, v3
	v_and_b32_e32 v5, 4, v5
	s_add_i32 m0, s37, 0x10000
	v_or3_b32 v3, v6, v5, v3
	v_add_lshl_u32 v5, v7, v17, 1
	global_load_lds_dwordx4 v134, s[40:41]
	s_add_i32 m0, s37, 0x12000
	v_lshl_add_u32 v138, v3, 11, v5
	s_add_u32 s12, s40, 0x40000
	global_load_lds_dwordx4 v138, s[40:41]
	s_addc_u32 s13, s41, 0
	s_add_i32 m0, s37, 0x14000
	v_lshl_add_u32 v136, v4, 11, v5
	global_load_lds_dwordx4 v134, s[12:13]
	s_add_i32 m0, s37, 0x16000
	s_add_u32 s38, s62, s8
	s_addc_u32 s39, s63, s9
	s_add_i32 s44, s37, 0x2000
	global_load_lds_dwordx4 v138, s[12:13]
	s_mov_b32 m0, s37
	s_add_u32 s8, s38, 0x40000
	global_load_lds_dwordx4 v132, s[38:39]
	s_mov_b32 m0, s44
	s_addc_u32 s9, s39, 0
	s_add_i32 s45, s37, 0x4000
	global_load_lds_dwordx4 v136, s[38:39]
	s_mov_b32 m0, s45
	s_add_i32 s46, s37, 0x6000
	global_load_lds_dwordx4 v132, s[8:9]
	s_mov_b32 m0, s46
	v_mov_b32_e32 v135, 0
	global_load_lds_dwordx4 v136, s[8:9]
	v_mov_b32_e32 v139, v135
	v_mov_b32_e32 v133, v135
	v_mov_b32_e32 v137, v135
	s_cmp_eq_u32 s1, 1
	s_mov_b32 s47, 0
	v_lshl_add_u64 v[10:11], s[40:41], 0, v[134:135]
	v_lshl_add_u64 v[8:9], s[40:41], 0, v[138:139]
	v_lshl_add_u64 v[4:5], s[38:39], 0, v[132:133]
	s_cselect_b64 s[8:9], -1, 0
	s_cmp_lg_u32 s1, 1
	v_lshl_add_u64 v[6:7], s[38:39], 0, v[136:137]
	s_cbranch_scc1 .LBB0_810
	s_barrier
	s_setprio 1

.LBB0_820:
	ds_read_b128 v[148:151], v158
	ds_read_b128 v[162:165], v158 offset:1024
	ds_read_b128 v[166:169], v158 offset:2048
	ds_read_b128 v[170:173], v158 offset:3072
	ds_read_b128 v[174:177], v159
	ds_read_b128 v[178:181], v159 offset:1024
	ds_read_b128 v[182:185], v159 offset:2048
	ds_read_b128 v[186:189], v159 offset:3072
	s_add_u32 s40, s38, 0xfffc0080
	s_addc_u32 s41, s39, -1
	s_cmp_eq_u32 s71, 12
	s_cselect_b32 s43, s29, s41
	s_cselect_b32 s42, s67, s40
	s_cselect_b32 s41, s27, s70
	s_cselect_b32 s40, s68, s69
	v_lshl_add_u64 v[152:153], s[38:39], 0, v[140:141]
	s_add_i32 m0, s37, 0xc000
	ds_read_b128 v[190:193], v160
	ds_read_b128 v[194:197], v160 offset:1024
	ds_read_b128 v[198:201], v160 offset:2048
	ds_read_b128 v[202:205], v160 offset:3072
	ds_read_b128 v[206:209], v160 offset:4096
	ds_read_b128 v[218:221], v160 offset:5120
	ds_read_b128 v[226:229], v160 offset:6144
	ds_read_b128 v[230:233], v160 offset:7168
	global_load_lds_dwordx4 v[152:153], off
	v_lshl_add_u64 v[152:153], s[38:39], 0, v[142:143]
	s_add_i32 m0, s37, 0xe000
	s_nop 0
	global_load_lds_dwordx4 v[152:153], off
	s_waitcnt vmcnt(8)
	s_waitcnt lgkmcnt(0)
	s_barrier
	s_waitcnt lgkmcnt(0)
	v_mfma_f32_16x16x32_bf16 v[128:131], v[148:151], v[190:193], v[128:131]
	v_mfma_f32_16x16x32_bf16 v[124:127], v[166:169], v[190:193], v[124:127]
	v_mfma_f32_16x16x32_bf16 v[112:115], v[148:151], v[198:201], v[112:115]
	v_mfma_f32_16x16x32_bf16 v[108:111], v[166:169], v[198:201], v[108:111]
	v_mfma_f32_16x16x32_bf16 v[96:99], v[148:151], v[206:209], v[96:99]
	v_mfma_f32_16x16x32_bf16 v[92:95], v[166:169], v[206:209], v[92:95]
	v_mfma_f32_16x16x32_bf16 v[80:83], v[148:151], v[226:229], v[80:83]
	v_mfma_f32_16x16x32_bf16 v[76:79], v[166:169], v[226:229], v[76:79]
	v_mfma_f32_16x16x32_bf16 v[128:131], v[162:165], v[194:197], v[128:131]
	v_mfma_f32_16x16x32_bf16 v[124:127], v[170:173], v[194:197], v[124:127]
	v_mfma_f32_16x16x32_bf16 v[112:115], v[162:165], v[202:205], v[112:115]
	v_mfma_f32_16x16x32_bf16 v[108:111], v[170:173], v[202:205], v[108:111]
	v_mfma_f32_16x16x32_bf16 v[96:99], v[162:165], v[218:221], v[96:99]
	v_mfma_f32_16x16x32_bf16 v[92:95], v[170:173], v[218:221], v[92:95]
	v_mfma_f32_16x16x32_bf16 v[80:83], v[162:165], v[230:233], v[80:83]
	v_mfma_f32_16x16x32_bf16 v[76:79], v[170:173], v[230:233], v[76:79]
	v_mfma_f32_16x16x32_bf16 v[120:123], v[174:177], v[190:193], v[120:123]
	v_mfma_f32_16x16x32_bf16 v[116:119], v[182:185], v[190:193], v[116:119]
	v_mfma_f32_16x16x32_bf16 v[104:107], v[174:177], v[198:201], v[104:107]
	v_mfma_f32_16x16x32_bf16 v[100:103], v[182:185], v[198:201], v[100:103]
	v_mfma_f32_16x16x32_bf16 v[88:91], v[174:177], v[206:209], v[88:91]
	v_mfma_f32_16x16x32_bf16 v[84:87], v[182:185], v[206:209], v[84:87]
	v_mfma_f32_16x16x32_bf16 v[72:75], v[174:177], v[226:229], v[72:75]
	v_mfma_f32_16x16x32_bf16 v[68:71], v[182:185], v[226:229], v[68:71]
	v_mfma_f32_16x16x32_bf16 v[120:123], v[178:181], v[194:197], v[120:123]
	v_mfma_f32_16x16x32_bf16 v[116:119], v[186:189], v[194:197], v[116:119]
	v_mfma_f32_16x16x32_bf16 v[104:107], v[178:181], v[202:205], v[104:107]
	v_mfma_f32_16x16x32_bf16 v[100:103], v[186:189], v[202:205], v[100:103]
	v_mfma_f32_16x16x32_bf16 v[88:91], v[178:181], v[218:221], v[88:91]
	v_mfma_f32_16x16x32_bf16 v[84:87], v[186:189], v[218:221], v[84:87]
	v_mfma_f32_16x16x32_bf16 v[72:75], v[178:181], v[230:233], v[72:75]
	v_mfma_f32_16x16x32_bf16 v[68:71], v[186:189], v[230:233], v[68:71]
	s_barrier
	s_add_i32 s72, s58, s33
	v_lshl_add_u64 v[152:153], s[40:41], 0, v[134:135]
	s_mov_b32 m0, s72
	ds_read_b128 v[190:193], v160 offset:16384
	ds_read_b128 v[194:197], v160 offset:17408
	ds_read_b128 v[198:201], v160 offset:18432
	ds_read_b128 v[202:205], v160 offset:19456
	ds_read_b128 v[206:209], v160 offset:20480
	ds_read_b128 v[218:221], v160 offset:21504
	ds_read_b128 v[226:229], v160 offset:22528
	ds_read_b128 v[230:233], v160 offset:23552
	global_load_lds_dwordx4 v[152:153], off
	s_add_i32 m0, s72, 0x2000
	s_add_u32 s72, s40, 0x40000
	v_lshl_add_u64 v[210:211], s[40:41], 0, v[138:139]
	s_addc_u32 s73, s41, 0
	s_add_i32 s74, s59, s33
	global_load_lds_dwordx4 v[210:211], off
	v_lshl_add_u64 v[234:235], s[72:73], 0, v[134:135]
	s_mov_b32 m0, s74
	v_lshl_add_u64 v[236:237], s[42:43], 0, v[136:137]
	global_load_lds_dwordx4 v[234:235], off
	v_lshl_add_u64 v[234:235], s[72:73], 0, v[138:139]
	s_add_i32 m0, s74, 0x2000
	s_nop 0
	global_load_lds_dwordx4 v[234:235], off
	v_lshl_add_u64 v[234:235], s[42:43], 0, v[132:133]
	s_mov_b32 m0, s37
	s_nop 0
	global_load_lds_dwordx4 v[234:235], off
	s_mov_b32 m0, s44
	s_nop 0
	global_load_lds_dwordx4 v[236:237], off
	s_waitcnt vmcnt(8)
	s_waitcnt lgkmcnt(0)
	s_barrier
	s_waitcnt lgkmcnt(0)
	v_mfma_f32_16x16x32_bf16 v[64:67], v[148:151], v[190:193], v[64:67]
	v_mfma_f32_16x16x32_bf16 v[60:63], v[166:169], v[190:193], v[60:63]
	v_mfma_f32_16x16x32_bf16 v[48:51], v[148:151], v[198:201], v[48:51]
	v_mfma_f32_16x16x32_bf16 v[44:47], v[166:169], v[198:201], v[44:47]
	v_mfma_f32_16x16x32_bf16 v[32:35], v[148:151], v[206:209], v[32:35]
	v_mfma_f32_16x16x32_bf16 v[28:31], v[166:169], v[206:209], v[28:31]
	v_mfma_f32_16x16x32_bf16 v[16:19], v[148:151], v[226:229], v[16:19]
	v_mfma_f32_16x16x32_bf16 v[12:15], v[166:169], v[226:229], v[12:15]
	v_mfma_f32_16x16x32_bf16 v[64:67], v[162:165], v[194:197], v[64:67]
	v_mfma_f32_16x16x32_bf16 v[60:63], v[170:173], v[194:197], v[60:63]
	v_mfma_f32_16x16x32_bf16 v[48:51], v[162:165], v[202:205], v[48:51]
	v_mfma_f32_16x16x32_bf16 v[44:47], v[170:173], v[202:205], v[44:47]
	v_mfma_f32_16x16x32_bf16 v[32:35], v[162:165], v[218:221], v[32:35]
	v_mfma_f32_16x16x32_bf16 v[28:31], v[170:173], v[218:221], v[28:31]
	v_mfma_f32_16x16x32_bf16 v[16:19], v[162:165], v[230:233], v[16:19]
	v_mfma_f32_16x16x32_bf16 v[12:15], v[170:173], v[230:233], v[12:15]
	v_mfma_f32_16x16x32_bf16 v[56:59], v[174:177], v[190:193], v[56:59]
	v_mfma_f32_16x16x32_bf16 v[52:55], v[182:185], v[190:193], v[52:55]
	v_mfma_f32_16x16x32_bf16 v[40:43], v[174:177], v[198:201], v[40:43]
	v_mfma_f32_16x16x32_bf16 v[36:39], v[182:185], v[198:201], v[36:39]
	v_mfma_f32_16x16x32_bf16 v[24:27], v[174:177], v[206:209], v[24:27]
	v_mfma_f32_16x16x32_bf16 v[20:23], v[182:185], v[206:209], v[20:23]
	v_mfma_f32_16x16x32_bf16 v[8:11], v[174:177], v[226:229], v[8:11]
	v_mfma_f32_16x16x32_bf16 v[4:7], v[182:185], v[226:229], v[4:7]
	v_mfma_f32_16x16x32_bf16 v[56:59], v[178:181], v[194:197], v[56:59]
	v_mfma_f32_16x16x32_bf16 v[52:55], v[186:189], v[194:197], v[52:55]
	v_mfma_f32_16x16x32_bf16 v[40:43], v[178:181], v[202:205], v[40:43]
	v_mfma_f32_16x16x32_bf16 v[36:39], v[186:189], v[202:205], v[36:39]
	v_mfma_f32_16x16x32_bf16 v[24:27], v[178:181], v[218:221], v[24:27]
	v_mfma_f32_16x16x32_bf16 v[20:23], v[186:189], v[218:221], v[20:23]
	v_mfma_f32_16x16x32_bf16 v[8:11], v[178:181], v[230:233], v[8:11]
	v_mfma_f32_16x16x32_bf16 v[4:7], v[186:189], v[230:233], v[4:7]
	s_barrier
	s_add_i32 s72, 0, 0x18000
	v_add_u32_e32 v161, s72, v154
	s_add_i32 s73, 0, 0x1c000
	ds_read_b128 v[148:151], v161
	ds_read_b128 v[162:165], v161 offset:1024
	ds_read_b128 v[166:169], v161 offset:2048
	ds_read_b128 v[170:173], v161 offset:3072
	v_add_u32_e32 v161, s73, v154
	ds_read_b128 v[174:177], v161
	ds_read_b128 v[178:181], v161 offset:1024
	ds_read_b128 v[182:185], v161 offset:2048
	ds_read_b128 v[186:189], v161 offset:3072
	s_add_u32 s42, s42, 0x40000
	s_addc_u32 s43, s43, 0
	s_mov_b32 m0, s45
	v_lshl_add_u64 v[238:239], s[42:43], 0, v[132:133]
	ds_read_b128 v[190:193], v160 offset:32768
	ds_read_b128 v[194:197], v160 offset:33792
	ds_read_b128 v[198:201], v160 offset:34816
	ds_read_b128 v[202:205], v160 offset:35840
	ds_read_b128 v[206:209], v160 offset:36864
	ds_read_b128 v[218:221], v160 offset:37888
	ds_read_b128 v[226:229], v160 offset:38912
	ds_read_b128 v[230:233], v160 offset:39936
	global_load_lds_dwordx4 v[238:239], off
	v_lshl_add_u64 v[238:239], s[42:43], 0, v[136:137]
	s_mov_b32 m0, s46
	s_nop 0
	global_load_lds_dwordx4 v[238:239], off
	s_waitcnt vmcnt(8)
	s_waitcnt lgkmcnt(0)
	s_barrier
	s_waitcnt lgkmcnt(0)
	v_mfma_f32_16x16x32_bf16 v[128:131], v[148:151], v[190:193], v[128:131]
	v_mfma_f32_16x16x32_bf16 v[124:127], v[166:169], v[190:193], v[124:127]
	v_mfma_f32_16x16x32_bf16 v[112:115], v[148:151], v[198:201], v[112:115]
	v_mfma_f32_16x16x32_bf16 v[108:111], v[166:169], v[198:201], v[108:111]
	v_mfma_f32_16x16x32_bf16 v[96:99], v[148:151], v[206:209], v[96:99]
	v_mfma_f32_16x16x32_bf16 v[92:95], v[166:169], v[206:209], v[92:95]
	v_mfma_f32_16x16x32_bf16 v[80:83], v[148:151], v[226:229], v[80:83]
	v_mfma_f32_16x16x32_bf16 v[76:79], v[166:169], v[226:229], v[76:79]
	v_mfma_f32_16x16x32_bf16 v[128:131], v[162:165], v[194:197], v[128:131]
	v_mfma_f32_16x16x32_bf16 v[124:127], v[170:173], v[194:197], v[124:127]
	v_mfma_f32_16x16x32_bf16 v[112:115], v[162:165], v[202:205], v[112:115]
	v_mfma_f32_16x16x32_bf16 v[108:111], v[170:173], v[202:205], v[108:111]
	v_mfma_f32_16x16x32_bf16 v[96:99], v[162:165], v[218:221], v[96:99]
	v_mfma_f32_16x16x32_bf16 v[92:95], v[170:173], v[218:221], v[92:95]
	v_mfma_f32_16x16x32_bf16 v[80:83], v[162:165], v[230:233], v[80:83]
	v_mfma_f32_16x16x32_bf16 v[76:79], v[170:173], v[230:233], v[76:79]
	v_mfma_f32_16x16x32_bf16 v[120:123], v[174:177], v[190:193], v[120:123]
	v_mfma_f32_16x16x32_bf16 v[116:119], v[182:185], v[190:193], v[116:119]
	v_mfma_f32_16x16x32_bf16 v[104:107], v[174:177], v[198:201], v[104:107]
	v_mfma_f32_16x16x32_bf16 v[100:103], v[182:185], v[198:201], v[100:103]
	v_mfma_f32_16x16x32_bf16 v[88:91], v[174:177], v[206:209], v[88:91]
	v_mfma_f32_16x16x32_bf16 v[84:87], v[182:185], v[206:209], v[84:87]
	v_mfma_f32_16x16x32_bf16 v[72:75], v[174:177], v[226:229], v[72:75]
	v_mfma_f32_16x16x32_bf16 v[68:71], v[182:185], v[226:229], v[68:71]
	v_mfma_f32_16x16x32_bf16 v[120:123], v[178:181], v[194:197], v[120:123]
	v_mfma_f32_16x16x32_bf16 v[116:119], v[186:189], v[194:197], v[116:119]
	v_mfma_f32_16x16x32_bf16 v[104:107], v[178:181], v[202:205], v[104:107]
	v_mfma_f32_16x16x32_bf16 v[100:103], v[186:189], v[202:205], v[100:103]
	v_mfma_f32_16x16x32_bf16 v[88:91], v[178:181], v[218:221], v[88:91]
	v_mfma_f32_16x16x32_bf16 v[84:87], v[186:189], v[218:221], v[84:87]
	v_mfma_f32_16x16x32_bf16 v[72:75], v[178:181], v[230:233], v[72:75]
	v_mfma_f32_16x16x32_bf16 v[68:71], v[186:189], v[230:233], v[68:71]
	s_barrier
	s_add_i32 s42, s72, s33
	v_lshl_add_u64 v[152:153], v[152:153], 0, s[12:13]
	s_mov_b32 m0, s42
	ds_read_b128 v[190:193], v160 offset:49152
	ds_read_b128 v[194:197], v160 offset:50176
	ds_read_b128 v[198:201], v160 offset:51200
	ds_read_b128 v[202:205], v160 offset:52224
	ds_read_b128 v[206:209], v160 offset:53248
	ds_read_b128 v[218:221], v160 offset:54272
	ds_read_b128 v[226:229], v160 offset:55296
	ds_read_b128 v[230:233], v160 offset:56320
	global_load_lds_dwordx4 v[152:153], off
	s_add_i32 m0, s42, 0x2000
	s_add_u32 s40, s40, 0x40080
	v_lshl_add_u64 v[152:153], v[210:211], 0, s[12:13]
	s_addc_u32 s41, s41, 0
	s_add_i32 s42, s73, s33
	global_load_lds_dwordx4 v[152:153], off
	v_lshl_add_u64 v[152:153], s[40:41], 0, v[134:135]
	s_mov_b32 m0, s42
	s_nop 0
	global_load_lds_dwordx4 v[152:153], off
	v_lshl_add_u64 v[152:153], s[40:41], 0, v[138:139]
	s_add_i32 m0, s42, 0x2000
	s_nop 0
	global_load_lds_dwordx4 v[152:153], off
	v_lshl_add_u64 v[152:153], v[234:235], 0, s[12:13]
	s_mov_b32 m0, s48
	s_nop 0
	global_load_lds_dwordx4 v[152:153], off
	v_lshl_add_u64 v[152:153], v[236:237], 0, s[12:13]
	s_mov_b32 m0, s49
	s_nop 0
	global_load_lds_dwordx4 v[152:153], off
	s_waitcnt vmcnt(8)
	s_waitcnt lgkmcnt(0)
	s_barrier
	s_waitcnt lgkmcnt(0)
	v_mfma_f32_16x16x32_bf16 v[64:67], v[148:151], v[190:193], v[64:67]
	v_mfma_f32_16x16x32_bf16 v[60:63], v[166:169], v[190:193], v[60:63]
	v_mfma_f32_16x16x32_bf16 v[48:51], v[148:151], v[198:201], v[48:51]
	v_mfma_f32_16x16x32_bf16 v[44:47], v[166:169], v[198:201], v[44:47]
	v_mfma_f32_16x16x32_bf16 v[32:35], v[148:151], v[206:209], v[32:35]
	v_mfma_f32_16x16x32_bf16 v[28:31], v[166:169], v[206:209], v[28:31]
	v_mfma_f32_16x16x32_bf16 v[16:19], v[148:151], v[226:229], v[16:19]
	v_mfma_f32_16x16x32_bf16 v[12:15], v[166:169], v[226:229], v[12:15]
	v_mfma_f32_16x16x32_bf16 v[64:67], v[162:165], v[194:197], v[64:67]
	v_mfma_f32_16x16x32_bf16 v[60:63], v[170:173], v[194:197], v[60:63]
	v_mfma_f32_16x16x32_bf16 v[48:51], v[162:165], v[202:205], v[48:51]
	v_mfma_f32_16x16x32_bf16 v[44:47], v[170:173], v[202:205], v[44:47]
	v_mfma_f32_16x16x32_bf16 v[32:35], v[162:165], v[218:221], v[32:35]
	v_mfma_f32_16x16x32_bf16 v[28:31], v[170:173], v[218:221], v[28:31]
	v_mfma_f32_16x16x32_bf16 v[16:19], v[162:165], v[230:233], v[16:19]
	v_mfma_f32_16x16x32_bf16 v[12:15], v[170:173], v[230:233], v[12:15]
	v_mfma_f32_16x16x32_bf16 v[56:59], v[174:177], v[190:193], v[56:59]
	v_mfma_f32_16x16x32_bf16 v[52:55], v[182:185], v[190:193], v[52:55]
	v_mfma_f32_16x16x32_bf16 v[40:43], v[174:177], v[198:201], v[40:43]
	v_mfma_f32_16x16x32_bf16 v[36:39], v[182:185], v[198:201], v[36:39]
	v_mfma_f32_16x16x32_bf16 v[24:27], v[174:177], v[206:209], v[24:27]
	v_mfma_f32_16x16x32_bf16 v[20:23], v[182:185], v[206:209], v[20:23]
	v_mfma_f32_16x16x32_bf16 v[8:11], v[174:177], v[226:229], v[8:11]
	v_mfma_f32_16x16x32_bf16 v[4:7], v[182:185], v[226:229], v[4:7]
	v_mfma_f32_16x16x32_bf16 v[56:59], v[178:181], v[194:197], v[56:59]
	v_mfma_f32_16x16x32_bf16 v[52:55], v[186:189], v[194:197], v[52:55]
	v_mfma_f32_16x16x32_bf16 v[40:43], v[178:181], v[202:205], v[40:43]
	v_mfma_f32_16x16x32_bf16 v[36:39], v[186:189], v[202:205], v[36:39]
	v_mfma_f32_16x16x32_bf16 v[24:27], v[178:181], v[218:221], v[24:27]
	v_mfma_f32_16x16x32_bf16 v[20:23], v[186:189], v[218:221], v[20:23]
	v_mfma_f32_16x16x32_bf16 v[8:11], v[178:181], v[230:233], v[8:11]
	v_mfma_f32_16x16x32_bf16 v[4:7], v[186:189], v[230:233], v[4:7]
	s_barrier
	s_add_i32 s71, s71, 2
	s_add_u32 s38, s38, 0x100
	s_addc_u32 s39, s39, 0
	s_add_u32 s69, s69, 0x100
	s_addc_u32 s70, s70, 0
	s_cmp_gt_u32 s71, 13
	s_cbranch_scc0 .LBB0_820
	s_and_b64 vcc, exec, s[16:17]
	s_cbranch_vccz .LBB0_823
	s_barrier

.LBB0_827:
	v_readlane_b32 s0, v244, 3
	v_readlane_b32 s1, v244, 4
	s_cmp_gt_i32 s1, 5
	s_cselect_b64 s[0:1], -1, 0
	s_and_b64 s[4:5], s[4:5], s[0:1]
	s_andn2_b64 vcc, exec, s[4:5]
	s_cbranch_vccnz .LBB0_881
	s_setprio 0
	s_waitcnt vmcnt(0)
	s_waitcnt vmcnt(0) lgkmcnt(0)
	s_barrier
	s_getreg_b32 s3, hwreg(HW_REG_HW_ID, 0, 6)
	s_and_b32 s3, s3, 63
	s_lshl_b32 s3, s3, 2
	s_add_i32 s3, s3, 0
	s_mov_b64 s[4:5], src_shared_base
	s_add_i32 s3, s3, 0x23e00
	v_mov_b32_e32 v4, s3
	v_mov_b32_e32 v5, s5
	flat_load_dword v3, v[4:5] sc0 sc1
	s_waitcnt vmcnt(0) lgkmcnt(0)
	v_readfirstlane_b32 s3, v3
	s_cmp_lg_u32 s3, 1
	s_cbranch_scc1 .Learlyinv_skip4
	buffer_inv sc1
	s_waitcnt vmcnt(0)

.LBB0_920:
	v_ashrrev_i32_e32 v6, 31, v4
	v_lshrrev_b32_e32 v6, 26, v6
	v_lshlrev_b32_e32 v5, 4, v4
	v_add_u32_e32 v6, v4, v6
	v_bfe_i32 v4, v4, 27, 1
	v_lshrrev_b32_e32 v4, 22, v4
	v_add_u32_e32 v4, v5, v4
	v_and_b32_e32 v4, 0xfffffc00, v4
	v_sub_u32_e32 v4, v5, v4
	v_lshrrev_b32_e32 v7, 4, v4
	v_bitop3_b32 v4, v7, v4, 32 bitop3:0x6c
	v_ashrrev_i32_e32 v8, 31, v4
	v_ashrrev_i32_e32 v6, 6, v6
	v_lshrrev_b32_e32 v8, 26, v8
	v_lshlrev_b32_e32 v7, 3, v6
	v_add_u32_e32 v8, v4, v8
	v_and_b32_e32 v7, -16, v7
	v_ashrrev_i32_e32 v9, 6, v8
	v_lshlrev_b32_e32 v6, 5, v6
	v_add_u32_e32 v7, v9, v7
	v_and_b32_e32 v16, 32, v6
	v_and_b32_e32 v6, 0xc0, v8
	s_ashr_i32 s4, s1, 3
	v_sub_u32_e32 v4, v4, v6
	v_mov_b32_e32 v6, 1
	v_lshlrev_b32_e32 v8, 1, v7
	v_lshrrev_b32_e32 v10, 2, v7
	v_and_b32_e32 v9, 3, v9
	s_mov_b32 s1, 0x7fffffe0
	v_ashrrev_i16_sdwa v4, v6, sext(v4) dst_sel:DWORD dst_unused:UNUSED_PAD src0_sel:DWORD src1_sel:BYTE_0
	v_and_b32_e32 v8, 24, v8
	v_and_b32_e32 v10, 4, v10
	v_and_or_b32 v9, v7, s1, v9
	v_bfe_i32 v17, v4, 0, 16
	v_or3_b32 v8, v9, v10, v8
	v_add_u32_e32 v4, v16, v17
	v_mul_lo_u32 v18, v7, s0
	v_mul_lo_u32 v7, v8, s0
	v_add_lshl_u32 v100, v4, v18, 1
	v_add_lshl_u32 v102, v7, v4, 1
	v_add_u32_e32 v4, 0x2000, v5
	v_ashrrev_i32_e32 v5, 31, v4
	v_lshrrev_b32_e32 v5, 22, v5
	v_add_u32_e32 v5, v4, v5
	v_ashrrev_i32_e32 v5, 10, v5
	v_mul_i32_i24_e32 v7, 0x400, v5
	v_sub_u32_e32 v4, v4, v7
	v_lshrrev_b32_e32 v7, 4, v4
	v_bitop3_b32 v4, v7, v4, 32 bitop3:0x6c
	v_ashrrev_i32_e32 v8, 31, v4
	v_lshrrev_b32_e32 v8, 26, v8
	v_lshlrev_b32_e32 v7, 3, v5
	v_add_u32_e32 v8, v4, v8
	v_and_b32_e32 v7, -16, v7
	v_ashrrev_i32_e32 v9, 6, v8
	v_lshlrev_b32_e32 v5, 5, v5
	v_add_u32_e32 v7, v9, v7
	v_and_b32_e32 v19, 32, v5
	v_and_b32_e32 v5, 0xc0, v8
	v_and_b32_e32 v8, 3, v9
	s_ashr_i32 s13, s3, 6
	v_and_or_b32 v8, v7, s1, v8
	s_ashr_i32 s1, s0, 31
	s_ashr_i32 s33, s3, 8
	s_lshl_b64 s[16:17], s[0:1], 8
	s_lshl_b64 s[18:19], s[0:1], 9
	s_lshl_b32 s38, s13, 10
	s_add_u32 s39, s82, 0x6400000
	s_addc_u32 s40, s83, 0
	s_add_i32 s4, s6, s4
	s_ashr_i32 s5, s4, 31
	s_lshr_b32 s5, s5, 27
	s_add_i32 s5, s4, s5
	s_ashr_i32 s6, s5, 5
	s_andn2_b32 s5, s5, 31
	s_sub_i32 s5, s4, s5
	s_bfe_i32 s4, s5, 0x80000
	s_bfe_u32 s4, s4, 0x3000c
	s_add_i32 s7, s5, s4
	s_bfe_i32 s4, s7, 0x80000
	s_and_b32 s7, s7, 0xf8
	s_sub_i32 s5, s5, s7
	s_lshl_b32 s6, s6, 3
	s_sext_i32_i8 s5, s5
	s_add_i32 s36, s6, s5
	s_ashr_i32 s5, s36, 31
	s_mul_i32 s5, s18, s5
	s_mul_hi_u32 s6, s18, s36
	s_add_i32 s5, s6, s5
	s_lshr_b64 s[6:7], s[0:1], 23
	s_sext_i32_i16 s12, s4
	s_mul_i32 s7, s6, s36
	s_lshr_b32 s4, s12, 3
	s_add_i32 s5, s5, s7
	s_bfe_i64 s[20:21], s[4:5], 0x100000
	s_ashr_i32 s7, s12, 3
	s_mul_hi_u32 s12, s18, s7
	s_mul_i32 s20, s18, s21
	s_add_i32 s12, s12, s20
	s_mul_i32 s6, s6, s7
	v_sub_u32_e32 v4, v4, v5
	s_add_i32 s12, s12, s6
	s_mul_i32 s6, s18, s7
	v_ashrrev_i16_sdwa v4, v6, sext(v4) dst_sel:DWORD dst_unused:UNUSED_PAD src0_sel:DWORD src1_sel:BYTE_0
	v_lshlrev_b32_e32 v5, 1, v7
	v_lshrrev_b32_e32 v6, 2, v7
	s_add_u32 s20, s10, s6
	v_and_b32_e32 v5, 24, v5
	v_and_b32_e32 v6, 4, v6
	s_addc_u32 s21, s11, s12
	s_add_i32 s42, s38, 0
	v_bfe_i32 v20, v4, 0, 16
	v_or3_b32 v5, v8, v6, v5
	s_add_i32 m0, s42, 0x10000
	v_add_u32_e32 v4, v19, v20
	v_mul_lo_u32 v5, v5, s0
	global_load_lds_dwordx4 v102, s[20:21]
	s_add_i32 m0, s42, 0x12000
	v_add_lshl_u32 v114, v5, v4, 1
	s_add_u32 s6, s20, s16
	global_load_lds_dwordx4 v114, s[20:21]
	s_addc_u32 s7, s21, s17
	s_add_i32 m0, s42, 0x14000
	s_mul_i32 s22, s18, s36
	global_load_lds_dwordx4 v102, s[6:7]
	s_add_i32 m0, s42, 0x16000
	s_add_u32 s22, s39, s22
	s_addc_u32 s23, s40, s5
	s_add_i32 s43, s42, 0x2000
	v_mul_lo_u32 v21, v7, s0
	global_load_lds_dwordx4 v114, s[6:7]
	s_mov_b32 m0, s42
	s_add_u32 s24, s22, s16
	v_add_lshl_u32 v112, v4, v21, 1
	global_load_lds_dwordx4 v100, s[22:23]
	s_mov_b32 m0, s43
	s_addc_u32 s25, s23, s17
	s_add_i32 s44, s42, 0x4000
	global_load_lds_dwordx4 v112, s[22:23]
	s_mov_b32 m0, s44
	s_add_i32 s45, s42, 0x6000
	global_load_lds_dwordx4 v100, s[24:25]
	s_mov_b32 m0, s45
	v_mov_b32_e32 v92, 0
	global_load_lds_dwordx4 v112, s[24:25]
	v_mov_b32_e32 v103, v92
	v_mov_b32_e32 v115, v92
	v_mov_b32_e32 v101, v92
	v_mov_b32_e32 v113, v92
	v_lshl_add_u64 v[14:15], s[20:21], 0, v[102:103]
	v_lshl_add_u64 v[10:11], s[20:21], 0, v[114:115]
	v_lshl_add_u64 v[6:7], s[6:7], 0, v[102:103]
	v_lshl_add_u64 v[4:5], s[6:7], 0, v[114:115]
	v_lshl_add_u64 v[12:13], s[22:23], 0, v[100:101]
	s_cmp_lg_u32 s33, 1
	v_lshl_add_u64 v[8:9], s[22:23], 0, v[112:113]
	s_cbranch_scc1 .LBB0_922
	s_barrier
	s_setprio 1

.LBB0_936:
	v_add_u32_e32 v93, s51, v152
	ds_read_b128 v[154:157], v93
	ds_read_b128 v[158:161], v93 offset:1024
	ds_read_b128 v[166:169], v93 offset:2048
	ds_read_b128 v[170:173], v93 offset:3072
	v_add_u32_e32 v93, s58, v152
	ds_read_b128 v[174:177], v93
	ds_read_b128 v[178:181], v93 offset:1024
	ds_read_b128 v[182:185], v93 offset:2048
	ds_read_b128 v[186:189], v93 offset:3072
	s_add_i32 s67, s34, 2
	s_add_u32 s68, s30, 0x80
	s_addc_u32 s35, s31, 0
	s_cmp_eq_u32 s50, s34
	s_cselect_b32 s34, s6, s68
	s_cselect_b32 s35, s7, s35
	s_cselect_b32 s69, s29, s66
	s_cselect_b32 s68, s28, s65
	v_lshl_add_u64 v[94:95], s[30:31], 0, v[120:121]
	s_add_i32 m0, s42, 0xc000
	ds_read_b128 v[190:193], v153
	ds_read_b128 v[194:197], v153 offset:1024
	ds_read_b128 v[198:201], v153 offset:2048
	ds_read_b128 v[202:205], v153 offset:3072
	ds_read_b128 v[206:209], v153 offset:4096
	ds_read_b128 v[218:221], v153 offset:5120
	ds_read_b128 v[226:229], v153 offset:6144
	ds_read_b128 v[230:233], v153 offset:7168
	global_load_lds_dwordx4 v[94:95], off
	v_lshl_add_u64 v[94:95], s[30:31], 0, v[122:123]
	s_add_i32 m0, s42, 0xe000
	s_nop 0
	global_load_lds_dwordx4 v[94:95], off
	s_waitcnt vmcnt(8)
	s_waitcnt lgkmcnt(0)
	s_barrier
	s_waitcnt lgkmcnt(0)
	v_mfma_f32_16x16x32_bf16 v[148:151], v[154:157], v[190:193], v[148:151]
	v_mfma_f32_16x16x32_bf16 v[144:147], v[166:169], v[190:193], v[144:147]
	v_mfma_f32_16x16x32_bf16 v[128:131], v[154:157], v[198:201], v[128:131]
	v_mfma_f32_16x16x32_bf16 v[124:127], v[166:169], v[198:201], v[124:127]
	v_mfma_f32_16x16x32_bf16 v[104:107], v[154:157], v[206:209], v[104:107]
	v_mfma_f32_16x16x32_bf16 v[94:97], v[166:169], v[206:209], v[96:99]
	v_mfma_f32_16x16x32_bf16 v[80:83], v[154:157], v[226:229], v[80:83]
	v_mfma_f32_16x16x32_bf16 v[76:79], v[166:169], v[226:229], v[76:79]
	v_mfma_f32_16x16x32_bf16 v[148:151], v[158:161], v[194:197], v[148:151]
	v_mfma_f32_16x16x32_bf16 v[144:147], v[170:173], v[194:197], v[144:147]
	v_mfma_f32_16x16x32_bf16 v[128:131], v[158:161], v[202:205], v[128:131]
	v_mfma_f32_16x16x32_bf16 v[124:127], v[170:173], v[202:205], v[124:127]
	v_mfma_f32_16x16x32_bf16 v[104:107], v[158:161], v[218:221], v[104:107]
	v_mfma_f32_16x16x32_bf16 v[94:97], v[170:173], v[218:221], v[94:97]
	v_mfma_f32_16x16x32_bf16 v[80:83], v[158:161], v[230:233], v[80:83]
	v_mfma_f32_16x16x32_bf16 v[76:79], v[170:173], v[230:233], v[76:79]
	v_mfma_f32_16x16x32_bf16 v[140:143], v[174:177], v[190:193], v[140:143]
	v_mfma_f32_16x16x32_bf16 v[136:139], v[182:185], v[190:193], v[136:139]
	v_mfma_f32_16x16x32_bf16 v[116:119], v[174:177], v[198:201], v[116:119]
	v_mfma_f32_16x16x32_bf16 v[108:111], v[182:185], v[198:201], v[108:111]
	v_mfma_f32_16x16x32_bf16 v[88:91], v[174:177], v[206:209], v[88:91]
	v_mfma_f32_16x16x32_bf16 v[84:87], v[182:185], v[206:209], v[84:87]
	v_mfma_f32_16x16x32_bf16 v[72:75], v[174:177], v[226:229], v[72:75]
	v_mfma_f32_16x16x32_bf16 v[68:71], v[182:185], v[226:229], v[68:71]
	v_mfma_f32_16x16x32_bf16 v[140:143], v[178:181], v[194:197], v[140:143]
	v_mfma_f32_16x16x32_bf16 v[136:139], v[186:189], v[194:197], v[136:139]
	v_mfma_f32_16x16x32_bf16 v[116:119], v[178:181], v[202:205], v[116:119]
	v_mfma_f32_16x16x32_bf16 v[108:111], v[186:189], v[202:205], v[108:111]
	v_mfma_f32_16x16x32_bf16 v[88:91], v[178:181], v[218:221], v[88:91]
	v_mfma_f32_16x16x32_bf16 v[84:87], v[186:189], v[218:221], v[84:87]
	v_mfma_f32_16x16x32_bf16 v[72:75], v[178:181], v[230:233], v[72:75]
	v_mfma_f32_16x16x32_bf16 v[68:71], v[186:189], v[230:233], v[68:71]
	s_barrier
	s_add_i32 s70, s51, s38
	v_lshl_add_u64 v[162:163], s[68:69], 0, v[102:103]
	s_mov_b32 m0, s70
	ds_read_b128 v[190:193], v153 offset:16384
	ds_read_b128 v[194:197], v153 offset:17408
	ds_read_b128 v[198:201], v153 offset:18432
	ds_read_b128 v[202:205], v153 offset:19456
	ds_read_b128 v[206:209], v153 offset:20480
	ds_read_b128 v[218:221], v153 offset:21504
	ds_read_b128 v[226:229], v153 offset:22528
	ds_read_b128 v[230:233], v153 offset:23552
	global_load_lds_dwordx4 v[162:163], off
	s_add_i32 m0, s70, 0x2000
	v_lshl_add_u64 v[210:211], s[68:69], 0, v[114:115]
	s_add_u32 s68, s68, s16
	s_addc_u32 s69, s69, s17
	s_add_i32 s70, s58, s38
	global_load_lds_dwordx4 v[210:211], off
	v_lshl_add_u64 v[234:235], s[68:69], 0, v[102:103]
	s_mov_b32 m0, s70
	v_lshl_add_u64 v[236:237], s[68:69], 0, v[114:115]
	global_load_lds_dwordx4 v[234:235], off
	s_add_i32 m0, s70, 0x2000
	v_lshl_add_u64 v[238:239], s[34:35], 0, v[100:101]
	global_load_lds_dwordx4 v[236:237], off
	s_mov_b32 m0, s42
	v_lshl_add_u64 v[240:241], s[34:35], 0, v[112:113]
	global_load_lds_dwordx4 v[238:239], off
	s_mov_b32 m0, s43
	s_nop 0
	global_load_lds_dwordx4 v[240:241], off
	s_waitcnt vmcnt(8)
	s_waitcnt lgkmcnt(0)
	s_barrier
	s_waitcnt lgkmcnt(0)
	v_mfma_f32_16x16x32_bf16 v[64:67], v[154:157], v[190:193], v[64:67]
	v_mfma_f32_16x16x32_bf16 v[60:63], v[166:169], v[190:193], v[60:63]
	v_mfma_f32_16x16x32_bf16 v[48:51], v[154:157], v[198:201], v[48:51]
	v_mfma_f32_16x16x32_bf16 v[44:47], v[166:169], v[198:201], v[44:47]
	v_mfma_f32_16x16x32_bf16 v[32:35], v[154:157], v[206:209], v[32:35]
	v_mfma_f32_16x16x32_bf16 v[28:31], v[166:169], v[206:209], v[28:31]
	v_mfma_f32_16x16x32_bf16 v[16:19], v[154:157], v[226:229], v[16:19]
	v_mfma_f32_16x16x32_bf16 v[12:15], v[166:169], v[226:229], v[12:15]
	v_mfma_f32_16x16x32_bf16 v[64:67], v[158:161], v[194:197], v[64:67]
	v_mfma_f32_16x16x32_bf16 v[60:63], v[170:173], v[194:197], v[60:63]
	v_mfma_f32_16x16x32_bf16 v[48:51], v[158:161], v[202:205], v[48:51]
	v_mfma_f32_16x16x32_bf16 v[44:47], v[170:173], v[202:205], v[44:47]
	v_mfma_f32_16x16x32_bf16 v[32:35], v[158:161], v[218:221], v[32:35]
	v_mfma_f32_16x16x32_bf16 v[28:31], v[170:173], v[218:221], v[28:31]
	v_mfma_f32_16x16x32_bf16 v[16:19], v[158:161], v[230:233], v[16:19]
	v_mfma_f32_16x16x32_bf16 v[12:15], v[170:173], v[230:233], v[12:15]
	v_mfma_f32_16x16x32_bf16 v[56:59], v[174:177], v[190:193], v[56:59]
	v_mfma_f32_16x16x32_bf16 v[52:55], v[182:185], v[190:193], v[52:55]
	v_mfma_f32_16x16x32_bf16 v[40:43], v[174:177], v[198:201], v[40:43]
	v_mfma_f32_16x16x32_bf16 v[36:39], v[182:185], v[198:201], v[36:39]
	v_mfma_f32_16x16x32_bf16 v[24:27], v[174:177], v[206:209], v[24:27]
	v_mfma_f32_16x16x32_bf16 v[20:23], v[182:185], v[206:209], v[20:23]
	v_mfma_f32_16x16x32_bf16 v[8:11], v[174:177], v[226:229], v[8:11]
	v_mfma_f32_16x16x32_bf16 v[4:7], v[182:185], v[226:229], v[4:7]
	v_mfma_f32_16x16x32_bf16 v[56:59], v[178:181], v[194:197], v[56:59]
	v_mfma_f32_16x16x32_bf16 v[52:55], v[186:189], v[194:197], v[52:55]
	v_mfma_f32_16x16x32_bf16 v[40:43], v[178:181], v[202:205], v[40:43]
	v_mfma_f32_16x16x32_bf16 v[36:39], v[186:189], v[202:205], v[36:39]
	v_mfma_f32_16x16x32_bf16 v[24:27], v[178:181], v[218:221], v[24:27]
	v_mfma_f32_16x16x32_bf16 v[20:23], v[186:189], v[218:221], v[20:23]
	v_mfma_f32_16x16x32_bf16 v[8:11], v[178:181], v[230:233], v[8:11]
	v_mfma_f32_16x16x32_bf16 v[4:7], v[186:189], v[230:233], v[4:7]
	s_barrier
	s_add_i32 s68, 0, 0x18000
	v_add_u32_e32 v93, s68, v152
	s_add_i32 s69, 0, 0x1c000
	ds_read_b128 v[154:157], v93
	ds_read_b128 v[158:161], v93 offset:1024
	ds_read_b128 v[166:169], v93 offset:2048
	ds_read_b128 v[170:173], v93 offset:3072
	v_add_u32_e32 v93, s69, v152
	ds_read_b128 v[174:177], v93
	ds_read_b128 v[178:181], v93 offset:1024
	ds_read_b128 v[182:185], v93 offset:2048
	ds_read_b128 v[186:189], v93 offset:3072
	s_add_u32 s34, s34, s16
	s_addc_u32 s35, s35, s17
	s_mov_b32 m0, s44
	v_lshl_add_u64 v[98:99], s[34:35], 0, v[100:101]
	ds_read_b128 v[190:193], v153 offset:32768
	ds_read_b128 v[194:197], v153 offset:33792
	ds_read_b128 v[198:201], v153 offset:34816
	ds_read_b128 v[202:205], v153 offset:35840
	ds_read_b128 v[206:209], v153 offset:36864
	ds_read_b128 v[218:221], v153 offset:37888
	ds_read_b128 v[226:229], v153 offset:38912
	ds_read_b128 v[230:233], v153 offset:39936
	global_load_lds_dwordx4 v[98:99], off
	v_lshl_add_u64 v[98:99], s[34:35], 0, v[112:113]
	s_mov_b32 m0, s45
	s_nop 0
	global_load_lds_dwordx4 v[98:99], off
	s_waitcnt vmcnt(8)
	s_waitcnt lgkmcnt(0)
	s_barrier
	s_waitcnt lgkmcnt(0)
	v_mfma_f32_16x16x32_bf16 v[148:151], v[154:157], v[190:193], v[148:151]
	v_mfma_f32_16x16x32_bf16 v[144:147], v[166:169], v[190:193], v[144:147]
	v_mfma_f32_16x16x32_bf16 v[128:131], v[154:157], v[198:201], v[128:131]
	v_mfma_f32_16x16x32_bf16 v[124:127], v[166:169], v[198:201], v[124:127]
	v_mfma_f32_16x16x32_bf16 v[104:107], v[154:157], v[206:209], v[104:107]
	v_mfma_f32_16x16x32_bf16 v[94:97], v[166:169], v[206:209], v[94:97]
	v_mfma_f32_16x16x32_bf16 v[80:83], v[154:157], v[226:229], v[80:83]
	v_mfma_f32_16x16x32_bf16 v[76:79], v[166:169], v[226:229], v[76:79]
	v_mfma_f32_16x16x32_bf16 v[148:151], v[158:161], v[194:197], v[148:151]
	v_mfma_f32_16x16x32_bf16 v[144:147], v[170:173], v[194:197], v[144:147]
	v_mfma_f32_16x16x32_bf16 v[128:131], v[158:161], v[202:205], v[128:131]
	v_mfma_f32_16x16x32_bf16 v[124:127], v[170:173], v[202:205], v[124:127]
	v_mfma_f32_16x16x32_bf16 v[104:107], v[158:161], v[218:221], v[104:107]
	v_mfma_f32_16x16x32_bf16 v[96:99], v[170:173], v[218:221], v[94:97]
	v_mfma_f32_16x16x32_bf16 v[80:83], v[158:161], v[230:233], v[80:83]
	v_mfma_f32_16x16x32_bf16 v[76:79], v[170:173], v[230:233], v[76:79]
	v_mfma_f32_16x16x32_bf16 v[140:143], v[174:177], v[190:193], v[140:143]
	v_mfma_f32_16x16x32_bf16 v[136:139], v[182:185], v[190:193], v[136:139]
	v_mfma_f32_16x16x32_bf16 v[116:119], v[174:177], v[198:201], v[116:119]
	v_mfma_f32_16x16x32_bf16 v[108:111], v[182:185], v[198:201], v[108:111]
	v_mfma_f32_16x16x32_bf16 v[88:91], v[174:177], v[206:209], v[88:91]
	v_mfma_f32_16x16x32_bf16 v[84:87], v[182:185], v[206:209], v[84:87]
	v_mfma_f32_16x16x32_bf16 v[72:75], v[174:177], v[226:229], v[72:75]
	v_mfma_f32_16x16x32_bf16 v[68:71], v[182:185], v[226:229], v[68:71]
	v_mfma_f32_16x16x32_bf16 v[140:143], v[178:181], v[194:197], v[140:143]
	v_mfma_f32_16x16x32_bf16 v[136:139], v[186:189], v[194:197], v[136:139]
	v_mfma_f32_16x16x32_bf16 v[116:119], v[178:181], v[202:205], v[116:119]
	v_mfma_f32_16x16x32_bf16 v[108:111], v[186:189], v[202:205], v[108:111]
	v_mfma_f32_16x16x32_bf16 v[88:91], v[178:181], v[218:221], v[88:91]
	v_mfma_f32_16x16x32_bf16 v[84:87], v[186:189], v[218:221], v[84:87]
	v_mfma_f32_16x16x32_bf16 v[72:75], v[178:181], v[230:233], v[72:75]
	v_mfma_f32_16x16x32_bf16 v[68:71], v[186:189], v[230:233], v[68:71]
	s_barrier
	s_add_i32 s34, s68, s38
	v_lshl_add_u64 v[94:95], v[162:163], 0, s[24:25]
	s_mov_b32 m0, s34
	ds_read_b128 v[190:193], v153 offset:49152
	ds_read_b128 v[194:197], v153 offset:50176
	ds_read_b128 v[198:201], v153 offset:51200
	ds_read_b128 v[202:205], v153 offset:52224
	ds_read_b128 v[206:209], v153 offset:53248
	ds_read_b128 v[218:221], v153 offset:54272
	ds_read_b128 v[226:229], v153 offset:55296
	ds_read_b128 v[230:233], v153 offset:56320
	global_load_lds_dwordx4 v[94:95], off
	v_lshl_add_u64 v[94:95], v[210:211], 0, s[24:25]
	s_add_i32 m0, s34, 0x2000
	s_add_i32 s34, s69, s38
	global_load_lds_dwordx4 v[94:95], off
	v_lshl_add_u64 v[94:95], v[234:235], 0, s[24:25]
	s_mov_b32 m0, s34
	s_nop 0
	global_load_lds_dwordx4 v[94:95], off
	v_lshl_add_u64 v[94:95], v[236:237], 0, s[24:25]
	s_add_i32 m0, s34, 0x2000
	s_nop 0
	global_load_lds_dwordx4 v[94:95], off
	v_lshl_add_u64 v[94:95], v[238:239], 0, s[24:25]
	s_mov_b32 m0, s46
	s_nop 0
	global_load_lds_dwordx4 v[94:95], off
	v_lshl_add_u64 v[94:95], v[240:241], 0, s[24:25]
	s_mov_b32 m0, s47
	s_nop 0
	global_load_lds_dwordx4 v[94:95], off
	s_waitcnt vmcnt(8)
	s_waitcnt lgkmcnt(0)
	s_barrier
	s_waitcnt lgkmcnt(0)
	v_mfma_f32_16x16x32_bf16 v[64:67], v[154:157], v[190:193], v[64:67]
	v_mfma_f32_16x16x32_bf16 v[60:63], v[166:169], v[190:193], v[60:63]
	v_mfma_f32_16x16x32_bf16 v[48:51], v[154:157], v[198:201], v[48:51]
	v_mfma_f32_16x16x32_bf16 v[44:47], v[166:169], v[198:201], v[44:47]
	v_mfma_f32_16x16x32_bf16 v[32:35], v[154:157], v[206:209], v[32:35]
	v_mfma_f32_16x16x32_bf16 v[28:31], v[166:169], v[206:209], v[28:31]
	v_mfma_f32_16x16x32_bf16 v[16:19], v[154:157], v[226:229], v[16:19]
	v_mfma_f32_16x16x32_bf16 v[12:15], v[166:169], v[226:229], v[12:15]
	v_mfma_f32_16x16x32_bf16 v[64:67], v[158:161], v[194:197], v[64:67]
	v_mfma_f32_16x16x32_bf16 v[60:63], v[170:173], v[194:197], v[60:63]
	v_mfma_f32_16x16x32_bf16 v[48:51], v[158:161], v[202:205], v[48:51]
	v_mfma_f32_16x16x32_bf16 v[44:47], v[170:173], v[202:205], v[44:47]
	v_mfma_f32_16x16x32_bf16 v[32:35], v[158:161], v[218:221], v[32:35]
	v_mfma_f32_16x16x32_bf16 v[28:31], v[170:173], v[218:221], v[28:31]
	v_mfma_f32_16x16x32_bf16 v[16:19], v[158:161], v[230:233], v[16:19]
	v_mfma_f32_16x16x32_bf16 v[12:15], v[170:173], v[230:233], v[12:15]
	v_mfma_f32_16x16x32_bf16 v[56:59], v[174:177], v[190:193], v[56:59]
	v_mfma_f32_16x16x32_bf16 v[52:55], v[182:185], v[190:193], v[52:55]
	v_mfma_f32_16x16x32_bf16 v[40:43], v[174:177], v[198:201], v[40:43]
	v_mfma_f32_16x16x32_bf16 v[36:39], v[182:185], v[198:201], v[36:39]
	v_mfma_f32_16x16x32_bf16 v[24:27], v[174:177], v[206:209], v[24:27]
	v_mfma_f32_16x16x32_bf16 v[20:23], v[182:185], v[206:209], v[20:23]
	v_mfma_f32_16x16x32_bf16 v[8:11], v[174:177], v[226:229], v[8:11]
	v_mfma_f32_16x16x32_bf16 v[4:7], v[182:185], v[226:229], v[4:7]
	v_mfma_f32_16x16x32_bf16 v[56:59], v[178:181], v[194:197], v[56:59]
	v_mfma_f32_16x16x32_bf16 v[52:55], v[186:189], v[194:197], v[52:55]
	v_mfma_f32_16x16x32_bf16 v[40:43], v[178:181], v[202:205], v[40:43]
	v_mfma_f32_16x16x32_bf16 v[36:39], v[186:189], v[202:205], v[36:39]
	v_mfma_f32_16x16x32_bf16 v[24:27], v[178:181], v[218:221], v[24:27]
	v_mfma_f32_16x16x32_bf16 v[20:23], v[186:189], v[218:221], v[20:23]
	v_mfma_f32_16x16x32_bf16 v[8:11], v[178:181], v[230:233], v[8:11]
	v_mfma_f32_16x16x32_bf16 v[4:7], v[186:189], v[230:233], v[4:7]
	s_barrier
	s_add_u32 s30, s30, 0x100
	s_addc_u32 s31, s31, 0
	s_add_u32 s65, s65, 0x100
	s_addc_u32 s66, s66, 0
	s_cmp_ge_i32 s67, s49
	s_mov_b32 s34, s67
	s_cbranch_scc0 .LBB0_936

.LBB0_987:
	v_readlane_b32 s0, v244, 3
	v_readlane_b32 s1, v244, 4
	s_cmp_gt_i32 s1, 6
	s_cselect_b64 s[0:1], -1, 0
	s_and_b64 s[4:5], s[8:9], s[0:1]
	s_andn2_b64 vcc, exec, s[4:5]
	s_cbranch_vccnz .LBB0_1041
	s_setprio 0
	s_waitcnt vmcnt(0)
	s_waitcnt vmcnt(0) lgkmcnt(0)
	s_barrier
	s_getreg_b32 s3, hwreg(HW_REG_HW_ID, 0, 6)
	s_and_b32 s3, s3, 63
	s_lshl_b32 s3, s3, 2
	s_add_i32 s3, s3, 0
	s_mov_b64 s[4:5], src_shared_base
	s_add_i32 s3, s3, 0x23e00
	v_mov_b32_e32 v4, s3
	v_mov_b32_e32 v5, s5
	flat_load_dword v3, v[4:5] sc0 sc1
	s_waitcnt vmcnt(0) lgkmcnt(0)
	v_readfirstlane_b32 s3, v3
	s_cmp_lg_u32 s3, 1
	s_cbranch_scc1 .Learlyinv_skip5
	buffer_inv sc1
	s_waitcnt vmcnt(0)

.LBB0_1103:
	s_and_b64 vcc, exec, s[0:1]
	s_cbranch_vccnz .LBB0_1170
	v_ashrrev_i32_e32 v6, 31, v4
	v_lshrrev_b32_e32 v6, 26, v6
	v_lshlrev_b32_e32 v5, 4, v4
	v_add_u32_e32 v6, v4, v6
	v_bfe_i32 v4, v4, 27, 1
	v_lshrrev_b32_e32 v4, 22, v4
	v_add_u32_e32 v4, v5, v4
	v_and_b32_e32 v4, 0xfffffc00, v4
	v_sub_u32_e32 v4, v5, v4
	v_ashrrev_i32_e32 v12, 6, v6
	v_lshrrev_b32_e32 v6, 4, v4
	v_bitop3_b32 v4, v6, v4, 32 bitop3:0x6c
	v_ashrrev_i32_e32 v7, 31, v4
	v_lshrrev_b32_e32 v7, 26, v7
	v_add_u32_e32 v7, v4, v7
	v_lshlrev_b32_e32 v6, 3, v12
	v_ashrrev_i32_e32 v13, 6, v7
	v_and_b32_e32 v7, 0xc0, v7
	v_and_b32_e32 v6, -16, v6
	v_sub_u32_e32 v4, v4, v7
	v_mov_b32_e32 v7, 1
	v_add_u32_e32 v6, v13, v6
	v_ashrrev_i16_sdwa v4, v7, sext(v4) dst_sel:DWORD dst_unused:UNUSED_PAD src0_sel:DWORD src1_sel:BYTE_0
	v_lshlrev_b32_e32 v8, 5, v12
	v_bfe_i32 v14, v4, 0, 16
	v_lshlrev_b32_e32 v4, 1, v6
	v_lshrrev_b32_e32 v9, 2, v6
	v_and_b32_e32 v10, 3, v13
	s_mov_b32 s1, 0x1fffe0
	v_and_b32_e32 v8, 32, v8
	v_and_b32_e32 v4, 24, v4
	v_and_b32_e32 v9, 4, v9
	v_and_or_b32 v10, v6, s1, v10
	v_or3_b32 v4, v10, v9, v4
	v_add_lshl_u32 v8, v8, v14, 1
	v_lshl_add_u32 v134, v4, 11, v8
	v_add_u32_e32 v4, 0x2000, v5
	v_ashrrev_i32_e32 v5, 31, v4
	v_lshrrev_b32_e32 v5, 22, v5
	v_add_u32_e32 v5, v4, v5
	v_ashrrev_i32_e32 v15, 10, v5
	v_mul_i32_i24_e32 v5, 0x400, v15
	v_sub_u32_e32 v4, v4, v5
	v_lshrrev_b32_e32 v5, 4, v4
	v_bitop3_b32 v4, v5, v4, 32 bitop3:0x6c
	v_lshl_add_u32 v132, v6, 11, v8
	v_ashrrev_i32_e32 v6, 31, v4
	v_lshrrev_b32_e32 v6, 26, v6
	v_add_u32_e32 v6, v4, v6
	v_lshlrev_b32_e32 v5, 3, v15
	v_ashrrev_i32_e32 v16, 6, v6
	v_and_b32_e32 v6, 0xc0, v6
	v_and_b32_e32 v5, -16, v5
	v_sub_u32_e32 v4, v4, v6
	v_add_u32_e32 v5, v16, v5
	v_ashrrev_i16_sdwa v4, v7, sext(v4) dst_sel:DWORD dst_unused:UNUSED_PAD src0_sel:DWORD src1_sel:BYTE_0
	v_and_b32_e32 v7, 3, v16
	v_and_or_b32 v7, v5, s1, v7
	s_ashr_i32 s1, s24, 6
	s_ashr_i32 s0, s24, 8
	s_lshl_b32 s3, s1, 10
	s_add_u32 s33, s82, 0x600000
	s_addc_u32 s50, s83, 0
	s_ashr_i32 s45, s44, 31
	s_ashr_i32 s47, s46, 31
	s_lshl_b64 s[4:5], s[44:45], 19
	s_lshl_b64 s[6:7], s[46:47], 19
	s_add_u32 s48, s33, s6
	v_lshlrev_b32_e32 v8, 5, v15
	v_bfe_i32 v17, v4, 0, 16
	v_lshlrev_b32_e32 v4, 1, v5
	v_lshrrev_b32_e32 v6, 2, v5
	s_addc_u32 s49, s50, s7
	s_add_i32 s47, s3, 0
	v_and_b32_e32 v8, 32, v8
	v_and_b32_e32 v4, 24, v4
	v_and_b32_e32 v6, 4, v6
	s_add_i32 m0, s47, 0x10000
	v_or3_b32 v4, v7, v6, v4
	v_add_lshl_u32 v6, v8, v17, 1
	global_load_lds_dwordx4 v134, s[48:49]
	s_add_i32 m0, s47, 0x12000
	v_lshl_add_u32 v138, v4, 11, v6
	s_add_u32 s6, s48, 0x40000
	global_load_lds_dwordx4 v138, s[48:49]
	s_addc_u32 s7, s49, 0
	s_add_i32 m0, s47, 0x14000
	v_lshl_add_u32 v136, v5, 11, v6
	global_load_lds_dwordx4 v134, s[6:7]
	s_add_i32 m0, s47, 0x16000
	s_add_u32 s4, s62, s4
	s_addc_u32 s5, s63, s5
	s_add_i32 s51, s47, 0x2000
	global_load_lds_dwordx4 v138, s[6:7]
	s_mov_b32 m0, s47
	s_add_u32 s6, s4, 0x40000
	global_load_lds_dwordx4 v132, s[4:5]
	s_mov_b32 m0, s51
	s_addc_u32 s7, s5, 0
	s_add_i32 s64, s47, 0x4000
	global_load_lds_dwordx4 v136, s[4:5]
	s_mov_b32 m0, s64
	s_add_i32 s65, s47, 0x6000
	global_load_lds_dwordx4 v132, s[6:7]
	s_mov_b32 m0, s65
	v_mov_b32_e32 v135, 0
	global_load_lds_dwordx4 v136, s[6:7]
	v_mov_b32_e32 v139, v135
	v_mov_b32_e32 v133, v135
	v_mov_b32_e32 v137, v135
	s_cmp_eq_u32 s0, 1
	s_mov_b32 s66, 0
	v_lshl_add_u64 v[10:11], s[48:49], 0, v[134:135]
	v_lshl_add_u64 v[8:9], s[48:49], 0, v[138:139]
	v_lshl_add_u64 v[4:5], s[4:5], 0, v[132:133]
	s_cselect_b64 s[6:7], -1, 0
	s_cmp_lg_u32 s0, 1
	v_lshl_add_u64 v[6:7], s[4:5], 0, v[136:137]
	s_cbranch_scc1 .LBB0_1106
	s_barrier
	s_setprio 1

.LBB0_1116:
	ds_read_b128 v[148:151], v160
	ds_read_b128 v[152:155], v160 offset:1024
	ds_read_b128 v[166:169], v160 offset:2048
	ds_read_b128 v[170:173], v160 offset:3072
	ds_read_b128 v[174:177], v161
	ds_read_b128 v[178:181], v161 offset:1024
	ds_read_b128 v[182:185], v161 offset:2048
	ds_read_b128 v[186:189], v161 offset:3072
	s_add_u32 s48, s4, 0xfffc0080
	s_addc_u32 s49, s5, -1
	s_cmp_eq_u32 s71, 12
	s_cselect_b32 s59, s39, s49
	s_cselect_b32 s58, s45, s48
	s_cselect_b32 s49, s37, s70
	s_cselect_b32 s48, s60, s61
	v_lshl_add_u64 v[210:211], s[4:5], 0, v[140:141]
	s_add_i32 m0, s47, 0xc000
	ds_read_b128 v[190:193], v162
	ds_read_b128 v[194:197], v162 offset:1024
	ds_read_b128 v[198:201], v162 offset:2048
	ds_read_b128 v[202:205], v162 offset:3072
	ds_read_b128 v[206:209], v162 offset:4096
	ds_read_b128 v[226:229], v162 offset:5120
	ds_read_b128 v[230:233], v162 offset:6144
	ds_read_b128 v[234:237], v162 offset:7168
	global_load_lds_dwordx4 v[210:211], off
	v_lshl_add_u64 v[210:211], s[4:5], 0, v[142:143]
	s_add_i32 m0, s47, 0xe000
	s_nop 0
	global_load_lds_dwordx4 v[210:211], off
	s_waitcnt vmcnt(8)
	s_waitcnt lgkmcnt(0)
	s_barrier
	s_waitcnt lgkmcnt(0)
	v_mfma_f32_16x16x32_bf16 v[128:131], v[148:151], v[190:193], v[128:131]
	v_mfma_f32_16x16x32_bf16 v[124:127], v[166:169], v[190:193], v[124:127]
	v_mfma_f32_16x16x32_bf16 v[112:115], v[148:151], v[198:201], v[112:115]
	v_mfma_f32_16x16x32_bf16 v[108:111], v[166:169], v[198:201], v[108:111]
	v_mfma_f32_16x16x32_bf16 v[96:99], v[148:151], v[206:209], v[96:99]
	v_mfma_f32_16x16x32_bf16 v[92:95], v[166:169], v[206:209], v[92:95]
	v_mfma_f32_16x16x32_bf16 v[80:83], v[148:151], v[230:233], v[80:83]
	v_mfma_f32_16x16x32_bf16 v[76:79], v[166:169], v[230:233], v[76:79]
	v_mfma_f32_16x16x32_bf16 v[128:131], v[152:155], v[194:197], v[128:131]
	v_mfma_f32_16x16x32_bf16 v[124:127], v[170:173], v[194:197], v[124:127]
	v_mfma_f32_16x16x32_bf16 v[112:115], v[152:155], v[202:205], v[112:115]
	v_mfma_f32_16x16x32_bf16 v[108:111], v[170:173], v[202:205], v[108:111]
	v_mfma_f32_16x16x32_bf16 v[96:99], v[152:155], v[226:229], v[96:99]
	v_mfma_f32_16x16x32_bf16 v[92:95], v[170:173], v[226:229], v[92:95]
	v_mfma_f32_16x16x32_bf16 v[80:83], v[152:155], v[234:237], v[80:83]
	v_mfma_f32_16x16x32_bf16 v[76:79], v[170:173], v[234:237], v[76:79]
	v_mfma_f32_16x16x32_bf16 v[120:123], v[174:177], v[190:193], v[120:123]
	v_mfma_f32_16x16x32_bf16 v[116:119], v[182:185], v[190:193], v[116:119]
	v_mfma_f32_16x16x32_bf16 v[104:107], v[174:177], v[198:201], v[104:107]
	v_mfma_f32_16x16x32_bf16 v[100:103], v[182:185], v[198:201], v[100:103]
	v_mfma_f32_16x16x32_bf16 v[88:91], v[174:177], v[206:209], v[88:91]
	v_mfma_f32_16x16x32_bf16 v[84:87], v[182:185], v[206:209], v[84:87]
	v_mfma_f32_16x16x32_bf16 v[72:75], v[174:177], v[230:233], v[72:75]
	v_mfma_f32_16x16x32_bf16 v[68:71], v[182:185], v[230:233], v[68:71]
	v_mfma_f32_16x16x32_bf16 v[120:123], v[178:181], v[194:197], v[120:123]
	v_mfma_f32_16x16x32_bf16 v[116:119], v[186:189], v[194:197], v[116:119]
	v_mfma_f32_16x16x32_bf16 v[104:107], v[178:181], v[202:205], v[104:107]
	v_mfma_f32_16x16x32_bf16 v[100:103], v[186:189], v[202:205], v[100:103]
	v_mfma_f32_16x16x32_bf16 v[88:91], v[178:181], v[226:229], v[88:91]
	v_mfma_f32_16x16x32_bf16 v[84:87], v[186:189], v[226:229], v[84:87]
	v_mfma_f32_16x16x32_bf16 v[72:75], v[178:181], v[234:237], v[72:75]
	v_mfma_f32_16x16x32_bf16 v[68:71], v[186:189], v[234:237], v[68:71]
	s_barrier
	s_add_i32 s72, s78, s3
	v_lshl_add_u64 v[210:211], s[48:49], 0, v[134:135]
	s_mov_b32 m0, s72
	ds_read_b128 v[190:193], v162 offset:16384
	ds_read_b128 v[194:197], v162 offset:17408
	ds_read_b128 v[198:201], v162 offset:18432
	ds_read_b128 v[202:205], v162 offset:19456
	ds_read_b128 v[206:209], v162 offset:20480
	ds_read_b128 v[226:229], v162 offset:21504
	ds_read_b128 v[230:233], v162 offset:22528
	ds_read_b128 v[234:237], v162 offset:23552
	global_load_lds_dwordx4 v[210:211], off
	s_add_i32 m0, s72, 0x2000
	s_add_u32 s72, s48, 0x40000
	v_lshl_add_u64 v[220:221], s[48:49], 0, v[138:139]
	s_addc_u32 s73, s49, 0
	s_add_i32 s74, s79, s3
	global_load_lds_dwordx4 v[220:221], off
	v_lshl_add_u64 v[238:239], s[72:73], 0, v[134:135]
	s_mov_b32 m0, s74
	v_lshl_add_u64 v[240:241], s[58:59], 0, v[136:137]
	global_load_lds_dwordx4 v[238:239], off
	v_lshl_add_u64 v[238:239], s[72:73], 0, v[138:139]
	s_add_i32 m0, s74, 0x2000
	s_nop 0
	global_load_lds_dwordx4 v[238:239], off
	v_lshl_add_u64 v[238:239], s[58:59], 0, v[132:133]
	s_mov_b32 m0, s47
	s_nop 0
	global_load_lds_dwordx4 v[238:239], off
	s_mov_b32 m0, s51
	s_nop 0
	global_load_lds_dwordx4 v[240:241], off
	s_waitcnt vmcnt(8)
	s_waitcnt lgkmcnt(0)
	s_barrier
	s_waitcnt lgkmcnt(0)
	v_mfma_f32_16x16x32_bf16 v[64:67], v[148:151], v[190:193], v[64:67]
	v_mfma_f32_16x16x32_bf16 v[60:63], v[166:169], v[190:193], v[60:63]
	v_mfma_f32_16x16x32_bf16 v[48:51], v[148:151], v[198:201], v[48:51]
	v_mfma_f32_16x16x32_bf16 v[44:47], v[166:169], v[198:201], v[44:47]
	v_mfma_f32_16x16x32_bf16 v[32:35], v[148:151], v[206:209], v[32:35]
	v_mfma_f32_16x16x32_bf16 v[28:31], v[166:169], v[206:209], v[28:31]
	v_mfma_f32_16x16x32_bf16 v[16:19], v[148:151], v[230:233], v[16:19]
	v_mfma_f32_16x16x32_bf16 v[12:15], v[166:169], v[230:233], v[12:15]
	v_mfma_f32_16x16x32_bf16 v[64:67], v[152:155], v[194:197], v[64:67]
	v_mfma_f32_16x16x32_bf16 v[60:63], v[170:173], v[194:197], v[60:63]
	v_mfma_f32_16x16x32_bf16 v[48:51], v[152:155], v[202:205], v[48:51]
	v_mfma_f32_16x16x32_bf16 v[44:47], v[170:173], v[202:205], v[44:47]
	v_mfma_f32_16x16x32_bf16 v[32:35], v[152:155], v[226:229], v[32:35]
	v_mfma_f32_16x16x32_bf16 v[28:31], v[170:173], v[226:229], v[28:31]
	v_mfma_f32_16x16x32_bf16 v[16:19], v[152:155], v[234:237], v[16:19]
	v_mfma_f32_16x16x32_bf16 v[12:15], v[170:173], v[234:237], v[12:15]
	v_mfma_f32_16x16x32_bf16 v[56:59], v[174:177], v[190:193], v[56:59]
	v_mfma_f32_16x16x32_bf16 v[52:55], v[182:185], v[190:193], v[52:55]
	v_mfma_f32_16x16x32_bf16 v[40:43], v[174:177], v[198:201], v[40:43]
	v_mfma_f32_16x16x32_bf16 v[36:39], v[182:185], v[198:201], v[36:39]
	v_mfma_f32_16x16x32_bf16 v[24:27], v[174:177], v[206:209], v[24:27]
	v_mfma_f32_16x16x32_bf16 v[20:23], v[182:185], v[206:209], v[20:23]
	v_mfma_f32_16x16x32_bf16 v[8:11], v[174:177], v[230:233], v[8:11]
	v_mfma_f32_16x16x32_bf16 v[4:7], v[182:185], v[230:233], v[4:7]
	v_mfma_f32_16x16x32_bf16 v[56:59], v[178:181], v[194:197], v[56:59]
	v_mfma_f32_16x16x32_bf16 v[52:55], v[186:189], v[194:197], v[52:55]
	v_mfma_f32_16x16x32_bf16 v[40:43], v[178:181], v[202:205], v[40:43]
	v_mfma_f32_16x16x32_bf16 v[36:39], v[186:189], v[202:205], v[36:39]
	v_mfma_f32_16x16x32_bf16 v[24:27], v[178:181], v[226:229], v[24:27]
	v_mfma_f32_16x16x32_bf16 v[20:23], v[186:189], v[226:229], v[20:23]
	v_mfma_f32_16x16x32_bf16 v[8:11], v[178:181], v[234:237], v[8:11]
	v_mfma_f32_16x16x32_bf16 v[4:7], v[186:189], v[234:237], v[4:7]
	s_barrier
	s_add_i32 s72, 0, 0x18000
	v_add_u32_e32 v165, s72, v3
	s_add_i32 s73, 0, 0x1c000
	ds_read_b128 v[148:151], v165
	ds_read_b128 v[152:155], v165 offset:1024
	ds_read_b128 v[166:169], v165 offset:2048
	ds_read_b128 v[170:173], v165 offset:3072
	v_add_u32_e32 v165, s73, v3
	ds_read_b128 v[174:177], v165
	ds_read_b128 v[178:181], v165 offset:1024
	ds_read_b128 v[182:185], v165 offset:2048
	ds_read_b128 v[186:189], v165 offset:3072
	s_add_u32 s58, s58, 0x40000
	s_addc_u32 s59, s59, 0
	s_mov_b32 m0, s64
	v_lshl_add_u64 v[242:243], s[58:59], 0, v[132:133]
	ds_read_b128 v[190:193], v162 offset:32768
	ds_read_b128 v[194:197], v162 offset:33792
	ds_read_b128 v[198:201], v162 offset:34816
	ds_read_b128 v[202:205], v162 offset:35840
	ds_read_b128 v[206:209], v162 offset:36864
	ds_read_b128 v[226:229], v162 offset:37888
	ds_read_b128 v[230:233], v162 offset:38912
	ds_read_b128 v[234:237], v162 offset:39936
	global_load_lds_dwordx4 v[242:243], off
	v_lshl_add_u64 v[242:243], s[58:59], 0, v[136:137]
	s_mov_b32 m0, s65
	s_nop 0
	global_load_lds_dwordx4 v[242:243], off
	s_waitcnt vmcnt(8)
	s_waitcnt lgkmcnt(0)
	s_barrier
	s_waitcnt lgkmcnt(0)
	v_mfma_f32_16x16x32_bf16 v[128:131], v[148:151], v[190:193], v[128:131]
	v_mfma_f32_16x16x32_bf16 v[124:127], v[166:169], v[190:193], v[124:127]
	v_mfma_f32_16x16x32_bf16 v[112:115], v[148:151], v[198:201], v[112:115]
	v_mfma_f32_16x16x32_bf16 v[108:111], v[166:169], v[198:201], v[108:111]
	v_mfma_f32_16x16x32_bf16 v[96:99], v[148:151], v[206:209], v[96:99]
	v_mfma_f32_16x16x32_bf16 v[92:95], v[166:169], v[206:209], v[92:95]
	v_mfma_f32_16x16x32_bf16 v[80:83], v[148:151], v[230:233], v[80:83]
	v_mfma_f32_16x16x32_bf16 v[76:79], v[166:169], v[230:233], v[76:79]
	v_mfma_f32_16x16x32_bf16 v[128:131], v[152:155], v[194:197], v[128:131]
	v_mfma_f32_16x16x32_bf16 v[124:127], v[170:173], v[194:197], v[124:127]
	v_mfma_f32_16x16x32_bf16 v[112:115], v[152:155], v[202:205], v[112:115]
	v_mfma_f32_16x16x32_bf16 v[108:111], v[170:173], v[202:205], v[108:111]
	v_mfma_f32_16x16x32_bf16 v[96:99], v[152:155], v[226:229], v[96:99]
	v_mfma_f32_16x16x32_bf16 v[92:95], v[170:173], v[226:229], v[92:95]
	v_mfma_f32_16x16x32_bf16 v[80:83], v[152:155], v[234:237], v[80:83]
	v_mfma_f32_16x16x32_bf16 v[76:79], v[170:173], v[234:237], v[76:79]
	v_mfma_f32_16x16x32_bf16 v[120:123], v[174:177], v[190:193], v[120:123]
	v_mfma_f32_16x16x32_bf16 v[116:119], v[182:185], v[190:193], v[116:119]
	v_mfma_f32_16x16x32_bf16 v[104:107], v[174:177], v[198:201], v[104:107]
	v_mfma_f32_16x16x32_bf16 v[100:103], v[182:185], v[198:201], v[100:103]
	v_mfma_f32_16x16x32_bf16 v[88:91], v[174:177], v[206:209], v[88:91]
	v_mfma_f32_16x16x32_bf16 v[84:87], v[182:185], v[206:209], v[84:87]
	v_mfma_f32_16x16x32_bf16 v[72:75], v[174:177], v[230:233], v[72:75]
	v_mfma_f32_16x16x32_bf16 v[68:71], v[182:185], v[230:233], v[68:71]
	v_mfma_f32_16x16x32_bf16 v[120:123], v[178:181], v[194:197], v[120:123]
	v_mfma_f32_16x16x32_bf16 v[116:119], v[186:189], v[194:197], v[116:119]
	v_mfma_f32_16x16x32_bf16 v[104:107], v[178:181], v[202:205], v[104:107]
	v_mfma_f32_16x16x32_bf16 v[100:103], v[186:189], v[202:205], v[100:103]
	v_mfma_f32_16x16x32_bf16 v[88:91], v[178:181], v[226:229], v[88:91]
	v_mfma_f32_16x16x32_bf16 v[84:87], v[186:189], v[226:229], v[84:87]
	v_mfma_f32_16x16x32_bf16 v[72:75], v[178:181], v[234:237], v[72:75]
	v_mfma_f32_16x16x32_bf16 v[68:71], v[186:189], v[234:237], v[68:71]
	s_barrier
	s_add_i32 s58, s72, s3
	v_lshl_add_u64 v[210:211], v[210:211], 0, s[22:23]
	s_mov_b32 m0, s58
	ds_read_b128 v[190:193], v162 offset:49152
	ds_read_b128 v[194:197], v162 offset:50176
	ds_read_b128 v[198:201], v162 offset:51200
	ds_read_b128 v[202:205], v162 offset:52224
	ds_read_b128 v[206:209], v162 offset:53248
	ds_read_b128 v[226:229], v162 offset:54272
	ds_read_b128 v[230:233], v162 offset:55296
	ds_read_b128 v[234:237], v162 offset:56320
	global_load_lds_dwordx4 v[210:211], off
	s_add_i32 m0, s58, 0x2000
	s_add_u32 s48, s48, 0x40080
	v_lshl_add_u64 v[210:211], v[220:221], 0, s[22:23]
	s_addc_u32 s49, s49, 0
	s_add_i32 s58, s73, s3
	global_load_lds_dwordx4 v[210:211], off
	v_lshl_add_u64 v[210:211], s[48:49], 0, v[134:135]
	s_mov_b32 m0, s58
	s_nop 0
	global_load_lds_dwordx4 v[210:211], off
	v_lshl_add_u64 v[210:211], s[48:49], 0, v[138:139]
	s_add_i32 m0, s58, 0x2000
	s_nop 0
	global_load_lds_dwordx4 v[210:211], off
	v_lshl_add_u64 v[210:211], v[238:239], 0, s[22:23]
	s_mov_b32 m0, s68
	s_nop 0
	global_load_lds_dwordx4 v[210:211], off
	v_lshl_add_u64 v[210:211], v[240:241], 0, s[22:23]
	s_mov_b32 m0, s69
	s_nop 0
	global_load_lds_dwordx4 v[210:211], off
	s_waitcnt vmcnt(8)
	s_waitcnt lgkmcnt(0)
	s_barrier
	s_waitcnt lgkmcnt(0)
	v_mfma_f32_16x16x32_bf16 v[64:67], v[148:151], v[190:193], v[64:67]
	v_mfma_f32_16x16x32_bf16 v[60:63], v[166:169], v[190:193], v[60:63]
	v_mfma_f32_16x16x32_bf16 v[48:51], v[148:151], v[198:201], v[48:51]
	v_mfma_f32_16x16x32_bf16 v[44:47], v[166:169], v[198:201], v[44:47]
	v_mfma_f32_16x16x32_bf16 v[32:35], v[148:151], v[206:209], v[32:35]
	v_mfma_f32_16x16x32_bf16 v[28:31], v[166:169], v[206:209], v[28:31]
	v_mfma_f32_16x16x32_bf16 v[16:19], v[148:151], v[230:233], v[16:19]
	v_mfma_f32_16x16x32_bf16 v[12:15], v[166:169], v[230:233], v[12:15]
	v_mfma_f32_16x16x32_bf16 v[64:67], v[152:155], v[194:197], v[64:67]
	v_mfma_f32_16x16x32_bf16 v[60:63], v[170:173], v[194:197], v[60:63]
	v_mfma_f32_16x16x32_bf16 v[48:51], v[152:155], v[202:205], v[48:51]
	v_mfma_f32_16x16x32_bf16 v[44:47], v[170:173], v[202:205], v[44:47]
	v_mfma_f32_16x16x32_bf16 v[32:35], v[152:155], v[226:229], v[32:35]
	v_mfma_f32_16x16x32_bf16 v[28:31], v[170:173], v[226:229], v[28:31]
	v_mfma_f32_16x16x32_bf16 v[16:19], v[152:155], v[234:237], v[16:19]
	v_mfma_f32_16x16x32_bf16 v[12:15], v[170:173], v[234:237], v[12:15]
	v_mfma_f32_16x16x32_bf16 v[56:59], v[174:177], v[190:193], v[56:59]
	v_mfma_f32_16x16x32_bf16 v[52:55], v[182:185], v[190:193], v[52:55]
	v_mfma_f32_16x16x32_bf16 v[40:43], v[174:177], v[198:201], v[40:43]
	v_mfma_f32_16x16x32_bf16 v[36:39], v[182:185], v[198:201], v[36:39]
	v_mfma_f32_16x16x32_bf16 v[24:27], v[174:177], v[206:209], v[24:27]
	v_mfma_f32_16x16x32_bf16 v[20:23], v[182:185], v[206:209], v[20:23]
	v_mfma_f32_16x16x32_bf16 v[8:11], v[174:177], v[230:233], v[8:11]
	v_mfma_f32_16x16x32_bf16 v[4:7], v[182:185], v[230:233], v[4:7]
	v_mfma_f32_16x16x32_bf16 v[56:59], v[178:181], v[194:197], v[56:59]
	v_mfma_f32_16x16x32_bf16 v[52:55], v[186:189], v[194:197], v[52:55]
	v_mfma_f32_16x16x32_bf16 v[40:43], v[178:181], v[202:205], v[40:43]
	v_mfma_f32_16x16x32_bf16 v[36:39], v[186:189], v[202:205], v[36:39]
	v_mfma_f32_16x16x32_bf16 v[24:27], v[178:181], v[226:229], v[24:27]
	v_mfma_f32_16x16x32_bf16 v[20:23], v[186:189], v[226:229], v[20:23]
	v_mfma_f32_16x16x32_bf16 v[8:11], v[178:181], v[234:237], v[8:11]
	v_mfma_f32_16x16x32_bf16 v[4:7], v[186:189], v[234:237], v[4:7]
	s_barrier
	s_add_i32 s71, s71, 2
	s_add_u32 s4, s4, 0x100
	s_addc_u32 s5, s5, 0
	s_add_u32 s61, s61, 0x100
	s_addc_u32 s70, s70, 0
	s_cmp_gt_u32 s71, 13
	s_cbranch_scc0 .LBB0_1116
	s_and_b64 vcc, exec, s[24:25]
	s_cbranch_vccz .LBB0_1119
	s_barrier

.LBB0_1170:
	v_readlane_b32 s0, v244, 3
	v_readlane_b32 s1, v244, 4
	s_cmp_gt_i32 s1, 7
	s_cselect_b64 s[0:1], -1, 0
	s_and_b64 s[4:5], s[8:9], s[0:1]
	s_andn2_b64 vcc, exec, s[4:5]
	s_cbranch_vccnz .LBB0_1224
	s_setprio 0
	s_waitcnt vmcnt(0)
	s_waitcnt vmcnt(0)
	s_barrier
	s_getreg_b32 s3, hwreg(HW_REG_HW_ID, 0, 6)
	s_and_b32 s3, s3, 63
	s_lshl_b32 s3, s3, 2
	s_add_i32 s3, s3, 0
	s_mov_b64 s[4:5], src_shared_base
	s_add_i32 s3, s3, 0x23e00
	v_mov_b32_e32 v4, s3
	v_mov_b32_e32 v5, s5
	flat_load_dword v3, v[4:5] sc0 sc1
	s_waitcnt vmcnt(0) lgkmcnt(0)
	v_readfirstlane_b32 s3, v3
	s_cmp_lg_u32 s3, 1
	s_cbranch_scc1 .Learlyinv_skip6
	buffer_inv sc1
	s_waitcnt vmcnt(0)

.LBB0_1600:
	v_ashrrev_i32_e32 v4, 31, v2
	v_lshrrev_b32_e32 v4, 26, v4
	v_lshlrev_b32_e32 v3, 4, v2
	v_add_u32_e32 v4, v2, v4
	v_bfe_i32 v2, v2, 27, 1
	v_lshrrev_b32_e32 v2, 22, v2
	v_add_u32_e32 v2, v3, v2
	v_and_b32_e32 v2, 0xfffffc00, v2
	v_sub_u32_e32 v2, v3, v2
	v_ashrrev_i32_e32 v10, 6, v4
	v_lshrrev_b32_e32 v4, 4, v2
	v_bitop3_b32 v2, v4, v2, 32 bitop3:0x6c
	v_ashrrev_i32_e32 v5, 31, v2
	v_lshrrev_b32_e32 v5, 26, v5
	v_add_u32_e32 v5, v2, v5
	v_lshlrev_b32_e32 v4, 3, v10
	v_ashrrev_i32_e32 v11, 6, v5
	v_and_b32_e32 v5, 0xc0, v5
	v_and_b32_e32 v4, -16, v4
	v_sub_u32_e32 v2, v2, v5
	v_mov_b32_e32 v5, 1
	v_add_u32_e32 v4, v11, v4
	v_ashrrev_i16_sdwa v2, v5, sext(v2) dst_sel:DWORD dst_unused:UNUSED_PAD src0_sel:DWORD src1_sel:BYTE_0
	v_lshlrev_b32_e32 v6, 5, v10
	v_bfe_i32 v12, v2, 0, 16
	v_lshlrev_b32_e32 v2, 1, v4
	v_lshrrev_b32_e32 v7, 2, v4
	v_and_b32_e32 v8, 3, v11
	s_mov_b32 s1, 0x1fffe0
	v_and_b32_e32 v6, 32, v6
	v_and_b32_e32 v2, 24, v2
	v_and_b32_e32 v7, 4, v7
	v_and_or_b32 v8, v4, s1, v8
	v_or3_b32 v2, v8, v7, v2
	v_add_lshl_u32 v6, v6, v12, 1
	v_lshl_add_u32 v132, v2, 11, v6
	v_add_u32_e32 v2, 0x2000, v3
	v_ashrrev_i32_e32 v3, 31, v2
	v_lshrrev_b32_e32 v3, 22, v3
	v_add_u32_e32 v3, v2, v3
	v_ashrrev_i32_e32 v13, 10, v3
	v_mul_i32_i24_e32 v3, 0x400, v13
	v_sub_u32_e32 v2, v2, v3
	v_lshrrev_b32_e32 v3, 4, v2
	v_bitop3_b32 v2, v3, v2, 32 bitop3:0x6c
	v_lshl_add_u32 v130, v4, 11, v6
	v_ashrrev_i32_e32 v4, 31, v2
	v_lshrrev_b32_e32 v4, 26, v4
	v_add_u32_e32 v4, v2, v4
	s_ashr_i32 s0, s5, 3
	v_lshlrev_b32_e32 v3, 3, v13
	v_ashrrev_i32_e32 v14, 6, v4
	v_and_b32_e32 v4, 0xc0, v4
	s_add_u32 s35, s82, 0x8600000
	v_and_b32_e32 v3, -16, v3
	v_sub_u32_e32 v2, v2, v4
	s_addc_u32 s36, s83, 0
	v_add_u32_e32 v3, v14, v3
	v_ashrrev_i16_sdwa v2, v5, sext(v2) dst_sel:DWORD dst_unused:UNUSED_PAD src0_sel:DWORD src1_sel:BYTE_0
	v_and_b32_e32 v5, 3, v14
	s_add_i32 s0, s4, s0
	v_and_or_b32 v5, v3, s1, v5
	s_ashr_i32 s1, s0, 31
	s_lshr_b32 s1, s1, 27
	s_add_i32 s1, s0, s1
	s_ashr_i32 s4, s1, 5
	s_andn2_b32 s1, s1, 31
	s_sub_i32 s1, s0, s1
	s_bfe_i32 s0, s1, 0x80000
	s_bfe_u32 s0, s0, 0x3000c
	s_add_i32 s5, s1, s0
	s_bfe_i32 s0, s5, 0x80000
	s_and_b32 s5, s5, 0xf8
	s_sub_i32 s1, s1, s5
	s_lshl_b32 s4, s4, 3
	s_sext_i32_i16 s0, s0
	s_sext_i32_i8 s1, s1
	s_lshr_b32 s0, s0, 3
	s_add_i32 s12, s4, s1
	s_ashr_i32 s7, s3, 6
	s_ashr_i32 s13, s12, 31
	s_bfe_i64 s[14:15], s[0:1], 0x100000
	s_ashr_i32 s33, s3, 8
	s_lshl_b32 s37, s7, 10
	s_lshl_b64 s[4:5], s[12:13], 19
	s_lshl_b64 s[14:15], s[14:15], 19
	s_add_u32 s26, s10, s14
	v_lshlrev_b32_e32 v6, 5, v13
	v_bfe_i32 v15, v2, 0, 16
	v_lshlrev_b32_e32 v2, 1, v3
	v_lshrrev_b32_e32 v4, 2, v3
	s_addc_u32 s27, s11, s15
	s_add_i32 s38, s37, 0
	v_and_b32_e32 v6, 32, v6
	v_and_b32_e32 v2, 24, v2
	v_and_b32_e32 v4, 4, v4
	s_add_i32 m0, s38, 0x10000
	v_or3_b32 v2, v5, v4, v2
	v_add_lshl_u32 v4, v6, v15, 1
	global_load_lds_dwordx4 v132, s[26:27]
	s_add_i32 m0, s38, 0x12000
	v_lshl_add_u32 v136, v2, 11, v4
	s_add_u32 s14, s26, 0x40000
	global_load_lds_dwordx4 v136, s[26:27]
	s_addc_u32 s15, s27, 0
	s_add_i32 m0, s38, 0x14000
	v_lshl_add_u32 v134, v3, 11, v4
	global_load_lds_dwordx4 v132, s[14:15]
	s_add_i32 m0, s38, 0x16000
	v_mov_b32_e32 v133, 0
	global_load_lds_dwordx4 v136, s[14:15]
	s_add_u32 s14, s35, s4
	s_addc_u32 s15, s36, s5
	s_add_i32 s39, s38, 0x2000
	s_mov_b32 m0, s38
	s_add_u32 s4, s14, 0x40000
	global_load_lds_dwordx4 v130, s[14:15]
	s_mov_b32 m0, s39
	s_addc_u32 s5, s15, 0
	s_add_i32 s40, s38, 0x4000
	global_load_lds_dwordx4 v134, s[14:15]
	s_mov_b32 m0, s40
	s_add_i32 s41, s38, 0x6000
	global_load_lds_dwordx4 v130, s[4:5]
	s_mov_b32 m0, s41
	v_mov_b32_e32 v137, v133
	global_load_lds_dwordx4 v134, s[4:5]
	v_mov_b32_e32 v131, v133
	v_mov_b32_e32 v135, v133
	v_lshl_add_u64 v[8:9], s[26:27], 0, v[132:133]
	v_lshl_add_u64 v[6:7], s[26:27], 0, v[136:137]
	v_lshl_add_u64 v[4:5], s[14:15], 0, v[130:131]
	s_cmp_lg_u32 s33, 1
	v_lshl_add_u64 v[2:3], s[14:15], 0, v[134:135]
	s_cbranch_scc1 .LBB0_1602
	s_barrier
	s_setprio 1

.LBB0_1612:
	v_add_u32_e32 v160, s46, v150
	ds_read_b128 v[152:155], v160
	ds_read_b128 v[156:159], v160 offset:1024
	ds_read_b128 v[166:169], v160 offset:2048
	ds_read_b128 v[170:173], v160 offset:3072
	v_add_u32_e32 v160, s47, v150
	s_add_u32 s28, s14, s26
	ds_read_b128 v[174:177], v160
	ds_read_b128 v[178:181], v160 offset:1024
	ds_read_b128 v[182:185], v160 offset:2048
	ds_read_b128 v[186:189], v160 offset:3072
	s_addc_u32 s29, s15, s27
	s_add_u32 s28, s28, 0x100
	s_addc_u32 s29, s29, 0
	s_add_u32 s60, s49, s26
	s_addc_u32 s61, s50, s27
	s_cmpk_eq_i32 s26, 0x700
	s_cselect_b32 s31, s21, s29
	s_cselect_b32 s30, s51, s28
	s_cselect_b32 s29, s19, s61
	s_cselect_b32 s28, s58, s60
	v_lshl_add_u64 v[160:161], v[146:147], 0, s[26:27]
	s_add_i32 m0, s38, 0xc000
	ds_read_b128 v[190:193], v151
	ds_read_b128 v[194:197], v151 offset:1024
	ds_read_b128 v[198:201], v151 offset:2048
	ds_read_b128 v[202:205], v151 offset:3072
	ds_read_b128 v[206:209], v151 offset:4096
	ds_read_b128 v[226:229], v151 offset:5120
	ds_read_b128 v[230:233], v151 offset:6144
	ds_read_b128 v[234:237], v151 offset:7168
	global_load_lds_dwordx4 v[160:161], off
	v_lshl_add_u64 v[160:161], v[148:149], 0, s[26:27]
	s_add_i32 m0, s38, 0xe000
	s_nop 0
	global_load_lds_dwordx4 v[160:161], off
	s_waitcnt vmcnt(8)
	s_waitcnt lgkmcnt(0)
	s_barrier
	s_waitcnt lgkmcnt(0)
	v_mfma_f32_16x16x32_bf16 v[122:125], v[152:155], v[190:193], v[122:125]
	v_mfma_f32_16x16x32_bf16 v[126:129], v[166:169], v[190:193], v[126:129]
	v_mfma_f32_16x16x32_bf16 v[110:113], v[152:155], v[198:201], v[110:113]
	v_mfma_f32_16x16x32_bf16 v[106:109], v[166:169], v[198:201], v[106:109]
	v_mfma_f32_16x16x32_bf16 v[94:97], v[152:155], v[206:209], v[94:97]
	v_mfma_f32_16x16x32_bf16 v[90:93], v[166:169], v[206:209], v[90:93]
	v_mfma_f32_16x16x32_bf16 v[78:81], v[152:155], v[230:233], v[78:81]
	v_mfma_f32_16x16x32_bf16 v[74:77], v[166:169], v[230:233], v[74:77]
	v_mfma_f32_16x16x32_bf16 v[122:125], v[156:159], v[194:197], v[122:125]
	v_mfma_f32_16x16x32_bf16 v[126:129], v[170:173], v[194:197], v[126:129]
	v_mfma_f32_16x16x32_bf16 v[110:113], v[156:159], v[202:205], v[110:113]
	v_mfma_f32_16x16x32_bf16 v[106:109], v[170:173], v[202:205], v[106:109]
	v_mfma_f32_16x16x32_bf16 v[94:97], v[156:159], v[226:229], v[94:97]
	v_mfma_f32_16x16x32_bf16 v[90:93], v[170:173], v[226:229], v[90:93]
	v_mfma_f32_16x16x32_bf16 v[78:81], v[156:159], v[234:237], v[78:81]
	v_mfma_f32_16x16x32_bf16 v[74:77], v[170:173], v[234:237], v[74:77]
	v_mfma_f32_16x16x32_bf16 v[118:121], v[174:177], v[190:193], v[118:121]
	v_mfma_f32_16x16x32_bf16 v[114:117], v[182:185], v[190:193], v[114:117]
	v_mfma_f32_16x16x32_bf16 v[102:105], v[174:177], v[198:201], v[102:105]
	v_mfma_f32_16x16x32_bf16 v[98:101], v[182:185], v[198:201], v[98:101]
	v_mfma_f32_16x16x32_bf16 v[86:89], v[174:177], v[206:209], v[86:89]
	v_mfma_f32_16x16x32_bf16 v[82:85], v[182:185], v[206:209], v[82:85]
	v_mfma_f32_16x16x32_bf16 v[70:73], v[174:177], v[230:233], v[70:73]
	v_mfma_f32_16x16x32_bf16 v[66:69], v[182:185], v[230:233], v[66:69]
	v_mfma_f32_16x16x32_bf16 v[118:121], v[178:181], v[194:197], v[118:121]
	v_mfma_f32_16x16x32_bf16 v[114:117], v[186:189], v[194:197], v[114:117]
	v_mfma_f32_16x16x32_bf16 v[102:105], v[178:181], v[202:205], v[102:105]
	v_mfma_f32_16x16x32_bf16 v[98:101], v[186:189], v[202:205], v[98:101]
	v_mfma_f32_16x16x32_bf16 v[86:89], v[178:181], v[226:229], v[86:89]
	v_mfma_f32_16x16x32_bf16 v[82:85], v[186:189], v[226:229], v[82:85]
	v_mfma_f32_16x16x32_bf16 v[70:73], v[178:181], v[234:237], v[70:73]
	v_mfma_f32_16x16x32_bf16 v[66:69], v[186:189], v[234:237], v[66:69]
	s_barrier
	s_add_i32 s60, s46, s37
	v_lshl_add_u64 v[160:161], s[28:29], 0, v[132:133]
	s_mov_b32 m0, s60
	ds_read_b128 v[190:193], v151 offset:16384
	ds_read_b128 v[194:197], v151 offset:17408
	ds_read_b128 v[198:201], v151 offset:18432
	ds_read_b128 v[202:205], v151 offset:19456
	ds_read_b128 v[206:209], v151 offset:20480
	ds_read_b128 v[226:229], v151 offset:21504
	ds_read_b128 v[230:233], v151 offset:22528
	ds_read_b128 v[234:237], v151 offset:23552
	global_load_lds_dwordx4 v[160:161], off
	s_add_i32 m0, s60, 0x2000
	s_add_u32 s60, s28, 0x40000
	v_lshl_add_u64 v[210:211], s[28:29], 0, v[136:137]
	s_addc_u32 s61, s29, 0
	s_add_i32 s64, s47, s37
	global_load_lds_dwordx4 v[210:211], off
	v_lshl_add_u64 v[214:215], s[60:61], 0, v[132:133]
	s_mov_b32 m0, s64
	v_lshl_add_u64 v[220:221], s[30:31], 0, v[134:135]
	global_load_lds_dwordx4 v[214:215], off
	v_lshl_add_u64 v[214:215], s[60:61], 0, v[136:137]
	s_add_i32 m0, s64, 0x2000
	s_nop 0
	global_load_lds_dwordx4 v[214:215], off
	v_lshl_add_u64 v[214:215], s[30:31], 0, v[130:131]
	s_mov_b32 m0, s38
	s_nop 0
	global_load_lds_dwordx4 v[214:215], off
	s_mov_b32 m0, s39
	s_nop 0
	global_load_lds_dwordx4 v[220:221], off
	s_waitcnt vmcnt(8)
	s_waitcnt lgkmcnt(0)
	s_barrier
	s_waitcnt lgkmcnt(0)
	v_mfma_f32_16x16x32_bf16 v[62:65], v[152:155], v[190:193], v[62:65]
	v_mfma_f32_16x16x32_bf16 v[58:61], v[166:169], v[190:193], v[58:61]
	v_mfma_f32_16x16x32_bf16 v[46:49], v[152:155], v[198:201], v[46:49]
	v_mfma_f32_16x16x32_bf16 v[42:45], v[166:169], v[198:201], v[42:45]
	v_mfma_f32_16x16x32_bf16 v[30:33], v[152:155], v[206:209], v[30:33]
	v_mfma_f32_16x16x32_bf16 v[26:29], v[166:169], v[206:209], v[26:29]
	v_mfma_f32_16x16x32_bf16 v[14:17], v[152:155], v[230:233], v[14:17]
	v_mfma_f32_16x16x32_bf16 v[10:13], v[166:169], v[230:233], v[10:13]
	v_mfma_f32_16x16x32_bf16 v[62:65], v[156:159], v[194:197], v[62:65]
	v_mfma_f32_16x16x32_bf16 v[58:61], v[170:173], v[194:197], v[58:61]
	v_mfma_f32_16x16x32_bf16 v[46:49], v[156:159], v[202:205], v[46:49]
	v_mfma_f32_16x16x32_bf16 v[42:45], v[170:173], v[202:205], v[42:45]
	v_mfma_f32_16x16x32_bf16 v[30:33], v[156:159], v[226:229], v[30:33]
	v_mfma_f32_16x16x32_bf16 v[26:29], v[170:173], v[226:229], v[26:29]
	v_mfma_f32_16x16x32_bf16 v[14:17], v[156:159], v[234:237], v[14:17]
	v_mfma_f32_16x16x32_bf16 v[10:13], v[170:173], v[234:237], v[10:13]
	v_mfma_f32_16x16x32_bf16 v[54:57], v[174:177], v[190:193], v[54:57]
	v_mfma_f32_16x16x32_bf16 v[50:53], v[182:185], v[190:193], v[50:53]
	v_mfma_f32_16x16x32_bf16 v[38:41], v[174:177], v[198:201], v[38:41]
	v_mfma_f32_16x16x32_bf16 v[34:37], v[182:185], v[198:201], v[34:37]
	v_mfma_f32_16x16x32_bf16 v[22:25], v[174:177], v[206:209], v[22:25]
	v_mfma_f32_16x16x32_bf16 v[18:21], v[182:185], v[206:209], v[18:21]
	v_mfma_f32_16x16x32_bf16 v[6:9], v[174:177], v[230:233], v[6:9]
	v_mfma_f32_16x16x32_bf16 v[2:5], v[182:185], v[230:233], v[2:5]
	v_mfma_f32_16x16x32_bf16 v[54:57], v[178:181], v[194:197], v[54:57]
	v_mfma_f32_16x16x32_bf16 v[50:53], v[186:189], v[194:197], v[50:53]
	v_mfma_f32_16x16x32_bf16 v[38:41], v[178:181], v[202:205], v[38:41]
	v_mfma_f32_16x16x32_bf16 v[34:37], v[186:189], v[202:205], v[34:37]
	v_mfma_f32_16x16x32_bf16 v[22:25], v[178:181], v[226:229], v[22:25]
	v_mfma_f32_16x16x32_bf16 v[18:21], v[186:189], v[226:229], v[18:21]
	v_mfma_f32_16x16x32_bf16 v[6:9], v[178:181], v[234:237], v[6:9]
	v_mfma_f32_16x16x32_bf16 v[2:5], v[186:189], v[234:237], v[2:5]
	s_barrier
	s_add_i32 s60, 0, 0x18000
	v_add_u32_e32 v163, s60, v150
	s_add_i32 s61, 0, 0x1c000
	ds_read_b128 v[152:155], v163
	ds_read_b128 v[156:159], v163 offset:1024
	ds_read_b128 v[166:169], v163 offset:2048
	ds_read_b128 v[170:173], v163 offset:3072
	v_add_u32_e32 v163, s61, v150
	ds_read_b128 v[174:177], v163
	ds_read_b128 v[178:181], v163 offset:1024
	ds_read_b128 v[182:185], v163 offset:2048
	ds_read_b128 v[186:189], v163 offset:3072
	s_add_u32 s30, s30, 0x40000
	s_addc_u32 s31, s31, 0
	s_mov_b32 m0, s40
	v_lshl_add_u64 v[238:239], s[30:31], 0, v[130:131]
	ds_read_b128 v[190:193], v151 offset:32768
	ds_read_b128 v[194:197], v151 offset:33792
	ds_read_b128 v[198:201], v151 offset:34816
	ds_read_b128 v[202:205], v151 offset:35840
	ds_read_b128 v[206:209], v151 offset:36864
	ds_read_b128 v[226:229], v151 offset:37888
	ds_read_b128 v[230:233], v151 offset:38912
	ds_read_b128 v[234:237], v151 offset:39936
	global_load_lds_dwordx4 v[238:239], off
	v_lshl_add_u64 v[238:239], s[30:31], 0, v[134:135]
	s_mov_b32 m0, s41
	s_nop 0
	global_load_lds_dwordx4 v[238:239], off
	s_waitcnt vmcnt(8)
	s_waitcnt lgkmcnt(0)
	s_barrier
	s_waitcnt lgkmcnt(0)
	v_mfma_f32_16x16x32_bf16 v[122:125], v[152:155], v[190:193], v[122:125]
	v_mfma_f32_16x16x32_bf16 v[126:129], v[166:169], v[190:193], v[126:129]
	v_mfma_f32_16x16x32_bf16 v[110:113], v[152:155], v[198:201], v[110:113]
	v_mfma_f32_16x16x32_bf16 v[106:109], v[166:169], v[198:201], v[106:109]
	v_mfma_f32_16x16x32_bf16 v[94:97], v[152:155], v[206:209], v[94:97]
	v_mfma_f32_16x16x32_bf16 v[90:93], v[166:169], v[206:209], v[90:93]
	v_mfma_f32_16x16x32_bf16 v[78:81], v[152:155], v[230:233], v[78:81]
	v_mfma_f32_16x16x32_bf16 v[74:77], v[166:169], v[230:233], v[74:77]
	v_mfma_f32_16x16x32_bf16 v[122:125], v[156:159], v[194:197], v[122:125]
	v_mfma_f32_16x16x32_bf16 v[126:129], v[170:173], v[194:197], v[126:129]
	v_mfma_f32_16x16x32_bf16 v[110:113], v[156:159], v[202:205], v[110:113]
	v_mfma_f32_16x16x32_bf16 v[106:109], v[170:173], v[202:205], v[106:109]
	v_mfma_f32_16x16x32_bf16 v[94:97], v[156:159], v[226:229], v[94:97]
	v_mfma_f32_16x16x32_bf16 v[90:93], v[170:173], v[226:229], v[90:93]
	v_mfma_f32_16x16x32_bf16 v[78:81], v[156:159], v[234:237], v[78:81]
	v_mfma_f32_16x16x32_bf16 v[74:77], v[170:173], v[234:237], v[74:77]
	v_mfma_f32_16x16x32_bf16 v[118:121], v[174:177], v[190:193], v[118:121]
	v_mfma_f32_16x16x32_bf16 v[114:117], v[182:185], v[190:193], v[114:117]
	v_mfma_f32_16x16x32_bf16 v[102:105], v[174:177], v[198:201], v[102:105]
	v_mfma_f32_16x16x32_bf16 v[98:101], v[182:185], v[198:201], v[98:101]
	v_mfma_f32_16x16x32_bf16 v[86:89], v[174:177], v[206:209], v[86:89]
	v_mfma_f32_16x16x32_bf16 v[82:85], v[182:185], v[206:209], v[82:85]
	v_mfma_f32_16x16x32_bf16 v[70:73], v[174:177], v[230:233], v[70:73]
	v_mfma_f32_16x16x32_bf16 v[66:69], v[182:185], v[230:233], v[66:69]
	v_mfma_f32_16x16x32_bf16 v[118:121], v[178:181], v[194:197], v[118:121]
	v_mfma_f32_16x16x32_bf16 v[114:117], v[186:189], v[194:197], v[114:117]
	v_mfma_f32_16x16x32_bf16 v[102:105], v[178:181], v[202:205], v[102:105]
	v_mfma_f32_16x16x32_bf16 v[98:101], v[186:189], v[202:205], v[98:101]
	v_mfma_f32_16x16x32_bf16 v[86:89], v[178:181], v[226:229], v[86:89]
	v_mfma_f32_16x16x32_bf16 v[82:85], v[186:189], v[226:229], v[82:85]
	v_mfma_f32_16x16x32_bf16 v[70:73], v[178:181], v[234:237], v[70:73]
	v_mfma_f32_16x16x32_bf16 v[66:69], v[186:189], v[234:237], v[66:69]
	s_barrier
	s_add_i32 s30, s60, s37
	v_lshl_add_u64 v[160:161], v[160:161], 0, s[16:17]
	s_mov_b32 m0, s30
	ds_read_b128 v[190:193], v151 offset:49152
	ds_read_b128 v[194:197], v151 offset:50176
	ds_read_b128 v[198:201], v151 offset:51200
	ds_read_b128 v[202:205], v151 offset:52224
	ds_read_b128 v[206:209], v151 offset:53248
	ds_read_b128 v[226:229], v151 offset:54272
	ds_read_b128 v[230:233], v151 offset:55296
	ds_read_b128 v[234:237], v151 offset:56320
	global_load_lds_dwordx4 v[160:161], off
	s_add_i32 m0, s30, 0x2000
	s_add_u32 s28, s28, 0x40080
	v_lshl_add_u64 v[160:161], v[210:211], 0, s[16:17]
	s_addc_u32 s29, s29, 0
	s_add_i32 s30, s61, s37
	global_load_lds_dwordx4 v[160:161], off
	v_lshl_add_u64 v[160:161], s[28:29], 0, v[132:133]
	s_mov_b32 m0, s30
	s_nop 0
	global_load_lds_dwordx4 v[160:161], off
	v_lshl_add_u64 v[160:161], s[28:29], 0, v[136:137]
	s_add_i32 m0, s30, 0x2000
	s_nop 0
	global_load_lds_dwordx4 v[160:161], off
	v_lshl_add_u64 v[160:161], v[214:215], 0, s[16:17]
	s_mov_b32 m0, s43
	s_nop 0
	global_load_lds_dwordx4 v[160:161], off
	v_lshl_add_u64 v[160:161], v[220:221], 0, s[16:17]
	s_mov_b32 m0, s44
	s_nop 0
	global_load_lds_dwordx4 v[160:161], off
	s_waitcnt vmcnt(8)
	s_waitcnt lgkmcnt(0)
	s_barrier
	s_waitcnt lgkmcnt(0)
	v_mfma_f32_16x16x32_bf16 v[62:65], v[152:155], v[190:193], v[62:65]
	v_mfma_f32_16x16x32_bf16 v[58:61], v[166:169], v[190:193], v[58:61]
	v_mfma_f32_16x16x32_bf16 v[46:49], v[152:155], v[198:201], v[46:49]
	v_mfma_f32_16x16x32_bf16 v[42:45], v[166:169], v[198:201], v[42:45]
	v_mfma_f32_16x16x32_bf16 v[30:33], v[152:155], v[206:209], v[30:33]
	v_mfma_f32_16x16x32_bf16 v[26:29], v[166:169], v[206:209], v[26:29]
	v_mfma_f32_16x16x32_bf16 v[14:17], v[152:155], v[230:233], v[14:17]
	v_mfma_f32_16x16x32_bf16 v[10:13], v[166:169], v[230:233], v[10:13]
	v_mfma_f32_16x16x32_bf16 v[62:65], v[156:159], v[194:197], v[62:65]
	v_mfma_f32_16x16x32_bf16 v[58:61], v[170:173], v[194:197], v[58:61]
	v_mfma_f32_16x16x32_bf16 v[46:49], v[156:159], v[202:205], v[46:49]
	v_mfma_f32_16x16x32_bf16 v[42:45], v[170:173], v[202:205], v[42:45]
	v_mfma_f32_16x16x32_bf16 v[30:33], v[156:159], v[226:229], v[30:33]
	v_mfma_f32_16x16x32_bf16 v[26:29], v[170:173], v[226:229], v[26:29]
	v_mfma_f32_16x16x32_bf16 v[14:17], v[156:159], v[234:237], v[14:17]
	v_mfma_f32_16x16x32_bf16 v[10:13], v[170:173], v[234:237], v[10:13]
	v_mfma_f32_16x16x32_bf16 v[54:57], v[174:177], v[190:193], v[54:57]
	v_mfma_f32_16x16x32_bf16 v[50:53], v[182:185], v[190:193], v[50:53]
	v_mfma_f32_16x16x32_bf16 v[38:41], v[174:177], v[198:201], v[38:41]
	v_mfma_f32_16x16x32_bf16 v[34:37], v[182:185], v[198:201], v[34:37]
	v_mfma_f32_16x16x32_bf16 v[22:25], v[174:177], v[206:209], v[22:25]
	v_mfma_f32_16x16x32_bf16 v[18:21], v[182:185], v[206:209], v[18:21]
	v_mfma_f32_16x16x32_bf16 v[6:9], v[174:177], v[230:233], v[6:9]
	v_mfma_f32_16x16x32_bf16 v[2:5], v[182:185], v[230:233], v[2:5]
	v_mfma_f32_16x16x32_bf16 v[54:57], v[178:181], v[194:197], v[54:57]
	v_mfma_f32_16x16x32_bf16 v[50:53], v[186:189], v[194:197], v[50:53]
	v_mfma_f32_16x16x32_bf16 v[38:41], v[178:181], v[202:205], v[38:41]
	v_mfma_f32_16x16x32_bf16 v[34:37], v[186:189], v[202:205], v[34:37]
	v_mfma_f32_16x16x32_bf16 v[22:25], v[178:181], v[226:229], v[22:25]
	v_mfma_f32_16x16x32_bf16 v[18:21], v[186:189], v[226:229], v[18:21]
	v_mfma_f32_16x16x32_bf16 v[6:9], v[178:181], v[234:237], v[6:9]
	v_mfma_f32_16x16x32_bf16 v[2:5], v[186:189], v[234:237], v[2:5]
	s_barrier
	s_add_i32 s59, s59, 2
	s_add_u32 s26, s26, 0x100
	s_addc_u32 s27, s27, 0
	s_cmp_gt_u32 s59, 13
	s_cbranch_scc0 .LBB0_1612
	s_add_u32 s26, s49, 0xffffff00
	s_addc_u32 s27, s50, -1
	s_andn2_b64 vcc, exec, s[4:5]
	s_cbranch_vccnz .LBB0_1603
	v_mov_b32_e32 v2, 0
	s_mov_b32 s6, s18
	s_mov_b32 s12, s20
	s_mov_b64 s[14:15], s[24:25]
	s_mov_b32 s45, s48
	v_mov_b32_e32 v3, v2
	v_mov_b32_e32 v4, v2
	v_mov_b32_e32 v5, v2
	v_mov_b32_e32 v6, v2
	v_mov_b32_e32 v7, v2
	v_mov_b32_e32 v8, v2
	v_mov_b32_e32 v9, v2
	v_mov_b32_e32 v18, v2
	v_mov_b32_e32 v19, v2
	v_mov_b32_e32 v20, v2
	v_mov_b32_e32 v21, v2
	v_mov_b32_e32 v22, v2
	v_mov_b32_e32 v23, v2
	v_mov_b32_e32 v24, v2
	v_mov_b32_e32 v25, v2
	v_mov_b32_e32 v34, v2
	v_mov_b32_e32 v35, v2
	v_mov_b32_e32 v36, v2
	v_mov_b32_e32 v37, v2
	v_mov_b32_e32 v38, v2
	v_mov_b32_e32 v39, v2
	v_mov_b32_e32 v40, v2
	v_mov_b32_e32 v41, v2
	v_mov_b32_e32 v50, v2
	v_mov_b32_e32 v51, v2
	v_mov_b32_e32 v52, v2
	v_mov_b32_e32 v53, v2
	v_mov_b32_e32 v54, v2
	v_mov_b32_e32 v55, v2
	v_mov_b32_e32 v56, v2
	v_mov_b32_e32 v57, v2
	v_mov_b32_e32 v10, v2
	v_mov_b32_e32 v11, v2
	v_mov_b32_e32 v12, v2
	v_mov_b32_e32 v13, v2
	v_mov_b32_e32 v14, v2
	v_mov_b32_e32 v15, v2
	v_mov_b32_e32 v16, v2
	v_mov_b32_e32 v17, v2
	v_mov_b32_e32 v26, v2
	v_mov_b32_e32 v27, v2
	v_mov_b32_e32 v28, v2
	v_mov_b32_e32 v29, v2
	v_mov_b32_e32 v30, v2
	v_mov_b32_e32 v31, v2
	v_mov_b32_e32 v32, v2
	v_mov_b32_e32 v33, v2
	v_mov_b32_e32 v42, v2
	v_mov_b32_e32 v43, v2
	v_mov_b32_e32 v44, v2
	v_mov_b32_e32 v45, v2
	v_mov_b32_e32 v46, v2
	v_mov_b32_e32 v47, v2
	v_mov_b32_e32 v48, v2
	v_mov_b32_e32 v49, v2
	v_mov_b32_e32 v58, v2
	v_mov_b32_e32 v59, v2
	v_mov_b32_e32 v60, v2
	v_mov_b32_e32 v61, v2
	v_mov_b32_e32 v62, v2
	v_mov_b32_e32 v63, v2
	v_mov_b32_e32 v64, v2
	v_mov_b32_e32 v65, v2
	v_mov_b32_e32 v66, v2
	v_mov_b32_e32 v67, v2
	v_mov_b32_e32 v68, v2
	v_mov_b32_e32 v69, v2
	v_mov_b32_e32 v70, v2
	v_mov_b32_e32 v71, v2
	v_mov_b32_e32 v72, v2
	v_mov_b32_e32 v73, v2
	v_mov_b32_e32 v82, v2
	v_mov_b32_e32 v83, v2
	v_mov_b32_e32 v84, v2
	v_mov_b32_e32 v85, v2
	v_mov_b32_e32 v86, v2
	v_mov_b32_e32 v87, v2
	v_mov_b32_e32 v88, v2
	v_mov_b32_e32 v89, v2
	v_mov_b32_e32 v98, v2
	v_mov_b32_e32 v99, v2
	v_mov_b32_e32 v100, v2
	v_mov_b32_e32 v101, v2
	v_mov_b32_e32 v102, v2
	v_mov_b32_e32 v103, v2
	v_mov_b32_e32 v104, v2
	v_mov_b32_e32 v105, v2
	v_mov_b32_e32 v114, v2
	v_mov_b32_e32 v115, v2
	v_mov_b32_e32 v116, v2
	v_mov_b32_e32 v117, v2
	v_mov_b32_e32 v118, v2
	v_mov_b32_e32 v119, v2
	v_mov_b32_e32 v120, v2
	v_mov_b32_e32 v121, v2
	v_mov_b32_e32 v74, v2
	v_mov_b32_e32 v75, v2
	v_mov_b32_e32 v76, v2
	v_mov_b32_e32 v77, v2
	v_mov_b32_e32 v78, v2
	v_mov_b32_e32 v79, v2
	v_mov_b32_e32 v80, v2
	v_mov_b32_e32 v81, v2
	v_mov_b32_e32 v90, v2
	v_mov_b32_e32 v91, v2
	v_mov_b32_e32 v92, v2
	v_mov_b32_e32 v93, v2
	v_mov_b32_e32 v94, v2
	v_mov_b32_e32 v95, v2
	v_mov_b32_e32 v96, v2
	v_mov_b32_e32 v97, v2
	v_mov_b32_e32 v106, v2
	v_mov_b32_e32 v107, v2
	v_mov_b32_e32 v108, v2
	v_mov_b32_e32 v109, v2
	v_mov_b32_e32 v110, v2
	v_mov_b32_e32 v111, v2
	v_mov_b32_e32 v112, v2
	v_mov_b32_e32 v113, v2
	v_mov_b32_e32 v126, v2
	v_mov_b32_e32 v127, v2
	v_mov_b32_e32 v128, v2
	v_mov_b32_e32 v129, v2
	v_mov_b32_e32 v122, v2
	v_mov_b32_e32 v123, v2
	v_mov_b32_e32 v124, v2
	v_mov_b32_e32 v125, v2
	s_andn2_b64 vcc, exec, s[0:1]
	s_cbranch_vccnz .LBB0_1604

.LBB0_1663:
	v_readlane_b32 s0, v244, 3
	v_readlane_b32 s1, v244, 4
	s_cmp_gt_i32 s1, 9
	s_cselect_b64 s[0:1], -1, 0
	s_and_b64 s[4:5], s[8:9], s[0:1]
	s_andn2_b64 vcc, exec, s[4:5]
	s_cbranch_vccnz .LBB0_1717
	s_setprio 0
	s_waitcnt vmcnt(0)
	s_waitcnt vmcnt(0) lgkmcnt(0)
	s_barrier
	s_getreg_b32 s3, hwreg(HW_REG_HW_ID, 0, 6)
	s_and_b32 s3, s3, 63
	s_lshl_b32 s3, s3, 2
	s_add_i32 s3, s3, 0
	s_mov_b64 s[4:5], src_shared_base
	s_add_i32 s3, s3, 0x23e00
	v_mov_b32_e32 v2, s3
	v_mov_b32_e32 v3, s5
	flat_load_dword v2, v[2:3] sc0 sc1
	s_waitcnt vmcnt(0) lgkmcnt(0)
	v_readfirstlane_b32 s3, v2
	s_cmp_lg_u32 s3, 1
	s_cbranch_scc1 .Learlyinv_skip8
	buffer_inv sc1
	s_waitcnt vmcnt(0)

.LBB0_1741:
	v_ashrrev_i32_e32 v4, 31, v2
	v_lshrrev_b32_e32 v4, 26, v4
	v_lshlrev_b32_e32 v3, 4, v2
	v_add_u32_e32 v4, v2, v4
	v_bfe_i32 v2, v2, 27, 1
	v_lshrrev_b32_e32 v2, 22, v2
	v_add_u32_e32 v2, v3, v2
	v_and_b32_e32 v2, 0xfffffc00, v2
	v_sub_u32_e32 v2, v3, v2
	v_ashrrev_i32_e32 v10, 6, v4
	v_lshrrev_b32_e32 v4, 4, v2
	v_bitop3_b32 v2, v4, v2, 32 bitop3:0x6c
	v_ashrrev_i32_e32 v5, 31, v2
	v_lshrrev_b32_e32 v5, 26, v5
	v_add_u32_e32 v5, v2, v5
	v_lshlrev_b32_e32 v4, 3, v10
	v_ashrrev_i32_e32 v11, 6, v5
	v_and_b32_e32 v5, 0xc0, v5
	v_and_b32_e32 v4, -16, v4
	v_sub_u32_e32 v2, v2, v5
	v_mov_b32_e32 v5, 1
	v_add_u32_e32 v4, v11, v4
	v_ashrrev_i16_sdwa v2, v5, sext(v2) dst_sel:DWORD dst_unused:UNUSED_PAD src0_sel:DWORD src1_sel:BYTE_0
	s_ashr_i32 s0, s9, 3
	v_lshlrev_b32_e32 v6, 5, v10
	v_bfe_i32 v12, v2, 0, 16
	v_lshlrev_b32_e32 v2, 1, v4
	v_lshrrev_b32_e32 v7, 2, v4
	v_and_b32_e32 v8, 3, v11
	s_mov_b32 s9, 0x1fffe0
	v_and_b32_e32 v6, 32, v6
	v_and_b32_e32 v2, 24, v2
	v_and_b32_e32 v7, 4, v7
	v_and_or_b32 v8, v4, s9, v8
	v_or3_b32 v2, v8, v7, v2
	v_add_lshl_u32 v6, v6, v12, 1
	v_lshl_add_u32 v132, v2, 11, v6
	v_add_u32_e32 v2, 0x2000, v3
	v_ashrrev_i32_e32 v3, 31, v2
	v_lshrrev_b32_e32 v3, 22, v3
	v_add_u32_e32 v3, v2, v3
	v_ashrrev_i32_e32 v13, 10, v3
	v_mul_i32_i24_e32 v3, 0x400, v13
	v_sub_u32_e32 v2, v2, v3
	v_lshrrev_b32_e32 v3, 4, v2
	v_bitop3_b32 v2, v3, v2, 32 bitop3:0x6c
	v_lshl_add_u32 v130, v4, 11, v6
	v_ashrrev_i32_e32 v4, 31, v2
	v_lshrrev_b32_e32 v4, 26, v4
	v_add_u32_e32 v4, v2, v4
	s_add_i32 s0, s8, s0
	v_lshlrev_b32_e32 v3, 3, v13
	v_ashrrev_i32_e32 v14, 6, v4
	v_and_b32_e32 v4, 0xc0, v4
	s_ashr_i32 s8, s0, 31
	v_and_b32_e32 v3, -16, v3
	v_sub_u32_e32 v2, v2, v4
	s_lshr_b32 s8, s8, 25
	v_add_u32_e32 v3, v14, v3
	v_ashrrev_i16_sdwa v2, v5, sext(v2) dst_sel:DWORD dst_unused:UNUSED_PAD src0_sel:DWORD src1_sel:BYTE_0
	v_and_b32_e32 v5, 3, v14
	s_add_i32 s8, s0, s8
	v_and_or_b32 v5, v3, s9, v5
	s_ashr_i32 s9, s8, 7
	s_and_b32 s8, s8, 0xffffff80
	s_sub_i32 s8, s0, s8
	s_bfe_i32 s0, s8, 0x80000
	s_bfe_u32 s0, s0, 0x3000c
	s_add_i32 s11, s8, s0
	s_bfe_i32 s0, s11, 0x80000
	s_and_b32 s11, s11, 0xf8
	s_sub_i32 s8, s8, s11
	s_lshl_b32 s9, s9, 3
	s_sext_i32_i16 s0, s0
	s_sext_i32_i8 s8, s8
	s_ashr_i32 s1, s14, 8
	s_lshr_b32 s0, s0, 3
	s_add_i32 s34, s9, s8
	s_ashr_i32 s10, s14, 6
	s_ashr_i32 s35, s34, 31
	s_bfe_i64 s[12:13], s[0:1], 0x100000
	s_lshl_b32 s33, s10, 10
	s_lshl_b64 s[8:9], s[34:35], 19
	s_lshl_b64 s[12:13], s[12:13], 19
	s_add_u32 s38, s6, s12
	v_lshlrev_b32_e32 v6, 5, v13
	v_bfe_i32 v15, v2, 0, 16
	v_lshlrev_b32_e32 v2, 1, v3
	v_lshrrev_b32_e32 v4, 2, v3
	s_addc_u32 s39, s7, s13
	s_add_i32 s35, s33, 0
	v_and_b32_e32 v6, 32, v6
	v_and_b32_e32 v2, 24, v2
	v_and_b32_e32 v4, 4, v4
	s_add_i32 m0, s35, 0x10000
	v_or3_b32 v2, v5, v4, v2
	v_add_lshl_u32 v4, v6, v15, 1
	global_load_lds_dwordx4 v132, s[38:39]
	s_add_i32 m0, s35, 0x12000
	v_lshl_add_u32 v136, v2, 11, v4
	s_add_u32 s12, s38, 0x40000
	global_load_lds_dwordx4 v136, s[38:39]
	s_addc_u32 s13, s39, 0
	s_add_i32 m0, s35, 0x14000
	v_lshl_add_u32 v134, v3, 11, v4
	global_load_lds_dwordx4 v132, s[12:13]
	s_add_i32 m0, s35, 0x16000
	s_add_u32 s36, s62, s8
	s_addc_u32 s37, s63, s9
	s_add_i32 s42, s35, 0x2000
	global_load_lds_dwordx4 v136, s[12:13]
	s_mov_b32 m0, s35
	s_add_u32 s8, s36, 0x40000
	global_load_lds_dwordx4 v130, s[36:37]
	s_mov_b32 m0, s42
	s_addc_u32 s9, s37, 0
	s_add_i32 s43, s35, 0x4000
	global_load_lds_dwordx4 v134, s[36:37]
	s_mov_b32 m0, s43
	s_add_i32 s44, s35, 0x6000
	global_load_lds_dwordx4 v130, s[8:9]
	s_mov_b32 m0, s44
	v_mov_b32_e32 v133, 0
	global_load_lds_dwordx4 v134, s[8:9]
	v_mov_b32_e32 v137, v133
	v_mov_b32_e32 v131, v133
	v_mov_b32_e32 v135, v133
	s_cmp_eq_u32 s1, 1
	s_mov_b32 s45, 0
	v_lshl_add_u64 v[8:9], s[38:39], 0, v[132:133]
	v_lshl_add_u64 v[6:7], s[38:39], 0, v[136:137]
	v_lshl_add_u64 v[2:3], s[36:37], 0, v[130:131]
	s_cselect_b64 s[8:9], -1, 0
	s_cmp_lg_u32 s1, 1
	v_lshl_add_u64 v[4:5], s[36:37], 0, v[134:135]
	s_cbranch_scc1 .LBB0_1743
	s_barrier
	s_setprio 1

.LBB0_1753:
	ds_read_b128 v[146:149], v157
	ds_read_b128 v[160:163], v157 offset:1024
	ds_read_b128 v[164:167], v157 offset:2048
	ds_read_b128 v[168:171], v157 offset:3072
	ds_read_b128 v[172:175], v158
	ds_read_b128 v[176:179], v158 offset:1024
	ds_read_b128 v[180:183], v158 offset:2048
	ds_read_b128 v[184:187], v158 offset:3072
	s_add_u32 s38, s36, 0xfffc0080
	s_addc_u32 s39, s37, -1
	s_cmp_eq_u32 s65, 12
	s_cselect_b32 s41, s27, s39
	s_cselect_b32 s40, s59, s38
	s_cselect_b32 s39, s25, s64
	s_cselect_b32 s38, s60, s61
	v_lshl_add_u64 v[150:151], s[36:37], 0, v[138:139]
	s_add_i32 m0, s35, 0xc000
	ds_read_b128 v[188:191], v159
	ds_read_b128 v[192:195], v159 offset:1024
	ds_read_b128 v[196:199], v159 offset:2048
	ds_read_b128 v[200:203], v159 offset:3072
	ds_read_b128 v[204:207], v159 offset:4096
	ds_read_b128 v[208:211], v159 offset:5120
	ds_read_b128 v[218:221], v159 offset:6144
	ds_read_b128 v[226:229], v159 offset:7168
	global_load_lds_dwordx4 v[150:151], off
	v_lshl_add_u64 v[150:151], s[36:37], 0, v[140:141]
	s_add_i32 m0, s35, 0xe000
	s_nop 0
	global_load_lds_dwordx4 v[150:151], off
	s_waitcnt vmcnt(8)
	s_waitcnt lgkmcnt(0)
	s_barrier
	s_waitcnt lgkmcnt(0)
	v_mfma_f32_16x16x32_bf16 v[126:129], v[146:149], v[188:191], v[126:129]
	v_mfma_f32_16x16x32_bf16 v[122:125], v[164:167], v[188:191], v[122:125]
	v_mfma_f32_16x16x32_bf16 v[110:113], v[146:149], v[196:199], v[110:113]
	v_mfma_f32_16x16x32_bf16 v[106:109], v[164:167], v[196:199], v[106:109]
	v_mfma_f32_16x16x32_bf16 v[94:97], v[146:149], v[204:207], v[94:97]
	v_mfma_f32_16x16x32_bf16 v[90:93], v[164:167], v[204:207], v[90:93]
	v_mfma_f32_16x16x32_bf16 v[78:81], v[146:149], v[218:221], v[78:81]
	v_mfma_f32_16x16x32_bf16 v[74:77], v[164:167], v[218:221], v[74:77]
	v_mfma_f32_16x16x32_bf16 v[126:129], v[160:163], v[192:195], v[126:129]
	v_mfma_f32_16x16x32_bf16 v[122:125], v[168:171], v[192:195], v[122:125]
	v_mfma_f32_16x16x32_bf16 v[110:113], v[160:163], v[200:203], v[110:113]
	v_mfma_f32_16x16x32_bf16 v[106:109], v[168:171], v[200:203], v[106:109]
	v_mfma_f32_16x16x32_bf16 v[94:97], v[160:163], v[208:211], v[94:97]
	v_mfma_f32_16x16x32_bf16 v[90:93], v[168:171], v[208:211], v[90:93]
	v_mfma_f32_16x16x32_bf16 v[78:81], v[160:163], v[226:229], v[78:81]
	v_mfma_f32_16x16x32_bf16 v[74:77], v[168:171], v[226:229], v[74:77]
	v_mfma_f32_16x16x32_bf16 v[118:121], v[172:175], v[188:191], v[118:121]
	v_mfma_f32_16x16x32_bf16 v[114:117], v[180:183], v[188:191], v[114:117]
	v_mfma_f32_16x16x32_bf16 v[102:105], v[172:175], v[196:199], v[102:105]
	v_mfma_f32_16x16x32_bf16 v[98:101], v[180:183], v[196:199], v[98:101]
	v_mfma_f32_16x16x32_bf16 v[86:89], v[172:175], v[204:207], v[86:89]
	v_mfma_f32_16x16x32_bf16 v[82:85], v[180:183], v[204:207], v[82:85]
	v_mfma_f32_16x16x32_bf16 v[70:73], v[172:175], v[218:221], v[70:73]
	v_mfma_f32_16x16x32_bf16 v[66:69], v[180:183], v[218:221], v[66:69]
	v_mfma_f32_16x16x32_bf16 v[118:121], v[176:179], v[192:195], v[118:121]
	v_mfma_f32_16x16x32_bf16 v[114:117], v[184:187], v[192:195], v[114:117]
	v_mfma_f32_16x16x32_bf16 v[102:105], v[176:179], v[200:203], v[102:105]
	v_mfma_f32_16x16x32_bf16 v[98:101], v[184:187], v[200:203], v[98:101]
	v_mfma_f32_16x16x32_bf16 v[86:89], v[176:179], v[208:211], v[86:89]
	v_mfma_f32_16x16x32_bf16 v[82:85], v[184:187], v[208:211], v[82:85]
	v_mfma_f32_16x16x32_bf16 v[70:73], v[176:179], v[226:229], v[70:73]
	v_mfma_f32_16x16x32_bf16 v[66:69], v[184:187], v[226:229], v[66:69]
	s_barrier
	s_add_i32 s66, s50, s33
	v_lshl_add_u64 v[150:151], s[38:39], 0, v[132:133]
	s_mov_b32 m0, s66
	ds_read_b128 v[188:191], v159 offset:16384
	ds_read_b128 v[192:195], v159 offset:17408
	ds_read_b128 v[196:199], v159 offset:18432
	ds_read_b128 v[200:203], v159 offset:19456
	ds_read_b128 v[204:207], v159 offset:20480
	ds_read_b128 v[208:211], v159 offset:21504
	ds_read_b128 v[218:221], v159 offset:22528
	ds_read_b128 v[226:229], v159 offset:23552
	global_load_lds_dwordx4 v[150:151], off
	s_add_i32 m0, s66, 0x2000
	s_add_u32 s66, s38, 0x40000
	v_lshl_add_u64 v[214:215], s[38:39], 0, v[136:137]
	s_addc_u32 s67, s39, 0
	s_add_i32 s68, s51, s33
	global_load_lds_dwordx4 v[214:215], off
	v_lshl_add_u64 v[230:231], s[66:67], 0, v[132:133]
	s_mov_b32 m0, s68
	v_lshl_add_u64 v[232:233], s[40:41], 0, v[134:135]
	global_load_lds_dwordx4 v[230:231], off
	v_lshl_add_u64 v[230:231], s[66:67], 0, v[136:137]
	s_add_i32 m0, s68, 0x2000
	s_nop 0
	global_load_lds_dwordx4 v[230:231], off
	v_lshl_add_u64 v[230:231], s[40:41], 0, v[130:131]
	s_mov_b32 m0, s35
	s_nop 0
	global_load_lds_dwordx4 v[230:231], off
	s_mov_b32 m0, s42
	s_nop 0
	global_load_lds_dwordx4 v[232:233], off
	s_waitcnt vmcnt(8)
	s_waitcnt lgkmcnt(0)
	s_barrier
	s_waitcnt lgkmcnt(0)
	v_mfma_f32_16x16x32_bf16 v[62:65], v[146:149], v[188:191], v[62:65]
	v_mfma_f32_16x16x32_bf16 v[58:61], v[164:167], v[188:191], v[58:61]
	v_mfma_f32_16x16x32_bf16 v[46:49], v[146:149], v[196:199], v[46:49]
	v_mfma_f32_16x16x32_bf16 v[42:45], v[164:167], v[196:199], v[42:45]
	v_mfma_f32_16x16x32_bf16 v[30:33], v[146:149], v[204:207], v[30:33]
	v_mfma_f32_16x16x32_bf16 v[26:29], v[164:167], v[204:207], v[26:29]
	v_mfma_f32_16x16x32_bf16 v[14:17], v[146:149], v[218:221], v[14:17]
	v_mfma_f32_16x16x32_bf16 v[10:13], v[164:167], v[218:221], v[10:13]
	v_mfma_f32_16x16x32_bf16 v[62:65], v[160:163], v[192:195], v[62:65]
	v_mfma_f32_16x16x32_bf16 v[58:61], v[168:171], v[192:195], v[58:61]
	v_mfma_f32_16x16x32_bf16 v[46:49], v[160:163], v[200:203], v[46:49]
	v_mfma_f32_16x16x32_bf16 v[42:45], v[168:171], v[200:203], v[42:45]
	v_mfma_f32_16x16x32_bf16 v[30:33], v[160:163], v[208:211], v[30:33]
	v_mfma_f32_16x16x32_bf16 v[26:29], v[168:171], v[208:211], v[26:29]
	v_mfma_f32_16x16x32_bf16 v[14:17], v[160:163], v[226:229], v[14:17]
	v_mfma_f32_16x16x32_bf16 v[10:13], v[168:171], v[226:229], v[10:13]
	v_mfma_f32_16x16x32_bf16 v[54:57], v[172:175], v[188:191], v[54:57]
	v_mfma_f32_16x16x32_bf16 v[50:53], v[180:183], v[188:191], v[50:53]
	v_mfma_f32_16x16x32_bf16 v[38:41], v[172:175], v[196:199], v[38:41]
	v_mfma_f32_16x16x32_bf16 v[34:37], v[180:183], v[196:199], v[34:37]
	v_mfma_f32_16x16x32_bf16 v[22:25], v[172:175], v[204:207], v[22:25]
	v_mfma_f32_16x16x32_bf16 v[18:21], v[180:183], v[204:207], v[18:21]
	v_mfma_f32_16x16x32_bf16 v[6:9], v[172:175], v[218:221], v[6:9]
	v_mfma_f32_16x16x32_bf16 v[2:5], v[180:183], v[218:221], v[2:5]
	v_mfma_f32_16x16x32_bf16 v[54:57], v[176:179], v[192:195], v[54:57]
	v_mfma_f32_16x16x32_bf16 v[50:53], v[184:187], v[192:195], v[50:53]
	v_mfma_f32_16x16x32_bf16 v[38:41], v[176:179], v[200:203], v[38:41]
	v_mfma_f32_16x16x32_bf16 v[34:37], v[184:187], v[200:203], v[34:37]
	v_mfma_f32_16x16x32_bf16 v[22:25], v[176:179], v[208:211], v[22:25]
	v_mfma_f32_16x16x32_bf16 v[18:21], v[184:187], v[208:211], v[18:21]
	v_mfma_f32_16x16x32_bf16 v[6:9], v[176:179], v[226:229], v[6:9]
	v_mfma_f32_16x16x32_bf16 v[2:5], v[184:187], v[226:229], v[2:5]
	s_barrier
	s_add_i32 s66, 0, 0x18000
	s_add_i32 s67, 0, 0x1c000
	v_add_u32_e32 v168, s66, v153
	v_add_u32_e32 v184, s67, v153
	ds_read_b128 v[146:149], v168
	ds_read_b128 v[160:163], v168 offset:1024
	ds_read_b128 v[164:167], v168 offset:2048
	ds_read_b128 v[168:171], v168 offset:3072
	ds_read_b128 v[172:175], v184
	ds_read_b128 v[176:179], v184 offset:1024
	ds_read_b128 v[180:183], v184 offset:2048
	ds_read_b128 v[184:187], v184 offset:3072
	s_add_u32 s40, s40, 0x40000
	s_addc_u32 s41, s41, 0
	s_mov_b32 m0, s43
	v_lshl_add_u64 v[234:235], s[40:41], 0, v[130:131]
	ds_read_b128 v[188:191], v159 offset:32768
	ds_read_b128 v[192:195], v159 offset:33792
	ds_read_b128 v[196:199], v159 offset:34816
	ds_read_b128 v[200:203], v159 offset:35840
	ds_read_b128 v[204:207], v159 offset:36864
	ds_read_b128 v[208:211], v159 offset:37888
	ds_read_b128 v[218:221], v159 offset:38912
	ds_read_b128 v[226:229], v159 offset:39936
	global_load_lds_dwordx4 v[234:235], off
	v_lshl_add_u64 v[234:235], s[40:41], 0, v[134:135]
	s_mov_b32 m0, s44
	s_nop 0
	global_load_lds_dwordx4 v[234:235], off
	s_waitcnt vmcnt(8)
	s_waitcnt lgkmcnt(0)
	s_barrier
	s_waitcnt lgkmcnt(0)
	v_mfma_f32_16x16x32_bf16 v[126:129], v[146:149], v[188:191], v[126:129]
	v_mfma_f32_16x16x32_bf16 v[122:125], v[164:167], v[188:191], v[122:125]
	v_mfma_f32_16x16x32_bf16 v[110:113], v[146:149], v[196:199], v[110:113]
	v_mfma_f32_16x16x32_bf16 v[106:109], v[164:167], v[196:199], v[106:109]
	v_mfma_f32_16x16x32_bf16 v[94:97], v[146:149], v[204:207], v[94:97]
	v_mfma_f32_16x16x32_bf16 v[90:93], v[164:167], v[204:207], v[90:93]
	v_mfma_f32_16x16x32_bf16 v[78:81], v[146:149], v[218:221], v[78:81]
	v_mfma_f32_16x16x32_bf16 v[74:77], v[164:167], v[218:221], v[74:77]
	v_mfma_f32_16x16x32_bf16 v[126:129], v[160:163], v[192:195], v[126:129]
	v_mfma_f32_16x16x32_bf16 v[122:125], v[168:171], v[192:195], v[122:125]
	v_mfma_f32_16x16x32_bf16 v[110:113], v[160:163], v[200:203], v[110:113]
	v_mfma_f32_16x16x32_bf16 v[106:109], v[168:171], v[200:203], v[106:109]
	v_mfma_f32_16x16x32_bf16 v[94:97], v[160:163], v[208:211], v[94:97]
	v_mfma_f32_16x16x32_bf16 v[90:93], v[168:171], v[208:211], v[90:93]
	v_mfma_f32_16x16x32_bf16 v[78:81], v[160:163], v[226:229], v[78:81]
	v_mfma_f32_16x16x32_bf16 v[74:77], v[168:171], v[226:229], v[74:77]
	v_mfma_f32_16x16x32_bf16 v[118:121], v[172:175], v[188:191], v[118:121]
	v_mfma_f32_16x16x32_bf16 v[114:117], v[180:183], v[188:191], v[114:117]
	v_mfma_f32_16x16x32_bf16 v[102:105], v[172:175], v[196:199], v[102:105]
	v_mfma_f32_16x16x32_bf16 v[98:101], v[180:183], v[196:199], v[98:101]
	v_mfma_f32_16x16x32_bf16 v[86:89], v[172:175], v[204:207], v[86:89]
	v_mfma_f32_16x16x32_bf16 v[82:85], v[180:183], v[204:207], v[82:85]
	v_mfma_f32_16x16x32_bf16 v[70:73], v[172:175], v[218:221], v[70:73]
	v_mfma_f32_16x16x32_bf16 v[66:69], v[180:183], v[218:221], v[66:69]
	v_mfma_f32_16x16x32_bf16 v[118:121], v[176:179], v[192:195], v[118:121]
	v_mfma_f32_16x16x32_bf16 v[114:117], v[184:187], v[192:195], v[114:117]
	v_mfma_f32_16x16x32_bf16 v[102:105], v[176:179], v[200:203], v[102:105]
	v_mfma_f32_16x16x32_bf16 v[98:101], v[184:187], v[200:203], v[98:101]
	v_mfma_f32_16x16x32_bf16 v[86:89], v[176:179], v[208:211], v[86:89]
	v_mfma_f32_16x16x32_bf16 v[82:85], v[184:187], v[208:211], v[82:85]
	v_mfma_f32_16x16x32_bf16 v[70:73], v[176:179], v[226:229], v[70:73]
	v_mfma_f32_16x16x32_bf16 v[66:69], v[184:187], v[226:229], v[66:69]
	s_barrier
	s_add_i32 s40, s66, s33
	v_lshl_add_u64 v[150:151], v[150:151], 0, s[12:13]
	s_mov_b32 m0, s40
	ds_read_b128 v[188:191], v159 offset:49152
	ds_read_b128 v[192:195], v159 offset:50176
	ds_read_b128 v[196:199], v159 offset:51200
	ds_read_b128 v[200:203], v159 offset:52224
	ds_read_b128 v[204:207], v159 offset:53248
	ds_read_b128 v[208:211], v159 offset:54272
	ds_read_b128 v[218:221], v159 offset:55296
	ds_read_b128 v[226:229], v159 offset:56320
	global_load_lds_dwordx4 v[150:151], off
	s_add_i32 m0, s40, 0x2000
	s_add_u32 s38, s38, 0x40080
	v_lshl_add_u64 v[150:151], v[214:215], 0, s[12:13]
	s_addc_u32 s39, s39, 0
	s_add_i32 s40, s67, s33
	global_load_lds_dwordx4 v[150:151], off
	v_lshl_add_u64 v[150:151], s[38:39], 0, v[132:133]
	s_mov_b32 m0, s40
	s_nop 0
	global_load_lds_dwordx4 v[150:151], off
	v_lshl_add_u64 v[150:151], s[38:39], 0, v[136:137]
	s_add_i32 m0, s40, 0x2000
	s_nop 0
	global_load_lds_dwordx4 v[150:151], off
	v_lshl_add_u64 v[150:151], v[230:231], 0, s[12:13]
	s_mov_b32 m0, s46
	s_nop 0
	global_load_lds_dwordx4 v[150:151], off
	v_lshl_add_u64 v[150:151], v[232:233], 0, s[12:13]
	s_mov_b32 m0, s47
	s_nop 0
	global_load_lds_dwordx4 v[150:151], off
	s_waitcnt vmcnt(8)
	s_waitcnt lgkmcnt(0)
	s_barrier
	s_waitcnt lgkmcnt(0)
	v_mfma_f32_16x16x32_bf16 v[62:65], v[146:149], v[188:191], v[62:65]
	v_mfma_f32_16x16x32_bf16 v[58:61], v[164:167], v[188:191], v[58:61]
	v_mfma_f32_16x16x32_bf16 v[46:49], v[146:149], v[196:199], v[46:49]
	v_mfma_f32_16x16x32_bf16 v[42:45], v[164:167], v[196:199], v[42:45]
	v_mfma_f32_16x16x32_bf16 v[30:33], v[146:149], v[204:207], v[30:33]
	v_mfma_f32_16x16x32_bf16 v[26:29], v[164:167], v[204:207], v[26:29]
	v_mfma_f32_16x16x32_bf16 v[14:17], v[146:149], v[218:221], v[14:17]
	v_mfma_f32_16x16x32_bf16 v[10:13], v[164:167], v[218:221], v[10:13]
	v_mfma_f32_16x16x32_bf16 v[62:65], v[160:163], v[192:195], v[62:65]
	v_mfma_f32_16x16x32_bf16 v[58:61], v[168:171], v[192:195], v[58:61]
	v_mfma_f32_16x16x32_bf16 v[46:49], v[160:163], v[200:203], v[46:49]
	v_mfma_f32_16x16x32_bf16 v[42:45], v[168:171], v[200:203], v[42:45]
	v_mfma_f32_16x16x32_bf16 v[30:33], v[160:163], v[208:211], v[30:33]
	v_mfma_f32_16x16x32_bf16 v[26:29], v[168:171], v[208:211], v[26:29]
	v_mfma_f32_16x16x32_bf16 v[14:17], v[160:163], v[226:229], v[14:17]
	v_mfma_f32_16x16x32_bf16 v[10:13], v[168:171], v[226:229], v[10:13]
	v_mfma_f32_16x16x32_bf16 v[54:57], v[172:175], v[188:191], v[54:57]
	v_mfma_f32_16x16x32_bf16 v[50:53], v[180:183], v[188:191], v[50:53]
	v_mfma_f32_16x16x32_bf16 v[38:41], v[172:175], v[196:199], v[38:41]
	v_mfma_f32_16x16x32_bf16 v[34:37], v[180:183], v[196:199], v[34:37]
	v_mfma_f32_16x16x32_bf16 v[22:25], v[172:175], v[204:207], v[22:25]
	v_mfma_f32_16x16x32_bf16 v[18:21], v[180:183], v[204:207], v[18:21]
	v_mfma_f32_16x16x32_bf16 v[6:9], v[172:175], v[218:221], v[6:9]
	v_mfma_f32_16x16x32_bf16 v[2:5], v[180:183], v[218:221], v[2:5]
	v_mfma_f32_16x16x32_bf16 v[54:57], v[176:179], v[192:195], v[54:57]
	v_mfma_f32_16x16x32_bf16 v[50:53], v[184:187], v[192:195], v[50:53]
	v_mfma_f32_16x16x32_bf16 v[38:41], v[176:179], v[200:203], v[38:41]
	v_mfma_f32_16x16x32_bf16 v[34:37], v[184:187], v[200:203], v[34:37]
	v_mfma_f32_16x16x32_bf16 v[22:25], v[176:179], v[208:211], v[22:25]
	v_mfma_f32_16x16x32_bf16 v[18:21], v[184:187], v[208:211], v[18:21]
	v_mfma_f32_16x16x32_bf16 v[6:9], v[176:179], v[226:229], v[6:9]
	v_mfma_f32_16x16x32_bf16 v[2:5], v[184:187], v[226:229], v[2:5]
	s_barrier
	s_add_i32 s65, s65, 2
	s_add_u32 s36, s36, 0x100
	s_addc_u32 s37, s37, 0
	s_add_u32 s61, s61, 0x100
	s_addc_u32 s64, s64, 0
	s_cmp_gt_u32 s65, 13
	s_cbranch_scc0 .LBB0_1753
	s_and_b64 vcc, exec, s[14:15]
	s_cbranch_vccz .LBB0_1756
	s_barrier

.LBB0_1760:
	v_readlane_b32 s0, v244, 3
	v_readlane_b32 s1, v244, 4
	s_cmp_gt_i32 s1, 10
	s_cselect_b64 s[0:1], -1, 0
	s_and_b64 s[4:5], s[4:5], s[0:1]
	s_andn2_b64 vcc, exec, s[4:5]
	s_cbranch_vccnz .LBB0_1814
	s_setprio 0
	s_waitcnt vmcnt(0)
	s_waitcnt vmcnt(0) lgkmcnt(0)
	s_barrier
	s_getreg_b32 s3, hwreg(HW_REG_HW_ID, 0, 6)
	s_and_b32 s3, s3, 63
	s_lshl_b32 s3, s3, 2
	s_add_i32 s3, s3, 0
	s_mov_b64 s[4:5], src_shared_base
	s_add_i32 s3, s3, 0x23e00
	v_mov_b32_e32 v2, s3
	v_mov_b32_e32 v3, s5
	flat_load_dword v2, v[2:3] sc0 sc1
	s_waitcnt vmcnt(0) lgkmcnt(0)
	v_readfirstlane_b32 s3, v2
	s_cmp_lg_u32 s3, 1
	s_cbranch_scc1 .Learlyinv_skip9
	buffer_inv sc1
	s_waitcnt vmcnt(0)

.LBB0_1848:
	v_ashrrev_i32_e32 v4, 31, v2
	v_lshrrev_b32_e32 v4, 26, v4
	v_lshlrev_b32_e32 v3, 4, v2
	v_add_u32_e32 v4, v2, v4
	v_bfe_i32 v2, v2, 27, 1
	v_lshrrev_b32_e32 v2, 22, v2
	v_add_u32_e32 v2, v3, v2
	v_and_b32_e32 v2, 0xfffffc00, v2
	v_sub_u32_e32 v2, v3, v2
	v_lshrrev_b32_e32 v5, 4, v2
	v_bitop3_b32 v2, v5, v2, 32 bitop3:0x6c
	v_ashrrev_i32_e32 v6, 31, v2
	v_ashrrev_i32_e32 v4, 6, v4
	v_lshrrev_b32_e32 v6, 26, v6
	v_lshlrev_b32_e32 v5, 3, v4
	v_add_u32_e32 v6, v2, v6
	v_and_b32_e32 v5, -16, v5
	v_ashrrev_i32_e32 v7, 6, v6
	v_lshlrev_b32_e32 v4, 5, v4
	v_add_u32_e32 v5, v7, v5
	v_and_b32_e32 v14, 32, v4
	v_and_b32_e32 v4, 0xc0, v6
	v_sub_u32_e32 v2, v2, v4
	v_mov_b32_e32 v4, 1
	v_lshlrev_b32_e32 v6, 1, v5
	v_lshrrev_b32_e32 v8, 2, v5
	v_and_b32_e32 v7, 3, v7
	s_mov_b32 s1, 0x7fffffe0
	v_ashrrev_i16_sdwa v2, v4, sext(v2) dst_sel:DWORD dst_unused:UNUSED_PAD src0_sel:DWORD src1_sel:BYTE_0
	v_and_b32_e32 v6, 24, v6
	v_and_b32_e32 v8, 4, v8
	v_and_or_b32 v7, v5, s1, v7
	v_bfe_i32 v15, v2, 0, 16
	v_or3_b32 v6, v7, v8, v6
	v_add_u32_e32 v2, v14, v15
	v_mul_lo_u32 v16, v5, s0
	v_mul_lo_u32 v5, v6, s0
	v_add_lshl_u32 v134, v2, v16, 1
	v_add_lshl_u32 v136, v5, v2, 1
	v_add_u32_e32 v2, 0x2000, v3
	v_ashrrev_i32_e32 v3, 31, v2
	v_lshrrev_b32_e32 v3, 22, v3
	v_add_u32_e32 v3, v2, v3
	v_ashrrev_i32_e32 v3, 10, v3
	v_mul_i32_i24_e32 v5, 0x400, v3
	v_sub_u32_e32 v2, v2, v5
	v_lshrrev_b32_e32 v5, 4, v2
	v_bitop3_b32 v2, v5, v2, 32 bitop3:0x6c
	v_ashrrev_i32_e32 v6, 31, v2
	v_lshrrev_b32_e32 v6, 26, v6
	v_lshlrev_b32_e32 v5, 3, v3
	v_add_u32_e32 v6, v2, v6
	v_and_b32_e32 v5, -16, v5
	v_ashrrev_i32_e32 v7, 6, v6
	v_lshlrev_b32_e32 v3, 5, v3
	v_add_u32_e32 v5, v7, v5
	v_and_b32_e32 v17, 32, v3
	v_and_b32_e32 v3, 0xc0, v6
	v_and_b32_e32 v6, 3, v7
	s_ashr_i32 s11, s30, 6
	v_and_or_b32 v6, v5, s1, v6
	s_ashr_i32 s1, s0, 31
	s_ashr_i32 s3, s30, 8
	s_lshl_b64 s[12:13], s[0:1], 8
	s_lshl_b64 s[14:15], s[0:1], 9
	s_lshl_b32 s34, s11, 10
	s_add_u32 s35, s82, 0x6400000
	s_addc_u32 s36, s83, 0
	s_add_i32 s4, s6, s4
	s_ashr_i32 s5, s4, 31
	s_lshr_b32 s5, s5, 27
	s_add_i32 s5, s4, s5
	s_ashr_i32 s6, s5, 5
	s_and_b32 s5, s5, 0xffe0
	s_sub_i32 s5, s4, s5
	s_bfe_i32 s4, s5, 0x80000
	s_bfe_u32 s4, s4, 0x3000c
	s_add_i32 s7, s5, s4
	s_bfe_i32 s4, s7, 0x80000
	s_and_b32 s7, s7, 0xf8
	s_sub_i32 s5, s5, s7
	s_lshl_b32 s6, s6, 3
	s_sext_i32_i8 s5, s5
	s_add_i32 s31, s6, s5
	s_ashr_i32 s5, s31, 31
	s_mul_i32 s5, s14, s5
	s_mul_hi_u32 s6, s14, s31
	s_add_i32 s5, s6, s5
	s_lshr_b64 s[6:7], s[0:1], 23
	s_sext_i32_i16 s10, s4
	s_mul_i32 s7, s6, s31
	s_lshr_b32 s4, s10, 3
	s_add_i32 s5, s5, s7
	s_bfe_i64 s[16:17], s[4:5], 0x100000
	s_ashr_i32 s7, s10, 3
	s_mul_hi_u32 s10, s14, s7
	s_mul_i32 s16, s14, s17
	s_add_i32 s10, s10, s16
	s_mul_i32 s6, s6, s7
	v_sub_u32_e32 v2, v2, v3
	s_add_i32 s10, s10, s6
	s_mul_i32 s6, s14, s7
	v_ashrrev_i16_sdwa v2, v4, sext(v2) dst_sel:DWORD dst_unused:UNUSED_PAD src0_sel:DWORD src1_sel:BYTE_0
	v_lshlrev_b32_e32 v3, 1, v5
	v_lshrrev_b32_e32 v4, 2, v5
	s_add_u32 s16, s8, s6
	v_and_b32_e32 v3, 24, v3
	v_and_b32_e32 v4, 4, v4
	s_addc_u32 s17, s9, s10
	s_add_i32 s38, s34, 0
	v_bfe_i32 v18, v2, 0, 16
	v_or3_b32 v3, v6, v4, v3
	s_add_i32 m0, s38, 0x10000
	v_add_u32_e32 v2, v17, v18
	v_mul_lo_u32 v3, v3, s0
	global_load_lds_dwordx4 v136, s[16:17]
	s_add_i32 m0, s38, 0x12000
	v_add_lshl_u32 v140, v3, v2, 1
	s_add_u32 s6, s16, s12
	global_load_lds_dwordx4 v140, s[16:17]
	s_addc_u32 s7, s17, s13
	s_add_i32 m0, s38, 0x14000
	s_mul_i32 s18, s14, s31
	global_load_lds_dwordx4 v136, s[6:7]
	s_add_i32 m0, s38, 0x16000
	s_add_u32 s18, s35, s18
	s_addc_u32 s19, s36, s5
	s_add_i32 s39, s38, 0x2000
	v_mul_lo_u32 v19, v5, s0
	global_load_lds_dwordx4 v140, s[6:7]
	s_mov_b32 m0, s38
	s_add_u32 s20, s18, s12
	v_add_lshl_u32 v138, v2, v19, 1
	global_load_lds_dwordx4 v134, s[18:19]
	s_mov_b32 m0, s39
	s_addc_u32 s21, s19, s13
	s_add_i32 s40, s38, 0x4000
	global_load_lds_dwordx4 v138, s[18:19]
	s_mov_b32 m0, s40
	s_add_i32 s41, s38, 0x6000
	global_load_lds_dwordx4 v134, s[20:21]
	s_mov_b32 m0, s41
	v_mov_b32_e32 v130, 0
	global_load_lds_dwordx4 v138, s[20:21]
	v_mov_b32_e32 v137, v130
	v_mov_b32_e32 v141, v130
	v_mov_b32_e32 v135, v130
	v_mov_b32_e32 v139, v130
	v_lshl_add_u64 v[12:13], s[16:17], 0, v[136:137]
	v_lshl_add_u64 v[8:9], s[16:17], 0, v[140:141]
	v_lshl_add_u64 v[4:5], s[6:7], 0, v[136:137]
	v_lshl_add_u64 v[2:3], s[6:7], 0, v[140:141]
	v_lshl_add_u64 v[10:11], s[18:19], 0, v[134:135]
	s_cmp_lg_u32 s3, 1
	v_lshl_add_u64 v[6:7], s[18:19], 0, v[138:139]
	s_cbranch_scc1 .LBB0_1850
	s_barrier
	s_setprio 1

.LBB0_1864:
	v_add_u32_e32 v131, s47, v151
	ds_read_b128 v[154:157], v131
	ds_read_b128 v[158:161], v131 offset:1024
	ds_read_b128 v[162:165], v131 offset:2048
	ds_read_b128 v[166:169], v131 offset:3072
	v_add_u32_e32 v131, s48, v151
	ds_read_b128 v[170:173], v131
	ds_read_b128 v[174:177], v131 offset:1024
	ds_read_b128 v[178:181], v131 offset:2048
	ds_read_b128 v[182:185], v131 offset:3072
	s_add_i32 s55, s28, 2
	s_add_u32 s58, s26, 0x80
	s_addc_u32 s29, s27, 0
	s_cmp_eq_u32 s46, s28
	s_cselect_b32 s28, s6, s58
	s_cselect_b32 s29, s7, s29
	s_cselect_b32 s59, s25, s54
	s_cselect_b32 s58, s24, s53
	v_lshl_add_u64 v[132:133], s[26:27], 0, v[142:143]
	s_add_i32 m0, s38, 0xc000
	ds_read_b128 v[186:189], v152
	ds_read_b128 v[194:197], v152 offset:1024
	ds_read_b128 v[198:201], v152 offset:2048
	ds_read_b128 v[202:205], v152 offset:3072
	ds_read_b128 v[206:209], v152 offset:4096
	ds_read_b128 v[218:221], v152 offset:5120
	ds_read_b128 v[226:229], v152 offset:6144
	ds_read_b128 v[230:233], v152 offset:7168
	global_load_lds_dwordx4 v[132:133], off
	v_lshl_add_u64 v[132:133], s[26:27], 0, v[144:145]
	s_add_i32 m0, s38, 0xe000
	s_nop 0
	global_load_lds_dwordx4 v[132:133], off
	s_waitcnt vmcnt(8)
	s_waitcnt lgkmcnt(0)
	s_barrier
	s_waitcnt lgkmcnt(0)
	v_mfma_f32_16x16x32_bf16 v[122:125], v[154:157], v[186:189], v[122:125]
	v_mfma_f32_16x16x32_bf16 v[126:129], v[162:165], v[186:189], v[126:129]
	v_mfma_f32_16x16x32_bf16 v[114:117], v[154:157], v[198:201], v[114:117]
	v_mfma_f32_16x16x32_bf16 v[118:121], v[162:165], v[198:201], v[118:121]
	v_mfma_f32_16x16x32_bf16 v[94:97], v[154:157], v[206:209], v[94:97]
	v_mfma_f32_16x16x32_bf16 v[90:93], v[162:165], v[206:209], v[90:93]
	v_mfma_f32_16x16x32_bf16 v[78:81], v[154:157], v[226:229], v[78:81]
	v_mfma_f32_16x16x32_bf16 v[74:77], v[162:165], v[226:229], v[74:77]
	v_mfma_f32_16x16x32_bf16 v[122:125], v[158:161], v[194:197], v[122:125]
	v_mfma_f32_16x16x32_bf16 v[126:129], v[166:169], v[194:197], v[126:129]
	v_mfma_f32_16x16x32_bf16 v[114:117], v[158:161], v[202:205], v[114:117]
	v_mfma_f32_16x16x32_bf16 v[118:121], v[166:169], v[202:205], v[118:121]
	v_mfma_f32_16x16x32_bf16 v[94:97], v[158:161], v[218:221], v[94:97]
	v_mfma_f32_16x16x32_bf16 v[90:93], v[166:169], v[218:221], v[90:93]
	v_mfma_f32_16x16x32_bf16 v[78:81], v[158:161], v[230:233], v[78:81]
	v_mfma_f32_16x16x32_bf16 v[74:77], v[166:169], v[230:233], v[74:77]
	v_mfma_f32_16x16x32_bf16 v[110:113], v[170:173], v[186:189], v[110:113]
	v_mfma_f32_16x16x32_bf16 v[106:109], v[178:181], v[186:189], v[106:109]
	v_mfma_f32_16x16x32_bf16 v[102:105], v[170:173], v[198:201], v[102:105]
	v_mfma_f32_16x16x32_bf16 v[98:101], v[178:181], v[198:201], v[98:101]
	v_mfma_f32_16x16x32_bf16 v[86:89], v[170:173], v[206:209], v[86:89]
	v_mfma_f32_16x16x32_bf16 v[82:85], v[178:181], v[206:209], v[82:85]
	v_mfma_f32_16x16x32_bf16 v[70:73], v[170:173], v[226:229], v[70:73]
	v_mfma_f32_16x16x32_bf16 v[66:69], v[178:181], v[226:229], v[66:69]
	v_mfma_f32_16x16x32_bf16 v[110:113], v[174:177], v[194:197], v[110:113]
	v_mfma_f32_16x16x32_bf16 v[106:109], v[182:185], v[194:197], v[106:109]
	v_mfma_f32_16x16x32_bf16 v[102:105], v[174:177], v[202:205], v[102:105]
	v_mfma_f32_16x16x32_bf16 v[98:101], v[182:185], v[202:205], v[98:101]
	v_mfma_f32_16x16x32_bf16 v[86:89], v[174:177], v[218:221], v[86:89]
	v_mfma_f32_16x16x32_bf16 v[82:85], v[182:185], v[218:221], v[82:85]
	v_mfma_f32_16x16x32_bf16 v[70:73], v[174:177], v[230:233], v[70:73]
	v_mfma_f32_16x16x32_bf16 v[66:69], v[182:185], v[230:233], v[66:69]
	s_barrier
	s_add_i32 s60, s47, s34
	v_lshl_add_u64 v[132:133], s[58:59], 0, v[136:137]
	s_mov_b32 m0, s60
	ds_read_b128 v[186:189], v152 offset:16384
	ds_read_b128 v[194:197], v152 offset:17408
	ds_read_b128 v[198:201], v152 offset:18432
	ds_read_b128 v[202:205], v152 offset:19456
	ds_read_b128 v[206:209], v152 offset:20480
	ds_read_b128 v[218:221], v152 offset:21504
	ds_read_b128 v[226:229], v152 offset:22528
	ds_read_b128 v[230:233], v152 offset:23552
	global_load_lds_dwordx4 v[132:133], off
	s_add_i32 m0, s60, 0x2000
	v_lshl_add_u64 v[190:191], s[58:59], 0, v[140:141]
	s_add_u32 s58, s58, s12
	s_addc_u32 s59, s59, s13
	s_add_i32 s60, s48, s34
	global_load_lds_dwordx4 v[190:191], off
	v_lshl_add_u64 v[210:211], s[58:59], 0, v[136:137]
	s_mov_b32 m0, s60
	v_lshl_add_u64 v[234:235], s[58:59], 0, v[140:141]
	global_load_lds_dwordx4 v[210:211], off
	s_add_i32 m0, s60, 0x2000
	v_lshl_add_u64 v[236:237], s[28:29], 0, v[134:135]
	global_load_lds_dwordx4 v[234:235], off
	s_mov_b32 m0, s38
	v_lshl_add_u64 v[238:239], s[28:29], 0, v[138:139]
	global_load_lds_dwordx4 v[236:237], off
	s_mov_b32 m0, s39
	s_nop 0
	global_load_lds_dwordx4 v[238:239], off
	s_waitcnt vmcnt(8)
	s_waitcnt lgkmcnt(0)
	s_barrier
	s_waitcnt lgkmcnt(0)
	v_mfma_f32_16x16x32_bf16 v[62:65], v[154:157], v[186:189], v[62:65]
	v_mfma_f32_16x16x32_bf16 v[58:61], v[162:165], v[186:189], v[58:61]
	v_mfma_f32_16x16x32_bf16 v[46:49], v[154:157], v[198:201], v[46:49]
	v_mfma_f32_16x16x32_bf16 v[42:45], v[162:165], v[198:201], v[42:45]
	v_mfma_f32_16x16x32_bf16 v[30:33], v[154:157], v[206:209], v[30:33]
	v_mfma_f32_16x16x32_bf16 v[26:29], v[162:165], v[206:209], v[26:29]
	v_mfma_f32_16x16x32_bf16 v[14:17], v[154:157], v[226:229], v[14:17]
	v_mfma_f32_16x16x32_bf16 v[10:13], v[162:165], v[226:229], v[10:13]
	v_mfma_f32_16x16x32_bf16 v[62:65], v[158:161], v[194:197], v[62:65]
	v_mfma_f32_16x16x32_bf16 v[58:61], v[166:169], v[194:197], v[58:61]
	v_mfma_f32_16x16x32_bf16 v[46:49], v[158:161], v[202:205], v[46:49]
	v_mfma_f32_16x16x32_bf16 v[42:45], v[166:169], v[202:205], v[42:45]
	v_mfma_f32_16x16x32_bf16 v[30:33], v[158:161], v[218:221], v[30:33]
	v_mfma_f32_16x16x32_bf16 v[26:29], v[166:169], v[218:221], v[26:29]
	v_mfma_f32_16x16x32_bf16 v[14:17], v[158:161], v[230:233], v[14:17]
	v_mfma_f32_16x16x32_bf16 v[10:13], v[166:169], v[230:233], v[10:13]
	v_mfma_f32_16x16x32_bf16 v[54:57], v[170:173], v[186:189], v[54:57]
	v_mfma_f32_16x16x32_bf16 v[50:53], v[178:181], v[186:189], v[50:53]
	v_mfma_f32_16x16x32_bf16 v[38:41], v[170:173], v[198:201], v[38:41]
	v_mfma_f32_16x16x32_bf16 v[34:37], v[178:181], v[198:201], v[34:37]
	v_mfma_f32_16x16x32_bf16 v[22:25], v[170:173], v[206:209], v[22:25]
	v_mfma_f32_16x16x32_bf16 v[18:21], v[178:181], v[206:209], v[18:21]
	v_mfma_f32_16x16x32_bf16 v[6:9], v[170:173], v[226:229], v[6:9]
	v_mfma_f32_16x16x32_bf16 v[2:5], v[178:181], v[226:229], v[2:5]
	v_mfma_f32_16x16x32_bf16 v[54:57], v[174:177], v[194:197], v[54:57]
	v_mfma_f32_16x16x32_bf16 v[50:53], v[182:185], v[194:197], v[50:53]
	v_mfma_f32_16x16x32_bf16 v[38:41], v[174:177], v[202:205], v[38:41]
	v_mfma_f32_16x16x32_bf16 v[34:37], v[182:185], v[202:205], v[34:37]
	v_mfma_f32_16x16x32_bf16 v[22:25], v[174:177], v[218:221], v[22:25]
	v_mfma_f32_16x16x32_bf16 v[18:21], v[182:185], v[218:221], v[18:21]
	v_mfma_f32_16x16x32_bf16 v[6:9], v[174:177], v[230:233], v[6:9]
	v_mfma_f32_16x16x32_bf16 v[2:5], v[182:185], v[230:233], v[2:5]
	s_barrier
	s_add_i32 s58, 0, 0x18000
	v_add_u32_e32 v131, s58, v151
	s_add_i32 s59, 0, 0x1c000
	ds_read_b128 v[154:157], v131
	ds_read_b128 v[158:161], v131 offset:1024
	ds_read_b128 v[162:165], v131 offset:2048
	ds_read_b128 v[166:169], v131 offset:3072
	v_add_u32_e32 v131, s59, v151
	ds_read_b128 v[170:173], v131
	ds_read_b128 v[174:177], v131 offset:1024
	ds_read_b128 v[178:181], v131 offset:2048
	ds_read_b128 v[182:185], v131 offset:3072
	s_add_u32 s28, s28, s12
	s_addc_u32 s29, s29, s13
	s_mov_b32 m0, s40
	v_lshl_add_u64 v[240:241], s[28:29], 0, v[134:135]
	ds_read_b128 v[186:189], v152 offset:32768
	ds_read_b128 v[194:197], v152 offset:33792
	ds_read_b128 v[198:201], v152 offset:34816
	ds_read_b128 v[202:205], v152 offset:35840
	ds_read_b128 v[206:209], v152 offset:36864
	ds_read_b128 v[218:221], v152 offset:37888
	ds_read_b128 v[226:229], v152 offset:38912
	ds_read_b128 v[230:233], v152 offset:39936
	global_load_lds_dwordx4 v[240:241], off
	v_lshl_add_u64 v[240:241], s[28:29], 0, v[138:139]
	s_mov_b32 m0, s41
	s_nop 0
	global_load_lds_dwordx4 v[240:241], off
	s_waitcnt vmcnt(8)
	s_waitcnt lgkmcnt(0)
	s_barrier
	s_waitcnt lgkmcnt(0)
	v_mfma_f32_16x16x32_bf16 v[122:125], v[154:157], v[186:189], v[122:125]
	v_mfma_f32_16x16x32_bf16 v[126:129], v[162:165], v[186:189], v[126:129]
	v_mfma_f32_16x16x32_bf16 v[114:117], v[154:157], v[198:201], v[114:117]
	v_mfma_f32_16x16x32_bf16 v[118:121], v[162:165], v[198:201], v[118:121]
	v_mfma_f32_16x16x32_bf16 v[94:97], v[154:157], v[206:209], v[94:97]
	v_mfma_f32_16x16x32_bf16 v[90:93], v[162:165], v[206:209], v[90:93]
	v_mfma_f32_16x16x32_bf16 v[78:81], v[154:157], v[226:229], v[78:81]
	v_mfma_f32_16x16x32_bf16 v[74:77], v[162:165], v[226:229], v[74:77]
	v_mfma_f32_16x16x32_bf16 v[122:125], v[158:161], v[194:197], v[122:125]
	v_mfma_f32_16x16x32_bf16 v[126:129], v[166:169], v[194:197], v[126:129]
	v_mfma_f32_16x16x32_bf16 v[114:117], v[158:161], v[202:205], v[114:117]
	v_mfma_f32_16x16x32_bf16 v[118:121], v[166:169], v[202:205], v[118:121]
	v_mfma_f32_16x16x32_bf16 v[94:97], v[158:161], v[218:221], v[94:97]
	v_mfma_f32_16x16x32_bf16 v[90:93], v[166:169], v[218:221], v[90:93]
	v_mfma_f32_16x16x32_bf16 v[78:81], v[158:161], v[230:233], v[78:81]
	v_mfma_f32_16x16x32_bf16 v[74:77], v[166:169], v[230:233], v[74:77]
	v_mfma_f32_16x16x32_bf16 v[110:113], v[170:173], v[186:189], v[110:113]
	v_mfma_f32_16x16x32_bf16 v[106:109], v[178:181], v[186:189], v[106:109]
	v_mfma_f32_16x16x32_bf16 v[102:105], v[170:173], v[198:201], v[102:105]
	v_mfma_f32_16x16x32_bf16 v[98:101], v[178:181], v[198:201], v[98:101]
	v_mfma_f32_16x16x32_bf16 v[86:89], v[170:173], v[206:209], v[86:89]
	v_mfma_f32_16x16x32_bf16 v[82:85], v[178:181], v[206:209], v[82:85]
	v_mfma_f32_16x16x32_bf16 v[70:73], v[170:173], v[226:229], v[70:73]
	v_mfma_f32_16x16x32_bf16 v[66:69], v[178:181], v[226:229], v[66:69]
	v_mfma_f32_16x16x32_bf16 v[110:113], v[174:177], v[194:197], v[110:113]
	v_mfma_f32_16x16x32_bf16 v[106:109], v[182:185], v[194:197], v[106:109]
	v_mfma_f32_16x16x32_bf16 v[102:105], v[174:177], v[202:205], v[102:105]
	v_mfma_f32_16x16x32_bf16 v[98:101], v[182:185], v[202:205], v[98:101]
	v_mfma_f32_16x16x32_bf16 v[86:89], v[174:177], v[218:221], v[86:89]
	v_mfma_f32_16x16x32_bf16 v[82:85], v[182:185], v[218:221], v[82:85]
	v_mfma_f32_16x16x32_bf16 v[70:73], v[174:177], v[230:233], v[70:73]
	v_mfma_f32_16x16x32_bf16 v[66:69], v[182:185], v[230:233], v[66:69]
	s_barrier
	s_add_i32 s28, s58, s34
	v_lshl_add_u64 v[132:133], v[132:133], 0, s[20:21]
	s_mov_b32 m0, s28
	ds_read_b128 v[186:189], v152 offset:49152
	ds_read_b128 v[194:197], v152 offset:50176
	ds_read_b128 v[198:201], v152 offset:51200
	ds_read_b128 v[202:205], v152 offset:52224
	ds_read_b128 v[206:209], v152 offset:53248
	ds_read_b128 v[218:221], v152 offset:54272
	ds_read_b128 v[226:229], v152 offset:55296
	ds_read_b128 v[230:233], v152 offset:56320
	global_load_lds_dwordx4 v[132:133], off
	v_lshl_add_u64 v[132:133], v[190:191], 0, s[20:21]
	s_add_i32 m0, s28, 0x2000
	s_add_i32 s28, s59, s34
	global_load_lds_dwordx4 v[132:133], off
	v_lshl_add_u64 v[132:133], v[210:211], 0, s[20:21]
	s_mov_b32 m0, s28
	s_nop 0
	global_load_lds_dwordx4 v[132:133], off
	v_lshl_add_u64 v[132:133], v[234:235], 0, s[20:21]
	s_add_i32 m0, s28, 0x2000
	s_nop 0
	global_load_lds_dwordx4 v[132:133], off
	v_lshl_add_u64 v[132:133], v[236:237], 0, s[20:21]
	s_mov_b32 m0, s42
	s_nop 0
	global_load_lds_dwordx4 v[132:133], off
	v_lshl_add_u64 v[132:133], v[238:239], 0, s[20:21]
	s_mov_b32 m0, s43
	s_nop 0
	global_load_lds_dwordx4 v[132:133], off
	s_waitcnt vmcnt(8)
	s_waitcnt lgkmcnt(0)
	s_barrier
	s_waitcnt lgkmcnt(0)
	v_mfma_f32_16x16x32_bf16 v[62:65], v[154:157], v[186:189], v[62:65]
	v_mfma_f32_16x16x32_bf16 v[58:61], v[162:165], v[186:189], v[58:61]
	v_mfma_f32_16x16x32_bf16 v[46:49], v[154:157], v[198:201], v[46:49]
	v_mfma_f32_16x16x32_bf16 v[42:45], v[162:165], v[198:201], v[42:45]
	v_mfma_f32_16x16x32_bf16 v[30:33], v[154:157], v[206:209], v[30:33]
	v_mfma_f32_16x16x32_bf16 v[26:29], v[162:165], v[206:209], v[26:29]
	v_mfma_f32_16x16x32_bf16 v[14:17], v[154:157], v[226:229], v[14:17]
	v_mfma_f32_16x16x32_bf16 v[10:13], v[162:165], v[226:229], v[10:13]
	v_mfma_f32_16x16x32_bf16 v[62:65], v[158:161], v[194:197], v[62:65]
	v_mfma_f32_16x16x32_bf16 v[58:61], v[166:169], v[194:197], v[58:61]
	v_mfma_f32_16x16x32_bf16 v[46:49], v[158:161], v[202:205], v[46:49]
	v_mfma_f32_16x16x32_bf16 v[42:45], v[166:169], v[202:205], v[42:45]
	v_mfma_f32_16x16x32_bf16 v[30:33], v[158:161], v[218:221], v[30:33]
	v_mfma_f32_16x16x32_bf16 v[26:29], v[166:169], v[218:221], v[26:29]
	v_mfma_f32_16x16x32_bf16 v[14:17], v[158:161], v[230:233], v[14:17]
	v_mfma_f32_16x16x32_bf16 v[10:13], v[166:169], v[230:233], v[10:13]
	v_mfma_f32_16x16x32_bf16 v[54:57], v[170:173], v[186:189], v[54:57]
	v_mfma_f32_16x16x32_bf16 v[50:53], v[178:181], v[186:189], v[50:53]
	v_mfma_f32_16x16x32_bf16 v[38:41], v[170:173], v[198:201], v[38:41]
	v_mfma_f32_16x16x32_bf16 v[34:37], v[178:181], v[198:201], v[34:37]
	v_mfma_f32_16x16x32_bf16 v[22:25], v[170:173], v[206:209], v[22:25]
	v_mfma_f32_16x16x32_bf16 v[18:21], v[178:181], v[206:209], v[18:21]
	v_mfma_f32_16x16x32_bf16 v[6:9], v[170:173], v[226:229], v[6:9]
	v_mfma_f32_16x16x32_bf16 v[2:5], v[178:181], v[226:229], v[2:5]
	v_mfma_f32_16x16x32_bf16 v[54:57], v[174:177], v[194:197], v[54:57]
	v_mfma_f32_16x16x32_bf16 v[50:53], v[182:185], v[194:197], v[50:53]
	v_mfma_f32_16x16x32_bf16 v[38:41], v[174:177], v[202:205], v[38:41]
	v_mfma_f32_16x16x32_bf16 v[34:37], v[182:185], v[202:205], v[34:37]
	v_mfma_f32_16x16x32_bf16 v[22:25], v[174:177], v[218:221], v[22:25]
	v_mfma_f32_16x16x32_bf16 v[18:21], v[182:185], v[218:221], v[18:21]
	v_mfma_f32_16x16x32_bf16 v[6:9], v[174:177], v[230:233], v[6:9]
	v_mfma_f32_16x16x32_bf16 v[2:5], v[182:185], v[230:233], v[2:5]
	s_barrier
	s_add_u32 s26, s26, 0x100
	s_addc_u32 s27, s27, 0
	s_add_u32 s53, s53, 0x100
	s_addc_u32 s54, s54, 0
	s_cmp_ge_i32 s55, s45
	s_mov_b32 s28, s55
	s_cbranch_scc0 .LBB0_1864
